# experts phase rewritten as L2-friendly table sweep (per-token sorted records, 64 groups ordered by table position, 4 tokens in registers, rolling one-group-ahead prefetch) + in-proj ring K-loop
# speedup vs baseline: 1.0647x; 1.0647x over previous
.LBB0_683:
	s_or_b64 exec, exec, s[10:11]
	s_and_b64 vcc, exec, s[4:5]
	s_waitcnt lgkmcnt(0)
	s_barrier
	v_mov_b32 v0, v214
	s_cbranch_vccz .LBB0_700
	v_and_b32_e32 v4, 63, v0
	v_readlane_b32 s36, v238, 20
	v_ashrrev_i32_e32 v76, 3, v0
	v_mov_b32_e32 v3, 0
	v_lshlrev_b32_e32 v2, 4, v4
	v_readlane_b32 s48, v238, 32
	v_readlane_b32 s49, v238, 33
	v_and_b32_e32 v5, 7, v0
	v_lshlrev_b32_e32 v6, 11, v76
	v_lshlrev_b32_e32 v0, 5, v4
	v_mov_b32_e32 v1, v3
	v_lshl_add_u64 v[82:83], s[6:7], 0, v[2:3]
	v_lshlrev_b32_e32 v2, 3, v4
	v_readlane_b32 s50, v238, 34
	v_readlane_b32 s51, v238, 35
	s_mov_b64 s[28:29], s[48:49]
	v_lshlrev_b32_e32 v7, 8, v5
	v_lshl_add_u64 v[80:81], s[74:75], 0, v[0:1]
	v_lshl_add_u64 v[84:85], s[8:9], 0, v[2:3]
	v_bfe_u32 v172, v4, 3, 1
	v_lshlrev_b32_e32 v172, 2, v172
	v_bfe_u32 v240, v4, 4, 1
	v_lshl_or_b32 v172, v240, 1, v172
	v_bfe_u32 v240, v4, 5, 1
	v_or_b32_e32 v172, v172, v240
	v_lshlrev_b32_e32 v172, 4, v172
	v_lshlrev_b32_e32 v2, 6, v4
	v_readlane_b32 s37, v238, 21
	v_readlane_b32 s39, v238, 23
	v_readlane_b32 s41, v238, 25
	v_readlane_b32 s43, v238, 27
	v_readlane_b32 s45, v238, 29
	v_readlane_b32 s47, v238, 31
	s_mov_b64 s[30:31], s[50:51]
	v_and_b32_e32 v0, 0xffffc000, v6
	s_movk_i32 s3, 0x80
	v_ashrrev_i32_e32 v77, 31, v76
	v_lshlrev_b32_e32 v78, 5, v5
	v_and_b32_e32 v79, -8, v76
	v_cmp_eq_u32_e64 s[0:1], 0, v5
	v_cmp_eq_u32_e64 s[4:5], 1, v5
	v_cmp_eq_u32_e64 s[6:7], 2, v5
	v_cmp_eq_u32_e64 s[8:9], 3, v5
	v_cmp_eq_u32_e64 s[10:11], 4, v5
	v_cmp_eq_u32_e64 s[12:13], 5, v5
	v_cmp_eq_u32_e64 s[14:15], 6, v5
	v_cmp_eq_u32_e64 s[16:17], 7, v5
	v_lshl_add_u64 v[86:87], s[92:93], 0, v[2:3]
	v_lshl_add_u64 v[88:89], s[28:29], 0, v[2:3]
	v_lshl_add_u64 v[90:91], s[30:31], 0, v[2:3]
	v_or3_b32 v173, v0, v172, s3
	s_movk_i32 s3, 0xff00
	v_bfrev_b32_e32 v174, 1
	v_add_u32_e32 v175, v6, v7
	s_mov_b32 s27, 0x378e98ab
	s_mov_b32 s30, 0x3b7cd369
	s_mov_b32 s31, 0xbcc618b2
	s_mov_b32 s33, 0x3dda74e4
	s_mov_b32 s37, 0x3f228afd
	s_mov_b32 s39, 0x3e03c728
	s_mov_b32 s41, 0xbfb8aa3b
	s_mov_b32 s43, 0x42ce8ed0
	s_mov_b32 s45, 0xc2b17218
	v_mov_b32_e32 v176, 0x3ba10414
	s_brev_b32 s47, -2
	s_mov_b32 s26, 0x3f9837f0
	v_mov_b32_e32 v177, 0x3727c5ac
	s_mov_b32 s49, 0x800000
	v_mov_b32_e32 v178, 0xb9c68948
	v_mov_b32_e32 v179, 0x7f800000
	v_mov_b32_e32 v180, 0x3a800000
	v_readlane_b32 s38, v238, 22
	v_readlane_b32 s40, v238, 24
	v_readlane_b32 s42, v238, 26
	v_readlane_b32 s44, v238, 28
	v_readlane_b32 s46, v238, 30
	s_branch .LBB0_686

.Lex_tok:
	v_and_b32_e32 v62, 63, v214
	v_and_b32_e32 v63, 8, v62
	v_cmp_ne_u32_e64 s[0:1], 0, v63
	v_lshlrev_b32_e32 v63, 3, v62
	v_lshlrev_b32_e32 v62, 4, v62
	v_lshrrev_b32_e32 v215, 4, v172
	s_add_u32 s98, s94, 0x28c0000
	s_addc_u32 s99, s95, 0
	s_add_u32 s100, s94, 0x38d0000
	s_addc_u32 s101, s95, 0
	s_mov_b32 s12, 0
.Lex_half:
	s_lshl_b32 s10, s12, 2
	v_add_u32_e32 v64, s10, v79
	v_ashrrev_i32_e32 v65, 31, v64
	v_lshl_add_u64 v[64:65], s[28:29], 0, v[64:65]
	v_lshlrev_b64 v[0:1], 11, v[64:65]
	v_lshl_add_u64 v[0:1], v[80:81], 0, v[0:1]
	global_load_dwordx4 v[216:219], v[0:1], off
	global_load_dwordx4 v[220:223], v[0:1], off offset:16
	s_lshl_b32 s10, s12, 2
	s_add_i32 s10, s10, 1
	v_add_u32_e32 v64, s10, v79
	v_ashrrev_i32_e32 v65, 31, v64
	v_lshl_add_u64 v[64:65], s[28:29], 0, v[64:65]
	v_lshlrev_b64 v[0:1], 11, v[64:65]
	v_lshl_add_u64 v[0:1], v[80:81], 0, v[0:1]
	global_load_dwordx4 v[224:227], v[0:1], off
	global_load_dwordx4 v[228:231], v[0:1], off offset:16
	s_lshl_b32 s10, s12, 2
	s_add_i32 s10, s10, 2
	v_add_u32_e32 v64, s10, v79
	v_ashrrev_i32_e32 v65, 31, v64
	v_lshl_add_u64 v[64:65], s[28:29], 0, v[64:65]
	v_lshlrev_b64 v[0:1], 11, v[64:65]
	v_lshl_add_u64 v[0:1], v[80:81], 0, v[0:1]
	global_load_dwordx4 v[232:235], v[0:1], off
	global_load_dwordx4 v[236:239], v[0:1], off offset:16
	s_lshl_b32 s10, s12, 2
	s_add_i32 s10, s10, 3
	v_add_u32_e32 v64, s10, v79
	v_ashrrev_i32_e32 v65, 31, v64
	v_lshl_add_u64 v[64:65], s[28:29], 0, v[64:65]
	v_lshlrev_b64 v[0:1], 11, v[64:65]
	v_lshl_add_u64 v[0:1], v[80:81], 0, v[0:1]
	global_load_dwordx4 v[240:243], v[0:1], off
	global_load_dwordx4 v[244:247], v[0:1], off offset:16
	s_lshl_b32 s51, s12, 2
.Lex_sort:
	v_and_b32_e32 v8, 63, v214
	v_or_b32_e32 v11, s51, v79
	v_lshlrev_b32_e32 v11, 11, v11
	v_lshl_add_u32 v10, v8, 4, v11
	ds_read_b32 v4, v10
	ds_read_b32 v5, v10 offset:1024
	v_or_b32_e32 v12, 64, v8
	s_waitcnt lgkmcnt(0)
	v_lshl_or_b32 v4, v4, 7, v8
	v_lshl_or_b32 v5, v5, 7, v12
	v_xor_b32_e32 v9, 1, v8
	v_lshlrev_b32_e32 v9, 2, v9
	ds_bpermute_b32 v6, v9, v4
	ds_bpermute_b32 v7, v9, v5
	v_bfe_u32 v10, v8, 0, 1
	v_bfe_u32 v12, v8, 1, 1
	v_xor_b32_e32 v10, v10, v12
	v_cmp_eq_u32_e32 vcc, 0, v10
	s_waitcnt lgkmcnt(0)
	v_min_u32_e32 v10, v4, v6
	v_max_u32_e32 v12, v4, v6
	v_min_u32_e32 v13, v5, v7
	v_max_u32_e32 v14, v5, v7
	v_cndmask_b32_e32 v4, v12, v10, vcc
	v_cndmask_b32_e32 v5, v14, v13, vcc
	v_xor_b32_e32 v9, 2, v8
	v_lshlrev_b32_e32 v9, 2, v9
	ds_bpermute_b32 v6, v9, v4
	ds_bpermute_b32 v7, v9, v5
	v_bfe_u32 v10, v8, 1, 1
	v_bfe_u32 v12, v8, 2, 1
	v_xor_b32_e32 v10, v10, v12
	v_cmp_eq_u32_e32 vcc, 0, v10
	s_waitcnt lgkmcnt(0)
	v_min_u32_e32 v10, v4, v6
	v_max_u32_e32 v12, v4, v6
	v_min_u32_e32 v13, v5, v7
	v_max_u32_e32 v14, v5, v7
	v_cndmask_b32_e32 v4, v12, v10, vcc
	v_cndmask_b32_e32 v5, v14, v13, vcc
	v_xor_b32_e32 v9, 1, v8
	v_lshlrev_b32_e32 v9, 2, v9
	ds_bpermute_b32 v6, v9, v4
	ds_bpermute_b32 v7, v9, v5
	v_bfe_u32 v10, v8, 0, 1
	v_bfe_u32 v12, v8, 2, 1
	v_xor_b32_e32 v10, v10, v12
	v_cmp_eq_u32_e32 vcc, 0, v10
	s_waitcnt lgkmcnt(0)
	v_min_u32_e32 v10, v4, v6
	v_max_u32_e32 v12, v4, v6
	v_min_u32_e32 v13, v5, v7
	v_max_u32_e32 v14, v5, v7
	v_cndmask_b32_e32 v4, v12, v10, vcc
	v_cndmask_b32_e32 v5, v14, v13, vcc
	v_xor_b32_e32 v9, 4, v8
	v_lshlrev_b32_e32 v9, 2, v9
	ds_bpermute_b32 v6, v9, v4
	ds_bpermute_b32 v7, v9, v5
	v_bfe_u32 v10, v8, 2, 1
	v_bfe_u32 v12, v8, 3, 1
	v_xor_b32_e32 v10, v10, v12
	v_cmp_eq_u32_e32 vcc, 0, v10
	s_waitcnt lgkmcnt(0)
	v_min_u32_e32 v10, v4, v6
	v_max_u32_e32 v12, v4, v6
	v_min_u32_e32 v13, v5, v7
	v_max_u32_e32 v14, v5, v7
	v_cndmask_b32_e32 v4, v12, v10, vcc
	v_cndmask_b32_e32 v5, v14, v13, vcc
	v_xor_b32_e32 v9, 2, v8
	v_lshlrev_b32_e32 v9, 2, v9
	ds_bpermute_b32 v6, v9, v4
	ds_bpermute_b32 v7, v9, v5
	v_bfe_u32 v10, v8, 1, 1
	v_bfe_u32 v12, v8, 3, 1
	v_xor_b32_e32 v10, v10, v12
	v_cmp_eq_u32_e32 vcc, 0, v10
	s_waitcnt lgkmcnt(0)
	v_min_u32_e32 v10, v4, v6
	v_max_u32_e32 v12, v4, v6
	v_min_u32_e32 v13, v5, v7
	v_max_u32_e32 v14, v5, v7
	v_cndmask_b32_e32 v4, v12, v10, vcc
	v_cndmask_b32_e32 v5, v14, v13, vcc
	v_xor_b32_e32 v9, 1, v8
	v_lshlrev_b32_e32 v9, 2, v9
	ds_bpermute_b32 v6, v9, v4
	ds_bpermute_b32 v7, v9, v5
	v_bfe_u32 v10, v8, 0, 1
	v_bfe_u32 v12, v8, 3, 1
	v_xor_b32_e32 v10, v10, v12
	v_cmp_eq_u32_e32 vcc, 0, v10
	s_waitcnt lgkmcnt(0)
	v_min_u32_e32 v10, v4, v6
	v_max_u32_e32 v12, v4, v6
	v_min_u32_e32 v13, v5, v7
	v_max_u32_e32 v14, v5, v7
	v_cndmask_b32_e32 v4, v12, v10, vcc
	v_cndmask_b32_e32 v5, v14, v13, vcc
	v_xor_b32_e32 v9, 8, v8
	v_lshlrev_b32_e32 v9, 2, v9
	ds_bpermute_b32 v6, v9, v4
	ds_bpermute_b32 v7, v9, v5
	v_bfe_u32 v10, v8, 3, 1
	v_bfe_u32 v12, v8, 4, 1
	v_xor_b32_e32 v10, v10, v12
	v_cmp_eq_u32_e32 vcc, 0, v10
	s_waitcnt lgkmcnt(0)
	v_min_u32_e32 v10, v4, v6
	v_max_u32_e32 v12, v4, v6
	v_min_u32_e32 v13, v5, v7
	v_max_u32_e32 v14, v5, v7
	v_cndmask_b32_e32 v4, v12, v10, vcc
	v_cndmask_b32_e32 v5, v14, v13, vcc
	v_xor_b32_e32 v9, 4, v8
	v_lshlrev_b32_e32 v9, 2, v9
	ds_bpermute_b32 v6, v9, v4
	ds_bpermute_b32 v7, v9, v5
	v_bfe_u32 v10, v8, 2, 1
	v_bfe_u32 v12, v8, 4, 1
	v_xor_b32_e32 v10, v10, v12
	v_cmp_eq_u32_e32 vcc, 0, v10
	s_waitcnt lgkmcnt(0)
	v_min_u32_e32 v10, v4, v6
	v_max_u32_e32 v12, v4, v6
	v_min_u32_e32 v13, v5, v7
	v_max_u32_e32 v14, v5, v7
	v_cndmask_b32_e32 v4, v12, v10, vcc
	v_cndmask_b32_e32 v5, v14, v13, vcc
	v_xor_b32_e32 v9, 2, v8
	v_lshlrev_b32_e32 v9, 2, v9
	ds_bpermute_b32 v6, v9, v4
	ds_bpermute_b32 v7, v9, v5
	v_bfe_u32 v10, v8, 1, 1
	v_bfe_u32 v12, v8, 4, 1
	v_xor_b32_e32 v10, v10, v12
	v_cmp_eq_u32_e32 vcc, 0, v10
	s_waitcnt lgkmcnt(0)
	v_min_u32_e32 v10, v4, v6
	v_max_u32_e32 v12, v4, v6
	v_min_u32_e32 v13, v5, v7
	v_max_u32_e32 v14, v5, v7
	v_cndmask_b32_e32 v4, v12, v10, vcc
	v_cndmask_b32_e32 v5, v14, v13, vcc
	v_xor_b32_e32 v9, 1, v8
	v_lshlrev_b32_e32 v9, 2, v9
	ds_bpermute_b32 v6, v9, v4
	ds_bpermute_b32 v7, v9, v5
	v_bfe_u32 v10, v8, 0, 1
	v_bfe_u32 v12, v8, 4, 1
	v_xor_b32_e32 v10, v10, v12
	v_cmp_eq_u32_e32 vcc, 0, v10
	s_waitcnt lgkmcnt(0)
	v_min_u32_e32 v10, v4, v6
	v_max_u32_e32 v12, v4, v6
	v_min_u32_e32 v13, v5, v7
	v_max_u32_e32 v14, v5, v7
	v_cndmask_b32_e32 v4, v12, v10, vcc
	v_cndmask_b32_e32 v5, v14, v13, vcc
	v_xor_b32_e32 v9, 16, v8
	v_lshlrev_b32_e32 v9, 2, v9
	ds_bpermute_b32 v6, v9, v4
	ds_bpermute_b32 v7, v9, v5
	v_bfe_u32 v10, v8, 4, 1
	v_bfe_u32 v12, v8, 5, 1
	v_xor_b32_e32 v10, v10, v12
	v_cmp_eq_u32_e32 vcc, 0, v10
	s_waitcnt lgkmcnt(0)
	v_min_u32_e32 v10, v4, v6
	v_max_u32_e32 v12, v4, v6
	v_min_u32_e32 v13, v5, v7
	v_max_u32_e32 v14, v5, v7
	v_cndmask_b32_e32 v4, v12, v10, vcc
	v_cndmask_b32_e32 v5, v14, v13, vcc
	v_xor_b32_e32 v9, 8, v8
	v_lshlrev_b32_e32 v9, 2, v9
	ds_bpermute_b32 v6, v9, v4
	ds_bpermute_b32 v7, v9, v5
	v_bfe_u32 v10, v8, 3, 1
	v_bfe_u32 v12, v8, 5, 1
	v_xor_b32_e32 v10, v10, v12
	v_cmp_eq_u32_e32 vcc, 0, v10
	s_waitcnt lgkmcnt(0)
	v_min_u32_e32 v10, v4, v6
	v_max_u32_e32 v12, v4, v6
	v_min_u32_e32 v13, v5, v7
	v_max_u32_e32 v14, v5, v7
	v_cndmask_b32_e32 v4, v12, v10, vcc
	v_cndmask_b32_e32 v5, v14, v13, vcc
	v_xor_b32_e32 v9, 4, v8
	v_lshlrev_b32_e32 v9, 2, v9
	ds_bpermute_b32 v6, v9, v4
	ds_bpermute_b32 v7, v9, v5
	v_bfe_u32 v10, v8, 2, 1
	v_bfe_u32 v12, v8, 5, 1
	v_xor_b32_e32 v10, v10, v12
	v_cmp_eq_u32_e32 vcc, 0, v10
	s_waitcnt lgkmcnt(0)
	v_min_u32_e32 v10, v4, v6
	v_max_u32_e32 v12, v4, v6
	v_min_u32_e32 v13, v5, v7
	v_max_u32_e32 v14, v5, v7
	v_cndmask_b32_e32 v4, v12, v10, vcc
	v_cndmask_b32_e32 v5, v14, v13, vcc
	v_xor_b32_e32 v9, 2, v8
	v_lshlrev_b32_e32 v9, 2, v9
	ds_bpermute_b32 v6, v9, v4
	ds_bpermute_b32 v7, v9, v5
	v_bfe_u32 v10, v8, 1, 1
	v_bfe_u32 v12, v8, 5, 1
	v_xor_b32_e32 v10, v10, v12
	v_cmp_eq_u32_e32 vcc, 0, v10
	s_waitcnt lgkmcnt(0)
	v_min_u32_e32 v10, v4, v6
	v_max_u32_e32 v12, v4, v6
	v_min_u32_e32 v13, v5, v7
	v_max_u32_e32 v14, v5, v7
	v_cndmask_b32_e32 v4, v12, v10, vcc
	v_cndmask_b32_e32 v5, v14, v13, vcc
	v_xor_b32_e32 v9, 1, v8
	v_lshlrev_b32_e32 v9, 2, v9
	ds_bpermute_b32 v6, v9, v4
	ds_bpermute_b32 v7, v9, v5
	v_bfe_u32 v10, v8, 0, 1
	v_bfe_u32 v12, v8, 5, 1
	v_xor_b32_e32 v10, v10, v12
	v_cmp_eq_u32_e32 vcc, 0, v10
	s_waitcnt lgkmcnt(0)
	v_min_u32_e32 v10, v4, v6
	v_max_u32_e32 v12, v4, v6
	v_min_u32_e32 v13, v5, v7
	v_max_u32_e32 v14, v5, v7
	v_cndmask_b32_e32 v4, v12, v10, vcc
	v_cndmask_b32_e32 v5, v14, v13, vcc
	v_xor_b32_e32 v9, 32, v8
	v_lshlrev_b32_e32 v9, 2, v9
	ds_bpermute_b32 v6, v9, v4
	ds_bpermute_b32 v7, v9, v5
	v_bfe_u32 v10, v8, 5, 1
	v_cmp_eq_u32_e32 vcc, 0, v10
	s_waitcnt lgkmcnt(0)
	v_min_u32_e32 v10, v4, v6
	v_max_u32_e32 v12, v4, v6
	v_min_u32_e32 v13, v5, v7
	v_max_u32_e32 v14, v5, v7
	v_cndmask_b32_e32 v4, v12, v10, vcc
	v_cndmask_b32_e32 v5, v13, v14, vcc
	v_xor_b32_e32 v9, 16, v8
	v_lshlrev_b32_e32 v9, 2, v9
	ds_bpermute_b32 v6, v9, v4
	ds_bpermute_b32 v7, v9, v5
	v_bfe_u32 v10, v8, 4, 1
	v_cmp_eq_u32_e32 vcc, 0, v10
	s_waitcnt lgkmcnt(0)
	v_min_u32_e32 v10, v4, v6
	v_max_u32_e32 v12, v4, v6
	v_min_u32_e32 v13, v5, v7
	v_max_u32_e32 v14, v5, v7
	v_cndmask_b32_e32 v4, v12, v10, vcc
	v_cndmask_b32_e32 v5, v13, v14, vcc
	v_xor_b32_e32 v9, 8, v8
	v_lshlrev_b32_e32 v9, 2, v9
	ds_bpermute_b32 v6, v9, v4
	ds_bpermute_b32 v7, v9, v5
	v_bfe_u32 v10, v8, 3, 1
	v_cmp_eq_u32_e32 vcc, 0, v10
	s_waitcnt lgkmcnt(0)
	v_min_u32_e32 v10, v4, v6
	v_max_u32_e32 v12, v4, v6
	v_min_u32_e32 v13, v5, v7
	v_max_u32_e32 v14, v5, v7
	v_cndmask_b32_e32 v4, v12, v10, vcc
	v_cndmask_b32_e32 v5, v13, v14, vcc
	v_xor_b32_e32 v9, 4, v8
	v_lshlrev_b32_e32 v9, 2, v9
	ds_bpermute_b32 v6, v9, v4
	ds_bpermute_b32 v7, v9, v5
	v_bfe_u32 v10, v8, 2, 1
	v_cmp_eq_u32_e32 vcc, 0, v10
	s_waitcnt lgkmcnt(0)
	v_min_u32_e32 v10, v4, v6
	v_max_u32_e32 v12, v4, v6
	v_min_u32_e32 v13, v5, v7
	v_max_u32_e32 v14, v5, v7
	v_cndmask_b32_e32 v4, v12, v10, vcc
	v_cndmask_b32_e32 v5, v13, v14, vcc
	v_xor_b32_e32 v9, 2, v8
	v_lshlrev_b32_e32 v9, 2, v9
	ds_bpermute_b32 v6, v9, v4
	ds_bpermute_b32 v7, v9, v5
	v_bfe_u32 v10, v8, 1, 1
	v_cmp_eq_u32_e32 vcc, 0, v10
	s_waitcnt lgkmcnt(0)
	v_min_u32_e32 v10, v4, v6
	v_max_u32_e32 v12, v4, v6
	v_min_u32_e32 v13, v5, v7
	v_max_u32_e32 v14, v5, v7
	v_cndmask_b32_e32 v4, v12, v10, vcc
	v_cndmask_b32_e32 v5, v13, v14, vcc
	v_xor_b32_e32 v9, 1, v8
	v_lshlrev_b32_e32 v9, 2, v9
	ds_bpermute_b32 v6, v9, v4
	ds_bpermute_b32 v7, v9, v5
	v_bfe_u32 v10, v8, 0, 1
	v_cmp_eq_u32_e32 vcc, 0, v10
	s_waitcnt lgkmcnt(0)
	v_min_u32_e32 v10, v4, v6
	v_max_u32_e32 v12, v4, v6
	v_min_u32_e32 v13, v5, v7
	v_max_u32_e32 v14, v5, v7
	v_cndmask_b32_e32 v4, v12, v10, vcc
	v_cndmask_b32_e32 v5, v13, v14, vcc
	v_min_u32_e32 v10, v4, v5
	v_max_u32_e32 v5, v4, v5
	v_mov_b32_e32 v4, v10
	v_xor_b32_e32 v9, 32, v8
	v_lshlrev_b32_e32 v9, 2, v9
	ds_bpermute_b32 v6, v9, v4
	ds_bpermute_b32 v7, v9, v5
	v_bfe_u32 v10, v8, 5, 1
	v_cmp_eq_u32_e32 vcc, 0, v10
	s_waitcnt lgkmcnt(0)
	v_min_u32_e32 v10, v4, v6
	v_max_u32_e32 v12, v4, v6
	v_min_u32_e32 v13, v5, v7
	v_max_u32_e32 v14, v5, v7
	v_cndmask_b32_e32 v4, v12, v10, vcc
	v_cndmask_b32_e32 v5, v14, v13, vcc
	v_xor_b32_e32 v9, 16, v8
	v_lshlrev_b32_e32 v9, 2, v9
	ds_bpermute_b32 v6, v9, v4
	ds_bpermute_b32 v7, v9, v5
	v_bfe_u32 v10, v8, 4, 1
	v_cmp_eq_u32_e32 vcc, 0, v10
	s_waitcnt lgkmcnt(0)
	v_min_u32_e32 v10, v4, v6
	v_max_u32_e32 v12, v4, v6
	v_min_u32_e32 v13, v5, v7
	v_max_u32_e32 v14, v5, v7
	v_cndmask_b32_e32 v4, v12, v10, vcc
	v_cndmask_b32_e32 v5, v14, v13, vcc
	v_xor_b32_e32 v9, 8, v8
	v_lshlrev_b32_e32 v9, 2, v9
	ds_bpermute_b32 v6, v9, v4
	ds_bpermute_b32 v7, v9, v5
	v_bfe_u32 v10, v8, 3, 1
	v_cmp_eq_u32_e32 vcc, 0, v10
	s_waitcnt lgkmcnt(0)
	v_min_u32_e32 v10, v4, v6
	v_max_u32_e32 v12, v4, v6
	v_min_u32_e32 v13, v5, v7
	v_max_u32_e32 v14, v5, v7
	v_cndmask_b32_e32 v4, v12, v10, vcc
	v_cndmask_b32_e32 v5, v14, v13, vcc
	v_xor_b32_e32 v9, 4, v8
	v_lshlrev_b32_e32 v9, 2, v9
	ds_bpermute_b32 v6, v9, v4
	ds_bpermute_b32 v7, v9, v5
	v_bfe_u32 v10, v8, 2, 1
	v_cmp_eq_u32_e32 vcc, 0, v10
	s_waitcnt lgkmcnt(0)
	v_min_u32_e32 v10, v4, v6
	v_max_u32_e32 v12, v4, v6
	v_min_u32_e32 v13, v5, v7
	v_max_u32_e32 v14, v5, v7
	v_cndmask_b32_e32 v4, v12, v10, vcc
	v_cndmask_b32_e32 v5, v14, v13, vcc
	v_xor_b32_e32 v9, 2, v8
	v_lshlrev_b32_e32 v9, 2, v9
	ds_bpermute_b32 v6, v9, v4
	ds_bpermute_b32 v7, v9, v5
	v_bfe_u32 v10, v8, 1, 1
	v_cmp_eq_u32_e32 vcc, 0, v10
	s_waitcnt lgkmcnt(0)
	v_min_u32_e32 v10, v4, v6
	v_max_u32_e32 v12, v4, v6
	v_min_u32_e32 v13, v5, v7
	v_max_u32_e32 v14, v5, v7
	v_cndmask_b32_e32 v4, v12, v10, vcc
	v_cndmask_b32_e32 v5, v14, v13, vcc
	v_xor_b32_e32 v9, 1, v8
	v_lshlrev_b32_e32 v9, 2, v9
	ds_bpermute_b32 v6, v9, v4
	ds_bpermute_b32 v7, v9, v5
	v_bfe_u32 v10, v8, 0, 1
	v_cmp_eq_u32_e32 vcc, 0, v10
	s_waitcnt lgkmcnt(0)
	v_min_u32_e32 v10, v4, v6
	v_max_u32_e32 v12, v4, v6
	v_min_u32_e32 v13, v5, v7
	v_max_u32_e32 v14, v5, v7
	v_cndmask_b32_e32 v4, v12, v10, vcc
	v_cndmask_b32_e32 v5, v14, v13, vcc
	v_and_b32_e32 v10, 0x7f, v4
	v_and_b32_e32 v12, 0x7f, v5
	v_lshl_add_u32 v10, v10, 4, v11
	v_lshl_add_u32 v12, v12, 4, v11
	ds_read_b128 v[16:19], v12
	ds_read_b128 v[12:15], v10
	v_lshl_add_u32 v9, v8, 4, v11
	s_waitcnt lgkmcnt(0)
	ds_write_b128 v9, v[12:15]
	ds_write_b128 v9, v[16:19] offset:1024
	s_waitcnt lgkmcnt(0)
	s_add_i32 s51, s51, 1
	s_and_b32 s17, s51, 3
	s_cmp_lg_u32 s17, 0
	s_cbranch_scc1 .Lex_sort
	s_lshl_b32 s10, s12, 2
	v_add_u32_e32 v255, s10, v79
	v_lshlrev_b32_e32 v255, 11, v255
	v_and_b32_e32 v8, 63, v214
	v_lshl_add_u32 v4, v8, 7, v255
	ds_read_b32 v5, v4
	ds_read_b32 v6, v4 offset:112
	s_waitcnt lgkmcnt(0)
	v_add_u32_e32 v5, v5, v6
	v_lshl_or_b32 v60, v5, 6, v8
	v_xor_b32_e32 v9, 1, v8
	v_lshlrev_b32_e32 v9, 2, v9
	ds_bpermute_b32 v5, v9, v60
	v_bfe_u32 v13, v8, 0, 1
	v_bfe_u32 v10, v8, 1, 1
	v_xor_b32_e32 v13, v13, v10
	v_cmp_eq_u32_e32 vcc, 0, v13
	s_waitcnt lgkmcnt(0)
	v_min_u32_e32 v10, v60, v5
	v_max_u32_e32 v12, v60, v5
	v_cndmask_b32_e32 v60, v12, v10, vcc
	v_xor_b32_e32 v9, 2, v8
	v_lshlrev_b32_e32 v9, 2, v9
	ds_bpermute_b32 v5, v9, v60
	v_bfe_u32 v13, v8, 1, 1
	v_bfe_u32 v10, v8, 2, 1
	v_xor_b32_e32 v13, v13, v10
	v_cmp_eq_u32_e32 vcc, 0, v13
	s_waitcnt lgkmcnt(0)
	v_min_u32_e32 v10, v60, v5
	v_max_u32_e32 v12, v60, v5
	v_cndmask_b32_e32 v60, v12, v10, vcc
	v_xor_b32_e32 v9, 1, v8
	v_lshlrev_b32_e32 v9, 2, v9
	ds_bpermute_b32 v5, v9, v60
	v_bfe_u32 v13, v8, 0, 1
	v_bfe_u32 v10, v8, 2, 1
	v_xor_b32_e32 v13, v13, v10
	v_cmp_eq_u32_e32 vcc, 0, v13
	s_waitcnt lgkmcnt(0)
	v_min_u32_e32 v10, v60, v5
	v_max_u32_e32 v12, v60, v5
	v_cndmask_b32_e32 v60, v12, v10, vcc
	v_xor_b32_e32 v9, 4, v8
	v_lshlrev_b32_e32 v9, 2, v9
	ds_bpermute_b32 v5, v9, v60
	v_bfe_u32 v13, v8, 2, 1
	v_bfe_u32 v10, v8, 3, 1
	v_xor_b32_e32 v13, v13, v10
	v_cmp_eq_u32_e32 vcc, 0, v13
	s_waitcnt lgkmcnt(0)
	v_min_u32_e32 v10, v60, v5
	v_max_u32_e32 v12, v60, v5
	v_cndmask_b32_e32 v60, v12, v10, vcc
	v_xor_b32_e32 v9, 2, v8
	v_lshlrev_b32_e32 v9, 2, v9
	ds_bpermute_b32 v5, v9, v60
	v_bfe_u32 v13, v8, 1, 1
	v_bfe_u32 v10, v8, 3, 1
	v_xor_b32_e32 v13, v13, v10
	v_cmp_eq_u32_e32 vcc, 0, v13
	s_waitcnt lgkmcnt(0)
	v_min_u32_e32 v10, v60, v5
	v_max_u32_e32 v12, v60, v5
	v_cndmask_b32_e32 v60, v12, v10, vcc
	v_xor_b32_e32 v9, 1, v8
	v_lshlrev_b32_e32 v9, 2, v9
	ds_bpermute_b32 v5, v9, v60
	v_bfe_u32 v13, v8, 0, 1
	v_bfe_u32 v10, v8, 3, 1
	v_xor_b32_e32 v13, v13, v10
	v_cmp_eq_u32_e32 vcc, 0, v13
	s_waitcnt lgkmcnt(0)
	v_min_u32_e32 v10, v60, v5
	v_max_u32_e32 v12, v60, v5
	v_cndmask_b32_e32 v60, v12, v10, vcc
	v_xor_b32_e32 v9, 8, v8
	v_lshlrev_b32_e32 v9, 2, v9
	ds_bpermute_b32 v5, v9, v60
	v_bfe_u32 v13, v8, 3, 1
	v_bfe_u32 v10, v8, 4, 1
	v_xor_b32_e32 v13, v13, v10
	v_cmp_eq_u32_e32 vcc, 0, v13
	s_waitcnt lgkmcnt(0)
	v_min_u32_e32 v10, v60, v5
	v_max_u32_e32 v12, v60, v5
	v_cndmask_b32_e32 v60, v12, v10, vcc
	v_xor_b32_e32 v9, 4, v8
	v_lshlrev_b32_e32 v9, 2, v9
	ds_bpermute_b32 v5, v9, v60
	v_bfe_u32 v13, v8, 2, 1
	v_bfe_u32 v10, v8, 4, 1
	v_xor_b32_e32 v13, v13, v10
	v_cmp_eq_u32_e32 vcc, 0, v13
	s_waitcnt lgkmcnt(0)
	v_min_u32_e32 v10, v60, v5
	v_max_u32_e32 v12, v60, v5
	v_cndmask_b32_e32 v60, v12, v10, vcc
	v_xor_b32_e32 v9, 2, v8
	v_lshlrev_b32_e32 v9, 2, v9
	ds_bpermute_b32 v5, v9, v60
	v_bfe_u32 v13, v8, 1, 1
	v_bfe_u32 v10, v8, 4, 1
	v_xor_b32_e32 v13, v13, v10
	v_cmp_eq_u32_e32 vcc, 0, v13
	s_waitcnt lgkmcnt(0)
	v_min_u32_e32 v10, v60, v5
	v_max_u32_e32 v12, v60, v5
	v_cndmask_b32_e32 v60, v12, v10, vcc
	v_xor_b32_e32 v9, 1, v8
	v_lshlrev_b32_e32 v9, 2, v9
	ds_bpermute_b32 v5, v9, v60
	v_bfe_u32 v13, v8, 0, 1
	v_bfe_u32 v10, v8, 4, 1
	v_xor_b32_e32 v13, v13, v10
	v_cmp_eq_u32_e32 vcc, 0, v13
	s_waitcnt lgkmcnt(0)
	v_min_u32_e32 v10, v60, v5
	v_max_u32_e32 v12, v60, v5
	v_cndmask_b32_e32 v60, v12, v10, vcc
	v_xor_b32_e32 v9, 16, v8
	v_lshlrev_b32_e32 v9, 2, v9
	ds_bpermute_b32 v5, v9, v60
	v_bfe_u32 v13, v8, 4, 1
	v_bfe_u32 v10, v8, 5, 1
	v_xor_b32_e32 v13, v13, v10
	v_cmp_eq_u32_e32 vcc, 0, v13
	s_waitcnt lgkmcnt(0)
	v_min_u32_e32 v10, v60, v5
	v_max_u32_e32 v12, v60, v5
	v_cndmask_b32_e32 v60, v12, v10, vcc
	v_xor_b32_e32 v9, 8, v8
	v_lshlrev_b32_e32 v9, 2, v9
	ds_bpermute_b32 v5, v9, v60
	v_bfe_u32 v13, v8, 3, 1
	v_bfe_u32 v10, v8, 5, 1
	v_xor_b32_e32 v13, v13, v10
	v_cmp_eq_u32_e32 vcc, 0, v13
	s_waitcnt lgkmcnt(0)
	v_min_u32_e32 v10, v60, v5
	v_max_u32_e32 v12, v60, v5
	v_cndmask_b32_e32 v60, v12, v10, vcc
	v_xor_b32_e32 v9, 4, v8
	v_lshlrev_b32_e32 v9, 2, v9
	ds_bpermute_b32 v5, v9, v60
	v_bfe_u32 v13, v8, 2, 1
	v_bfe_u32 v10, v8, 5, 1
	v_xor_b32_e32 v13, v13, v10
	v_cmp_eq_u32_e32 vcc, 0, v13
	s_waitcnt lgkmcnt(0)
	v_min_u32_e32 v10, v60, v5
	v_max_u32_e32 v12, v60, v5
	v_cndmask_b32_e32 v60, v12, v10, vcc
	v_xor_b32_e32 v9, 2, v8
	v_lshlrev_b32_e32 v9, 2, v9
	ds_bpermute_b32 v5, v9, v60
	v_bfe_u32 v13, v8, 1, 1
	v_bfe_u32 v10, v8, 5, 1
	v_xor_b32_e32 v13, v13, v10
	v_cmp_eq_u32_e32 vcc, 0, v13
	s_waitcnt lgkmcnt(0)
	v_min_u32_e32 v10, v60, v5
	v_max_u32_e32 v12, v60, v5
	v_cndmask_b32_e32 v60, v12, v10, vcc
	v_xor_b32_e32 v9, 1, v8
	v_lshlrev_b32_e32 v9, 2, v9
	ds_bpermute_b32 v5, v9, v60
	v_bfe_u32 v13, v8, 0, 1
	v_bfe_u32 v10, v8, 5, 1
	v_xor_b32_e32 v13, v13, v10
	v_cmp_eq_u32_e32 vcc, 0, v13
	s_waitcnt lgkmcnt(0)
	v_min_u32_e32 v10, v60, v5
	v_max_u32_e32 v12, v60, v5
	v_cndmask_b32_e32 v60, v12, v10, vcc
	v_xor_b32_e32 v9, 32, v8
	v_lshlrev_b32_e32 v9, 2, v9
	ds_bpermute_b32 v5, v9, v60
	v_bfe_u32 v13, v8, 5, 1
	v_cmp_eq_u32_e32 vcc, 0, v13
	s_waitcnt lgkmcnt(0)
	v_min_u32_e32 v10, v60, v5
	v_max_u32_e32 v12, v60, v5
	v_cndmask_b32_e32 v60, v12, v10, vcc
	v_xor_b32_e32 v9, 16, v8
	v_lshlrev_b32_e32 v9, 2, v9
	ds_bpermute_b32 v5, v9, v60
	v_bfe_u32 v13, v8, 4, 1
	v_cmp_eq_u32_e32 vcc, 0, v13
	s_waitcnt lgkmcnt(0)
	v_min_u32_e32 v10, v60, v5
	v_max_u32_e32 v12, v60, v5
	v_cndmask_b32_e32 v60, v12, v10, vcc
	v_xor_b32_e32 v9, 8, v8
	v_lshlrev_b32_e32 v9, 2, v9
	ds_bpermute_b32 v5, v9, v60
	v_bfe_u32 v13, v8, 3, 1
	v_cmp_eq_u32_e32 vcc, 0, v13
	s_waitcnt lgkmcnt(0)
	v_min_u32_e32 v10, v60, v5
	v_max_u32_e32 v12, v60, v5
	v_cndmask_b32_e32 v60, v12, v10, vcc
	v_xor_b32_e32 v9, 4, v8
	v_lshlrev_b32_e32 v9, 2, v9
	ds_bpermute_b32 v5, v9, v60
	v_bfe_u32 v13, v8, 2, 1
	v_cmp_eq_u32_e32 vcc, 0, v13
	s_waitcnt lgkmcnt(0)
	v_min_u32_e32 v10, v60, v5
	v_max_u32_e32 v12, v60, v5
	v_cndmask_b32_e32 v60, v12, v10, vcc
	v_xor_b32_e32 v9, 2, v8
	v_lshlrev_b32_e32 v9, 2, v9
	ds_bpermute_b32 v5, v9, v60
	v_bfe_u32 v13, v8, 1, 1
	v_cmp_eq_u32_e32 vcc, 0, v13
	s_waitcnt lgkmcnt(0)
	v_min_u32_e32 v10, v60, v5
	v_max_u32_e32 v12, v60, v5
	v_cndmask_b32_e32 v60, v12, v10, vcc
	v_xor_b32_e32 v9, 1, v8
	v_lshlrev_b32_e32 v9, 2, v9
	ds_bpermute_b32 v5, v9, v60
	v_bfe_u32 v13, v8, 0, 1
	v_cmp_eq_u32_e32 vcc, 0, v13
	s_waitcnt lgkmcnt(0)
	v_min_u32_e32 v10, v60, v5
	v_max_u32_e32 v12, v60, v5
	v_cndmask_b32_e32 v60, v12, v10, vcc
	s_waitcnt vmcnt(0)
	v_mov_b32_e32 v4, v216
	v_mov_b32_e32 v5, v217
	v_mov_b32_e32 v6, v218
	v_mov_b32_e32 v7, v219
	v_mov_b32_e32 v8, v220
	v_mov_b32_e32 v9, v221
	v_mov_b32_e32 v10, v222
	v_mov_b32_e32 v11, v223
	v_mov_b32_e32 v12, v224
	v_mov_b32_e32 v13, v225
	v_mov_b32_e32 v14, v226
	v_mov_b32_e32 v15, v227
	v_mov_b32_e32 v16, v228
	v_mov_b32_e32 v17, v229
	v_mov_b32_e32 v18, v230
	v_mov_b32_e32 v19, v231
	v_mov_b32_e32 v20, v232
	v_mov_b32_e32 v21, v233
	v_mov_b32_e32 v22, v234
	v_mov_b32_e32 v23, v235
	v_mov_b32_e32 v24, v236
	v_mov_b32_e32 v25, v237
	v_mov_b32_e32 v26, v238
	v_mov_b32_e32 v27, v239
	v_mov_b32_e32 v28, v240
	v_mov_b32_e32 v29, v241
	v_mov_b32_e32 v30, v242
	v_mov_b32_e32 v31, v243
	v_mov_b32_e32 v32, v244
	v_mov_b32_e32 v33, v245
	v_mov_b32_e32 v34, v246
	v_mov_b32_e32 v35, v247
	v_lshlrev_b32_e32 v96, 16, v4
	v_and_b32_e32 v97, 0xffff0000, v4
	v_lshlrev_b32_e32 v92, 16, v8
	v_and_b32_e32 v93, 0xffff0000, v8
	v_lshlrev_b32_e32 v98, 16, v5
	v_and_b32_e32 v99, 0xffff0000, v5
	v_lshlrev_b32_e32 v94, 16, v9
	v_and_b32_e32 v95, 0xffff0000, v9
	v_lshlrev_b32_e32 v100, 16, v6
	v_and_b32_e32 v101, 0xffff0000, v6
	v_lshlrev_b32_e32 v104, 16, v10
	v_and_b32_e32 v105, 0xffff0000, v10
	v_lshlrev_b32_e32 v102, 16, v7
	v_and_b32_e32 v103, 0xffff0000, v7
	v_lshlrev_b32_e32 v106, 16, v11
	v_and_b32_e32 v107, 0xffff0000, v11
	v_lshlrev_b32_e32 v134, 16, v12
	v_and_b32_e32 v135, 0xffff0000, v12
	v_lshlrev_b32_e32 v148, 16, v16
	v_and_b32_e32 v149, 0xffff0000, v16
	v_lshlrev_b32_e32 v142, 16, v13
	v_and_b32_e32 v143, 0xffff0000, v13
	v_lshlrev_b32_e32 v150, 16, v17
	v_and_b32_e32 v151, 0xffff0000, v17
	v_lshlrev_b32_e32 v144, 16, v14
	v_and_b32_e32 v145, 0xffff0000, v14
	v_lshlrev_b32_e32 v152, 16, v18
	v_and_b32_e32 v153, 0xffff0000, v18
	v_lshlrev_b32_e32 v146, 16, v15
	v_and_b32_e32 v147, 0xffff0000, v15
	v_lshlrev_b32_e32 v154, 16, v19
	v_and_b32_e32 v155, 0xffff0000, v19
	v_lshlrev_b32_e32 v216, 16, v20
	v_and_b32_e32 v217, 0xffff0000, v20
	v_lshlrev_b32_e32 v224, 16, v24
	v_and_b32_e32 v225, 0xffff0000, v24
	v_lshlrev_b32_e32 v218, 16, v21
	v_and_b32_e32 v219, 0xffff0000, v21
	v_lshlrev_b32_e32 v226, 16, v25
	v_and_b32_e32 v227, 0xffff0000, v25
	v_lshlrev_b32_e32 v220, 16, v22
	v_and_b32_e32 v221, 0xffff0000, v22
	v_lshlrev_b32_e32 v228, 16, v26
	v_and_b32_e32 v229, 0xffff0000, v26
	v_lshlrev_b32_e32 v222, 16, v23
	v_and_b32_e32 v223, 0xffff0000, v23
	v_lshlrev_b32_e32 v230, 16, v27
	v_and_b32_e32 v231, 0xffff0000, v27
	v_lshlrev_b32_e32 v232, 16, v28
	v_and_b32_e32 v233, 0xffff0000, v28
	v_lshlrev_b32_e32 v70, 16, v32
	v_and_b32_e32 v71, 0xffff0000, v32
	v_lshlrev_b32_e32 v234, 16, v29
	v_and_b32_e32 v235, 0xffff0000, v29
	v_lshlrev_b32_e32 v72, 16, v33
	v_and_b32_e32 v73, 0xffff0000, v33
	v_lshlrev_b32_e32 v236, 16, v30
	v_and_b32_e32 v237, 0xffff0000, v30
	v_lshlrev_b32_e32 v74, 16, v34
	v_and_b32_e32 v75, 0xffff0000, v34
	v_lshlrev_b32_e32 v238, 16, v31
	v_and_b32_e32 v239, 0xffff0000, v31
	v_lshlrev_b32_e32 v2, 16, v35
	v_and_b32_e32 v3, 0xffff0000, v35
	v_mov_b32_e32 v108, 0
	v_mov_b32_e32 v109, 0
	v_mov_b32_e32 v110, 0
	v_mov_b32_e32 v111, 0
	v_mov_b32_e32 v112, 0
	v_mov_b32_e32 v113, 0
	v_mov_b32_e32 v114, 0
	v_mov_b32_e32 v115, 0
	v_mov_b32_e32 v116, 0
	v_mov_b32_e32 v117, 0
	v_mov_b32_e32 v118, 0
	v_mov_b32_e32 v119, 0
	v_mov_b32_e32 v120, 0
	v_mov_b32_e32 v121, 0
	v_mov_b32_e32 v122, 0
	v_mov_b32_e32 v123, 0
	v_mov_b32_e32 v124, 0
	v_mov_b32_e32 v125, 0
	v_mov_b32_e32 v126, 0
	v_mov_b32_e32 v127, 0
	v_mov_b32_e32 v128, 0
	v_mov_b32_e32 v129, 0
	v_mov_b32_e32 v130, 0
	v_mov_b32_e32 v131, 0
	v_mov_b32_e32 v132, 0
	v_mov_b32_e32 v133, 0
	v_mov_b32_e32 v136, 0
	v_mov_b32_e32 v137, 0
	v_mov_b32_e32 v138, 0
	v_mov_b32_e32 v139, 0
	v_mov_b32_e32 v140, 0
	v_mov_b32_e32 v141, 0
	v_mov_b32_e32 v188, 0
	v_mov_b32_e32 v189, 0
	v_mov_b32_e32 v190, 0
	v_mov_b32_e32 v191, 0
	v_mov_b32_e32 v192, 0
	v_mov_b32_e32 v193, 0
	v_mov_b32_e32 v194, 0
	v_mov_b32_e32 v195, 0
	v_mov_b32_e32 v196, 0
	v_mov_b32_e32 v197, 0
	v_mov_b32_e32 v198, 0
	v_mov_b32_e32 v199, 0
	v_mov_b32_e32 v200, 0
	v_mov_b32_e32 v201, 0
	v_mov_b32_e32 v202, 0
	v_mov_b32_e32 v203, 0
	v_mov_b32_e32 v204, 0
	v_mov_b32_e32 v205, 0
	v_mov_b32_e32 v206, 0
	v_mov_b32_e32 v207, 0
	v_mov_b32_e32 v208, 0
	v_mov_b32_e32 v209, 0
	v_mov_b32_e32 v210, 0
	v_mov_b32_e32 v211, 0
	v_mov_b32_e32 v212, 0
	v_mov_b32_e32 v213, 0
	v_mov_b32_e32 v186, 0
	v_mov_b32_e32 v187, 0
	v_mov_b32_e32 v66, 0
	v_mov_b32_e32 v67, 0
	v_mov_b32_e32 v68, 0
	v_mov_b32_e32 v69, 0
	v_lshl_add_u32 v61, v215, 4, v255
	s_mov_b32 s4, 0
	v_readlane_b32 s14, v60, s4
	s_and_b32 s14, s14, 63
	v_lshl_add_u32 v0, s14, 7, v61
	ds_read_b128 v[56:59], v0
	s_waitcnt lgkmcnt(0)
	v_readlane_b32 s5, v56, 0
	s_lshl_b32 s52, s5, 10
	s_add_u32 s56, s98, s52
	s_addc_u32 s57, s99, 0
	global_load_dwordx4 v[4:7], v62, s[56:57]
	v_readlane_b32 s6, v56, 32
	s_lshl_b32 s52, s6, 10
	s_add_u32 s56, s98, s52
	s_addc_u32 s57, s99, 0
	global_load_dwordx4 v[8:11], v62, s[56:57]
	v_readlane_b32 s7, v56, 16
	s_lshl_b32 s52, s7, 10
	s_add_u32 s56, s98, s52
	s_addc_u32 s57, s99, 0
	global_load_dwordx4 v[12:15], v62, s[56:57]
	v_readlane_b32 s8, v56, 48
	s_lshl_b32 s52, s8, 10
	s_add_u32 s56, s98, s52
	s_addc_u32 s57, s99, 0
	global_load_dwordx4 v[16:19], v62, s[56:57]
	v_readlane_b32 s9, v56, 8
	s_lshl_b32 s52, s9, 10
	s_add_u32 s56, s98, s52
	s_addc_u32 s57, s99, 0
	global_load_dwordx4 v[20:23], v62, s[56:57]
	v_readlane_b32 s11, v56, 40
	s_lshl_b32 s52, s11, 10
	s_add_u32 s56, s98, s52
	s_addc_u32 s57, s99, 0
	global_load_dwordx4 v[24:27], v62, s[56:57]
	v_readlane_b32 s13, v56, 24
	s_lshl_b32 s52, s13, 10
	s_add_u32 s56, s98, s52
	s_addc_u32 s57, s99, 0
	global_load_dwordx4 v[28:31], v62, s[56:57]
	v_readlane_b32 s16, v56, 56
	s_lshl_b32 s52, s16, 10
	s_add_u32 s56, s98, s52
	s_addc_u32 s57, s99, 0
	global_load_dwordx4 v[32:35], v62, s[56:57]
	s_lshl_b32 s52, s5, 9
	s_add_u32 s58, s100, s52
	s_addc_u32 s59, s101, 0
	global_load_dwordx2 v[36:37], v63, s[58:59]
	s_lshl_b32 s52, s6, 9
	s_add_u32 s58, s100, s52
	s_addc_u32 s59, s101, 0
	global_load_dwordx2 v[38:39], v63, s[58:59]
	s_lshl_b32 s52, s7, 9
	s_add_u32 s58, s100, s52
	s_addc_u32 s59, s101, 0
	global_load_dwordx2 v[40:41], v63, s[58:59]
	s_lshl_b32 s52, s8, 9
	s_add_u32 s58, s100, s52
	s_addc_u32 s59, s101, 0
	global_load_dwordx2 v[42:43], v63, s[58:59]
	s_lshl_b32 s52, s9, 9
	s_add_u32 s58, s100, s52
	s_addc_u32 s59, s101, 0
	global_load_dwordx2 v[44:45], v63, s[58:59]
	s_lshl_b32 s52, s11, 9
	s_add_u32 s58, s100, s52
	s_addc_u32 s59, s101, 0
	global_load_dwordx2 v[46:47], v63, s[58:59]
	s_lshl_b32 s52, s13, 9
	s_add_u32 s58, s100, s52
	s_addc_u32 s59, s101, 0
	global_load_dwordx2 v[48:49], v63, s[58:59]
	s_lshl_b32 s52, s16, 9
	s_add_u32 s58, s100, s52
	s_addc_u32 s59, s101, 0
	global_load_dwordx2 v[50:51], v63, s[58:59]
	v_mov_b32_e32 v52, v56
	v_mov_b32_e32 v53, v57
	v_mov_b32_e32 v54, v58
	v_mov_b32_e32 v55, v59
	s_lshr_b32 s15, s14, 4
.Lex_grp:
	s_add_i32 s17, s4, 1
	s_min_u32 s17, s17, 63
	v_readlane_b32 s14, v60, s17
	s_and_b32 s14, s14, 63
	v_lshl_add_u32 v0, s14, 7, v61
	ds_read_b128 v[56:59], v0
	s_waitcnt lgkmcnt(0)
	s_cmp_lg_u32 s15, 0
	s_cbranch_scc1 .Lex_d1
	s_waitcnt vmcnt(14)
	v_cvt_pk_f32_fp8_e32 v[156:157], v4
	v_cvt_pk_f32_fp8_sdwa v[158:159], v4 src0_sel:WORD_1
	v_cvt_pk_f32_fp8_e32 v[160:161], v5
	v_cvt_pk_f32_fp8_sdwa v[162:163], v5 src0_sel:WORD_1
	v_cvt_pk_f32_fp8_e32 v[164:165], v8
	v_cvt_pk_f32_fp8_sdwa v[166:167], v8 src0_sel:WORD_1
	v_cvt_pk_f32_fp8_e32 v[168:169], v9
	v_cvt_pk_f32_fp8_sdwa v[170:171], v9 src0_sel:WORD_1
	v_pk_fma_f32 v[182:183], v[156:157], v[96:97], 0 op_sel_hi:[1,1,0]
	v_pk_fma_f32 v[184:185], v[164:165], v[96:97], 0 op_sel_hi:[1,1,0]
	v_pk_fma_f32 v[182:183], v[158:159], v[98:99], v[182:183]
	v_pk_fma_f32 v[184:185], v[166:167], v[98:99], v[184:185]
	v_pk_fma_f32 v[182:183], v[160:161], v[100:101], v[182:183]
	v_pk_fma_f32 v[184:185], v[168:169], v[100:101], v[184:185]
	v_pk_fma_f32 v[182:183], v[162:163], v[102:103], v[182:183]
	v_pk_fma_f32 v[184:185], v[170:171], v[102:103], v[184:185]
	v_cvt_pk_f32_fp8_e32 v[156:157], v6
	v_cvt_pk_f32_fp8_sdwa v[158:159], v6 src0_sel:WORD_1
	v_cvt_pk_f32_fp8_e32 v[160:161], v7
	v_cvt_pk_f32_fp8_sdwa v[162:163], v7 src0_sel:WORD_1
	v_cvt_pk_f32_fp8_e32 v[164:165], v10
	v_cvt_pk_f32_fp8_sdwa v[166:167], v10 src0_sel:WORD_1
	v_cvt_pk_f32_fp8_e32 v[168:169], v11
	v_cvt_pk_f32_fp8_sdwa v[170:171], v11 src0_sel:WORD_1
	v_pk_fma_f32 v[182:183], v[156:157], v[92:93], v[182:183]
	v_pk_fma_f32 v[184:185], v[164:165], v[92:93], v[184:185]
	v_pk_fma_f32 v[182:183], v[158:159], v[94:95], v[182:183]
	v_pk_fma_f32 v[184:185], v[166:167], v[94:95], v[184:185]
	v_pk_fma_f32 v[182:183], v[160:161], v[104:105], v[182:183]
	v_pk_fma_f32 v[184:185], v[168:169], v[104:105], v[184:185]
	v_pk_fma_f32 v[182:183], v[162:163], v[106:107], v[182:183]
	v_pk_fma_f32 v[184:185], v[170:171], v[106:107], v[184:185]
	v_add_f32_e32 v240, v182, v183
	v_add_f32_e32 v241, v184, v185
	v_readlane_b32 s5, v56, 0
	s_lshl_b32 s52, s5, 10
	s_add_u32 s56, s98, s52
	s_addc_u32 s57, s99, 0
	global_load_dwordx4 v[4:7], v62, s[56:57]
	v_readlane_b32 s6, v56, 32
	s_lshl_b32 s52, s6, 10
	s_add_u32 s56, s98, s52
	s_addc_u32 s57, s99, 0
	global_load_dwordx4 v[8:11], v62, s[56:57]
	s_waitcnt vmcnt(14)
	v_cvt_pk_f32_fp8_e32 v[156:157], v12
	v_cvt_pk_f32_fp8_sdwa v[158:159], v12 src0_sel:WORD_1
	v_cvt_pk_f32_fp8_e32 v[160:161], v13
	v_cvt_pk_f32_fp8_sdwa v[162:163], v13 src0_sel:WORD_1
	v_cvt_pk_f32_fp8_e32 v[164:165], v16
	v_cvt_pk_f32_fp8_sdwa v[166:167], v16 src0_sel:WORD_1
	v_cvt_pk_f32_fp8_e32 v[168:169], v17
	v_cvt_pk_f32_fp8_sdwa v[170:171], v17 src0_sel:WORD_1
	v_pk_fma_f32 v[182:183], v[156:157], v[96:97], 0 op_sel_hi:[1,1,0]
	v_pk_fma_f32 v[184:185], v[164:165], v[96:97], 0 op_sel_hi:[1,1,0]
	v_pk_fma_f32 v[182:183], v[158:159], v[98:99], v[182:183]
	v_pk_fma_f32 v[184:185], v[166:167], v[98:99], v[184:185]
	v_pk_fma_f32 v[182:183], v[160:161], v[100:101], v[182:183]
	v_pk_fma_f32 v[184:185], v[168:169], v[100:101], v[184:185]
	v_pk_fma_f32 v[182:183], v[162:163], v[102:103], v[182:183]
	v_pk_fma_f32 v[184:185], v[170:171], v[102:103], v[184:185]
	v_cvt_pk_f32_fp8_e32 v[156:157], v14
	v_cvt_pk_f32_fp8_sdwa v[158:159], v14 src0_sel:WORD_1
	v_cvt_pk_f32_fp8_e32 v[160:161], v15
	v_cvt_pk_f32_fp8_sdwa v[162:163], v15 src0_sel:WORD_1
	v_cvt_pk_f32_fp8_e32 v[164:165], v18
	v_cvt_pk_f32_fp8_sdwa v[166:167], v18 src0_sel:WORD_1
	v_cvt_pk_f32_fp8_e32 v[168:169], v19
	v_cvt_pk_f32_fp8_sdwa v[170:171], v19 src0_sel:WORD_1
	v_pk_fma_f32 v[182:183], v[156:157], v[92:93], v[182:183]
	v_pk_fma_f32 v[184:185], v[164:165], v[92:93], v[184:185]
	v_pk_fma_f32 v[182:183], v[158:159], v[94:95], v[182:183]
	v_pk_fma_f32 v[184:185], v[166:167], v[94:95], v[184:185]
	v_pk_fma_f32 v[182:183], v[160:161], v[104:105], v[182:183]
	v_pk_fma_f32 v[184:185], v[168:169], v[104:105], v[184:185]
	v_pk_fma_f32 v[182:183], v[162:163], v[106:107], v[182:183]
	v_pk_fma_f32 v[184:185], v[170:171], v[106:107], v[184:185]
	v_add_f32_e32 v242, v182, v183
	v_add_f32_e32 v243, v184, v185
	v_readlane_b32 s7, v56, 16
	s_lshl_b32 s52, s7, 10
	s_add_u32 s56, s98, s52
	s_addc_u32 s57, s99, 0
	global_load_dwordx4 v[12:15], v62, s[56:57]
	v_readlane_b32 s8, v56, 48
	s_lshl_b32 s52, s8, 10
	s_add_u32 s56, s98, s52
	s_addc_u32 s57, s99, 0
	global_load_dwordx4 v[16:19], v62, s[56:57]
	s_waitcnt vmcnt(14)
	v_cvt_pk_f32_fp8_e32 v[156:157], v20
	v_cvt_pk_f32_fp8_sdwa v[158:159], v20 src0_sel:WORD_1
	v_cvt_pk_f32_fp8_e32 v[160:161], v21
	v_cvt_pk_f32_fp8_sdwa v[162:163], v21 src0_sel:WORD_1
	v_cvt_pk_f32_fp8_e32 v[164:165], v24
	v_cvt_pk_f32_fp8_sdwa v[166:167], v24 src0_sel:WORD_1
	v_cvt_pk_f32_fp8_e32 v[168:169], v25
	v_cvt_pk_f32_fp8_sdwa v[170:171], v25 src0_sel:WORD_1
	v_pk_fma_f32 v[182:183], v[156:157], v[96:97], 0 op_sel_hi:[1,1,0]
	v_pk_fma_f32 v[184:185], v[164:165], v[96:97], 0 op_sel_hi:[1,1,0]
	v_pk_fma_f32 v[182:183], v[158:159], v[98:99], v[182:183]
	v_pk_fma_f32 v[184:185], v[166:167], v[98:99], v[184:185]
	v_pk_fma_f32 v[182:183], v[160:161], v[100:101], v[182:183]
	v_pk_fma_f32 v[184:185], v[168:169], v[100:101], v[184:185]
	v_pk_fma_f32 v[182:183], v[162:163], v[102:103], v[182:183]
	v_pk_fma_f32 v[184:185], v[170:171], v[102:103], v[184:185]
	v_cvt_pk_f32_fp8_e32 v[156:157], v22
	v_cvt_pk_f32_fp8_sdwa v[158:159], v22 src0_sel:WORD_1
	v_cvt_pk_f32_fp8_e32 v[160:161], v23
	v_cvt_pk_f32_fp8_sdwa v[162:163], v23 src0_sel:WORD_1
	v_cvt_pk_f32_fp8_e32 v[164:165], v26
	v_cvt_pk_f32_fp8_sdwa v[166:167], v26 src0_sel:WORD_1
	v_cvt_pk_f32_fp8_e32 v[168:169], v27
	v_cvt_pk_f32_fp8_sdwa v[170:171], v27 src0_sel:WORD_1
	v_pk_fma_f32 v[182:183], v[156:157], v[92:93], v[182:183]
	v_pk_fma_f32 v[184:185], v[164:165], v[92:93], v[184:185]
	v_pk_fma_f32 v[182:183], v[158:159], v[94:95], v[182:183]
	v_pk_fma_f32 v[184:185], v[166:167], v[94:95], v[184:185]
	v_pk_fma_f32 v[182:183], v[160:161], v[104:105], v[182:183]
	v_pk_fma_f32 v[184:185], v[168:169], v[104:105], v[184:185]
	v_pk_fma_f32 v[182:183], v[162:163], v[106:107], v[182:183]
	v_pk_fma_f32 v[184:185], v[170:171], v[106:107], v[184:185]
	v_add_f32_e32 v244, v182, v183
	v_add_f32_e32 v245, v184, v185
	v_readlane_b32 s9, v56, 8
	s_lshl_b32 s52, s9, 10
	s_add_u32 s56, s98, s52
	s_addc_u32 s57, s99, 0
	global_load_dwordx4 v[20:23], v62, s[56:57]
	v_readlane_b32 s11, v56, 40
	s_lshl_b32 s52, s11, 10
	s_add_u32 s56, s98, s52
	s_addc_u32 s57, s99, 0
	global_load_dwordx4 v[24:27], v62, s[56:57]
	s_waitcnt vmcnt(14)
	v_cvt_pk_f32_fp8_e32 v[156:157], v28
	v_cvt_pk_f32_fp8_sdwa v[158:159], v28 src0_sel:WORD_1
	v_cvt_pk_f32_fp8_e32 v[160:161], v29
	v_cvt_pk_f32_fp8_sdwa v[162:163], v29 src0_sel:WORD_1
	v_cvt_pk_f32_fp8_e32 v[164:165], v32
	v_cvt_pk_f32_fp8_sdwa v[166:167], v32 src0_sel:WORD_1
	v_cvt_pk_f32_fp8_e32 v[168:169], v33
	v_cvt_pk_f32_fp8_sdwa v[170:171], v33 src0_sel:WORD_1
	v_pk_fma_f32 v[182:183], v[156:157], v[96:97], 0 op_sel_hi:[1,1,0]
	v_pk_fma_f32 v[184:185], v[164:165], v[96:97], 0 op_sel_hi:[1,1,0]
	v_pk_fma_f32 v[182:183], v[158:159], v[98:99], v[182:183]
	v_pk_fma_f32 v[184:185], v[166:167], v[98:99], v[184:185]
	v_pk_fma_f32 v[182:183], v[160:161], v[100:101], v[182:183]
	v_pk_fma_f32 v[184:185], v[168:169], v[100:101], v[184:185]
	v_pk_fma_f32 v[182:183], v[162:163], v[102:103], v[182:183]
	v_pk_fma_f32 v[184:185], v[170:171], v[102:103], v[184:185]
	v_cvt_pk_f32_fp8_e32 v[156:157], v30
	v_cvt_pk_f32_fp8_sdwa v[158:159], v30 src0_sel:WORD_1
	v_cvt_pk_f32_fp8_e32 v[160:161], v31
	v_cvt_pk_f32_fp8_sdwa v[162:163], v31 src0_sel:WORD_1
	v_cvt_pk_f32_fp8_e32 v[164:165], v34
	v_cvt_pk_f32_fp8_sdwa v[166:167], v34 src0_sel:WORD_1
	v_cvt_pk_f32_fp8_e32 v[168:169], v35
	v_cvt_pk_f32_fp8_sdwa v[170:171], v35 src0_sel:WORD_1
	v_pk_fma_f32 v[182:183], v[156:157], v[92:93], v[182:183]
	v_pk_fma_f32 v[184:185], v[164:165], v[92:93], v[184:185]
	v_pk_fma_f32 v[182:183], v[158:159], v[94:95], v[182:183]
	v_pk_fma_f32 v[184:185], v[166:167], v[94:95], v[184:185]
	v_pk_fma_f32 v[182:183], v[160:161], v[104:105], v[182:183]
	v_pk_fma_f32 v[184:185], v[168:169], v[104:105], v[184:185]
	v_pk_fma_f32 v[182:183], v[162:163], v[106:107], v[182:183]
	v_pk_fma_f32 v[184:185], v[170:171], v[106:107], v[184:185]
	v_add_f32_e32 v246, v182, v183
	v_add_f32_e32 v247, v184, v185
	v_readlane_b32 s13, v56, 24
	s_lshl_b32 s52, s13, 10
	s_add_u32 s56, s98, s52
	s_addc_u32 s57, s99, 0
	global_load_dwordx4 v[28:31], v62, s[56:57]
	v_readlane_b32 s16, v56, 56
	s_lshl_b32 s52, s16, 10
	s_add_u32 s56, s98, s52
	s_addc_u32 s57, s99, 0
	global_load_dwordx4 v[32:35], v62, s[56:57]
	s_branch .Lex_d4
.Lex_d1:
	s_cmp_lg_u32 s15, 1
	s_cbranch_scc1 .Lex_d2
	s_waitcnt vmcnt(14)
	v_cvt_pk_f32_fp8_e32 v[156:157], v4
	v_cvt_pk_f32_fp8_sdwa v[158:159], v4 src0_sel:WORD_1
	v_cvt_pk_f32_fp8_e32 v[160:161], v5
	v_cvt_pk_f32_fp8_sdwa v[162:163], v5 src0_sel:WORD_1
	v_cvt_pk_f32_fp8_e32 v[164:165], v8
	v_cvt_pk_f32_fp8_sdwa v[166:167], v8 src0_sel:WORD_1
	v_cvt_pk_f32_fp8_e32 v[168:169], v9
	v_cvt_pk_f32_fp8_sdwa v[170:171], v9 src0_sel:WORD_1
	v_pk_fma_f32 v[182:183], v[156:157], v[134:135], 0 op_sel_hi:[1,1,0]
	v_pk_fma_f32 v[184:185], v[164:165], v[134:135], 0 op_sel_hi:[1,1,0]
	v_pk_fma_f32 v[182:183], v[158:159], v[142:143], v[182:183]
	v_pk_fma_f32 v[184:185], v[166:167], v[142:143], v[184:185]
	v_pk_fma_f32 v[182:183], v[160:161], v[144:145], v[182:183]
	v_pk_fma_f32 v[184:185], v[168:169], v[144:145], v[184:185]
	v_pk_fma_f32 v[182:183], v[162:163], v[146:147], v[182:183]
	v_pk_fma_f32 v[184:185], v[170:171], v[146:147], v[184:185]
	v_cvt_pk_f32_fp8_e32 v[156:157], v6
	v_cvt_pk_f32_fp8_sdwa v[158:159], v6 src0_sel:WORD_1
	v_cvt_pk_f32_fp8_e32 v[160:161], v7
	v_cvt_pk_f32_fp8_sdwa v[162:163], v7 src0_sel:WORD_1
	v_cvt_pk_f32_fp8_e32 v[164:165], v10
	v_cvt_pk_f32_fp8_sdwa v[166:167], v10 src0_sel:WORD_1
	v_cvt_pk_f32_fp8_e32 v[168:169], v11
	v_cvt_pk_f32_fp8_sdwa v[170:171], v11 src0_sel:WORD_1
	v_pk_fma_f32 v[182:183], v[156:157], v[148:149], v[182:183]
	v_pk_fma_f32 v[184:185], v[164:165], v[148:149], v[184:185]
	v_pk_fma_f32 v[182:183], v[158:159], v[150:151], v[182:183]
	v_pk_fma_f32 v[184:185], v[166:167], v[150:151], v[184:185]
	v_pk_fma_f32 v[182:183], v[160:161], v[152:153], v[182:183]
	v_pk_fma_f32 v[184:185], v[168:169], v[152:153], v[184:185]
	v_pk_fma_f32 v[182:183], v[162:163], v[154:155], v[182:183]
	v_pk_fma_f32 v[184:185], v[170:171], v[154:155], v[184:185]
	v_add_f32_e32 v240, v182, v183
	v_add_f32_e32 v241, v184, v185
	v_readlane_b32 s5, v56, 0
	s_lshl_b32 s52, s5, 10
	s_add_u32 s56, s98, s52
	s_addc_u32 s57, s99, 0
	global_load_dwordx4 v[4:7], v62, s[56:57]
	v_readlane_b32 s6, v56, 32
	s_lshl_b32 s52, s6, 10
	s_add_u32 s56, s98, s52
	s_addc_u32 s57, s99, 0
	global_load_dwordx4 v[8:11], v62, s[56:57]
	s_waitcnt vmcnt(14)
	v_cvt_pk_f32_fp8_e32 v[156:157], v12
	v_cvt_pk_f32_fp8_sdwa v[158:159], v12 src0_sel:WORD_1
	v_cvt_pk_f32_fp8_e32 v[160:161], v13
	v_cvt_pk_f32_fp8_sdwa v[162:163], v13 src0_sel:WORD_1
	v_cvt_pk_f32_fp8_e32 v[164:165], v16
	v_cvt_pk_f32_fp8_sdwa v[166:167], v16 src0_sel:WORD_1
	v_cvt_pk_f32_fp8_e32 v[168:169], v17
	v_cvt_pk_f32_fp8_sdwa v[170:171], v17 src0_sel:WORD_1
	v_pk_fma_f32 v[182:183], v[156:157], v[134:135], 0 op_sel_hi:[1,1,0]
	v_pk_fma_f32 v[184:185], v[164:165], v[134:135], 0 op_sel_hi:[1,1,0]
	v_pk_fma_f32 v[182:183], v[158:159], v[142:143], v[182:183]
	v_pk_fma_f32 v[184:185], v[166:167], v[142:143], v[184:185]
	v_pk_fma_f32 v[182:183], v[160:161], v[144:145], v[182:183]
	v_pk_fma_f32 v[184:185], v[168:169], v[144:145], v[184:185]
	v_pk_fma_f32 v[182:183], v[162:163], v[146:147], v[182:183]
	v_pk_fma_f32 v[184:185], v[170:171], v[146:147], v[184:185]
	v_cvt_pk_f32_fp8_e32 v[156:157], v14
	v_cvt_pk_f32_fp8_sdwa v[158:159], v14 src0_sel:WORD_1
	v_cvt_pk_f32_fp8_e32 v[160:161], v15
	v_cvt_pk_f32_fp8_sdwa v[162:163], v15 src0_sel:WORD_1
	v_cvt_pk_f32_fp8_e32 v[164:165], v18
	v_cvt_pk_f32_fp8_sdwa v[166:167], v18 src0_sel:WORD_1
	v_cvt_pk_f32_fp8_e32 v[168:169], v19
	v_cvt_pk_f32_fp8_sdwa v[170:171], v19 src0_sel:WORD_1
	v_pk_fma_f32 v[182:183], v[156:157], v[148:149], v[182:183]
	v_pk_fma_f32 v[184:185], v[164:165], v[148:149], v[184:185]
	v_pk_fma_f32 v[182:183], v[158:159], v[150:151], v[182:183]
	v_pk_fma_f32 v[184:185], v[166:167], v[150:151], v[184:185]
	v_pk_fma_f32 v[182:183], v[160:161], v[152:153], v[182:183]
	v_pk_fma_f32 v[184:185], v[168:169], v[152:153], v[184:185]
	v_pk_fma_f32 v[182:183], v[162:163], v[154:155], v[182:183]
	v_pk_fma_f32 v[184:185], v[170:171], v[154:155], v[184:185]
	v_add_f32_e32 v242, v182, v183
	v_add_f32_e32 v243, v184, v185
	v_readlane_b32 s7, v56, 16
	s_lshl_b32 s52, s7, 10
	s_add_u32 s56, s98, s52
	s_addc_u32 s57, s99, 0
	global_load_dwordx4 v[12:15], v62, s[56:57]
	v_readlane_b32 s8, v56, 48
	s_lshl_b32 s52, s8, 10
	s_add_u32 s56, s98, s52
	s_addc_u32 s57, s99, 0
	global_load_dwordx4 v[16:19], v62, s[56:57]
	s_waitcnt vmcnt(14)
	v_cvt_pk_f32_fp8_e32 v[156:157], v20
	v_cvt_pk_f32_fp8_sdwa v[158:159], v20 src0_sel:WORD_1
	v_cvt_pk_f32_fp8_e32 v[160:161], v21
	v_cvt_pk_f32_fp8_sdwa v[162:163], v21 src0_sel:WORD_1
	v_cvt_pk_f32_fp8_e32 v[164:165], v24
	v_cvt_pk_f32_fp8_sdwa v[166:167], v24 src0_sel:WORD_1
	v_cvt_pk_f32_fp8_e32 v[168:169], v25
	v_cvt_pk_f32_fp8_sdwa v[170:171], v25 src0_sel:WORD_1
	v_pk_fma_f32 v[182:183], v[156:157], v[134:135], 0 op_sel_hi:[1,1,0]
	v_pk_fma_f32 v[184:185], v[164:165], v[134:135], 0 op_sel_hi:[1,1,0]
	v_pk_fma_f32 v[182:183], v[158:159], v[142:143], v[182:183]
	v_pk_fma_f32 v[184:185], v[166:167], v[142:143], v[184:185]
	v_pk_fma_f32 v[182:183], v[160:161], v[144:145], v[182:183]
	v_pk_fma_f32 v[184:185], v[168:169], v[144:145], v[184:185]
	v_pk_fma_f32 v[182:183], v[162:163], v[146:147], v[182:183]
	v_pk_fma_f32 v[184:185], v[170:171], v[146:147], v[184:185]
	v_cvt_pk_f32_fp8_e32 v[156:157], v22
	v_cvt_pk_f32_fp8_sdwa v[158:159], v22 src0_sel:WORD_1
	v_cvt_pk_f32_fp8_e32 v[160:161], v23
	v_cvt_pk_f32_fp8_sdwa v[162:163], v23 src0_sel:WORD_1
	v_cvt_pk_f32_fp8_e32 v[164:165], v26
	v_cvt_pk_f32_fp8_sdwa v[166:167], v26 src0_sel:WORD_1
	v_cvt_pk_f32_fp8_e32 v[168:169], v27
	v_cvt_pk_f32_fp8_sdwa v[170:171], v27 src0_sel:WORD_1
	v_pk_fma_f32 v[182:183], v[156:157], v[148:149], v[182:183]
	v_pk_fma_f32 v[184:185], v[164:165], v[148:149], v[184:185]
	v_pk_fma_f32 v[182:183], v[158:159], v[150:151], v[182:183]
	v_pk_fma_f32 v[184:185], v[166:167], v[150:151], v[184:185]
	v_pk_fma_f32 v[182:183], v[160:161], v[152:153], v[182:183]
	v_pk_fma_f32 v[184:185], v[168:169], v[152:153], v[184:185]
	v_pk_fma_f32 v[182:183], v[162:163], v[154:155], v[182:183]
	v_pk_fma_f32 v[184:185], v[170:171], v[154:155], v[184:185]
	v_add_f32_e32 v244, v182, v183
	v_add_f32_e32 v245, v184, v185
	v_readlane_b32 s9, v56, 8
	s_lshl_b32 s52, s9, 10
	s_add_u32 s56, s98, s52
	s_addc_u32 s57, s99, 0
	global_load_dwordx4 v[20:23], v62, s[56:57]
	v_readlane_b32 s11, v56, 40
	s_lshl_b32 s52, s11, 10
	s_add_u32 s56, s98, s52
	s_addc_u32 s57, s99, 0
	global_load_dwordx4 v[24:27], v62, s[56:57]
	s_waitcnt vmcnt(14)
	v_cvt_pk_f32_fp8_e32 v[156:157], v28
	v_cvt_pk_f32_fp8_sdwa v[158:159], v28 src0_sel:WORD_1
	v_cvt_pk_f32_fp8_e32 v[160:161], v29
	v_cvt_pk_f32_fp8_sdwa v[162:163], v29 src0_sel:WORD_1
	v_cvt_pk_f32_fp8_e32 v[164:165], v32
	v_cvt_pk_f32_fp8_sdwa v[166:167], v32 src0_sel:WORD_1
	v_cvt_pk_f32_fp8_e32 v[168:169], v33
	v_cvt_pk_f32_fp8_sdwa v[170:171], v33 src0_sel:WORD_1
	v_pk_fma_f32 v[182:183], v[156:157], v[134:135], 0 op_sel_hi:[1,1,0]
	v_pk_fma_f32 v[184:185], v[164:165], v[134:135], 0 op_sel_hi:[1,1,0]
	v_pk_fma_f32 v[182:183], v[158:159], v[142:143], v[182:183]
	v_pk_fma_f32 v[184:185], v[166:167], v[142:143], v[184:185]
	v_pk_fma_f32 v[182:183], v[160:161], v[144:145], v[182:183]
	v_pk_fma_f32 v[184:185], v[168:169], v[144:145], v[184:185]
	v_pk_fma_f32 v[182:183], v[162:163], v[146:147], v[182:183]
	v_pk_fma_f32 v[184:185], v[170:171], v[146:147], v[184:185]
	v_cvt_pk_f32_fp8_e32 v[156:157], v30
	v_cvt_pk_f32_fp8_sdwa v[158:159], v30 src0_sel:WORD_1
	v_cvt_pk_f32_fp8_e32 v[160:161], v31
	v_cvt_pk_f32_fp8_sdwa v[162:163], v31 src0_sel:WORD_1
	v_cvt_pk_f32_fp8_e32 v[164:165], v34
	v_cvt_pk_f32_fp8_sdwa v[166:167], v34 src0_sel:WORD_1
	v_cvt_pk_f32_fp8_e32 v[168:169], v35
	v_cvt_pk_f32_fp8_sdwa v[170:171], v35 src0_sel:WORD_1
	v_pk_fma_f32 v[182:183], v[156:157], v[148:149], v[182:183]
	v_pk_fma_f32 v[184:185], v[164:165], v[148:149], v[184:185]
	v_pk_fma_f32 v[182:183], v[158:159], v[150:151], v[182:183]
	v_pk_fma_f32 v[184:185], v[166:167], v[150:151], v[184:185]
	v_pk_fma_f32 v[182:183], v[160:161], v[152:153], v[182:183]
	v_pk_fma_f32 v[184:185], v[168:169], v[152:153], v[184:185]
	v_pk_fma_f32 v[182:183], v[162:163], v[154:155], v[182:183]
	v_pk_fma_f32 v[184:185], v[170:171], v[154:155], v[184:185]
	v_add_f32_e32 v246, v182, v183
	v_add_f32_e32 v247, v184, v185
	v_readlane_b32 s13, v56, 24
	s_lshl_b32 s52, s13, 10
	s_add_u32 s56, s98, s52
	s_addc_u32 s57, s99, 0
	global_load_dwordx4 v[28:31], v62, s[56:57]
	v_readlane_b32 s16, v56, 56
	s_lshl_b32 s52, s16, 10
	s_add_u32 s56, s98, s52
	s_addc_u32 s57, s99, 0
	global_load_dwordx4 v[32:35], v62, s[56:57]
	s_branch .Lex_d4
.Lex_d2:
	s_cmp_lg_u32 s15, 2
	s_cbranch_scc1 .Lex_d3
	s_waitcnt vmcnt(14)
	v_cvt_pk_f32_fp8_e32 v[156:157], v4
	v_cvt_pk_f32_fp8_sdwa v[158:159], v4 src0_sel:WORD_1
	v_cvt_pk_f32_fp8_e32 v[160:161], v5
	v_cvt_pk_f32_fp8_sdwa v[162:163], v5 src0_sel:WORD_1
	v_cvt_pk_f32_fp8_e32 v[164:165], v8
	v_cvt_pk_f32_fp8_sdwa v[166:167], v8 src0_sel:WORD_1
	v_cvt_pk_f32_fp8_e32 v[168:169], v9
	v_cvt_pk_f32_fp8_sdwa v[170:171], v9 src0_sel:WORD_1
	v_pk_fma_f32 v[182:183], v[156:157], v[216:217], 0 op_sel_hi:[1,1,0]
	v_pk_fma_f32 v[184:185], v[164:165], v[216:217], 0 op_sel_hi:[1,1,0]
	v_pk_fma_f32 v[182:183], v[158:159], v[218:219], v[182:183]
	v_pk_fma_f32 v[184:185], v[166:167], v[218:219], v[184:185]
	v_pk_fma_f32 v[182:183], v[160:161], v[220:221], v[182:183]
	v_pk_fma_f32 v[184:185], v[168:169], v[220:221], v[184:185]
	v_pk_fma_f32 v[182:183], v[162:163], v[222:223], v[182:183]
	v_pk_fma_f32 v[184:185], v[170:171], v[222:223], v[184:185]
	v_cvt_pk_f32_fp8_e32 v[156:157], v6
	v_cvt_pk_f32_fp8_sdwa v[158:159], v6 src0_sel:WORD_1
	v_cvt_pk_f32_fp8_e32 v[160:161], v7
	v_cvt_pk_f32_fp8_sdwa v[162:163], v7 src0_sel:WORD_1
	v_cvt_pk_f32_fp8_e32 v[164:165], v10
	v_cvt_pk_f32_fp8_sdwa v[166:167], v10 src0_sel:WORD_1
	v_cvt_pk_f32_fp8_e32 v[168:169], v11
	v_cvt_pk_f32_fp8_sdwa v[170:171], v11 src0_sel:WORD_1
	v_pk_fma_f32 v[182:183], v[156:157], v[224:225], v[182:183]
	v_pk_fma_f32 v[184:185], v[164:165], v[224:225], v[184:185]
	v_pk_fma_f32 v[182:183], v[158:159], v[226:227], v[182:183]
	v_pk_fma_f32 v[184:185], v[166:167], v[226:227], v[184:185]
	v_pk_fma_f32 v[182:183], v[160:161], v[228:229], v[182:183]
	v_pk_fma_f32 v[184:185], v[168:169], v[228:229], v[184:185]
	v_pk_fma_f32 v[182:183], v[162:163], v[230:231], v[182:183]
	v_pk_fma_f32 v[184:185], v[170:171], v[230:231], v[184:185]
	v_add_f32_e32 v240, v182, v183
	v_add_f32_e32 v241, v184, v185
	v_readlane_b32 s5, v56, 0
	s_lshl_b32 s52, s5, 10
	s_add_u32 s56, s98, s52
	s_addc_u32 s57, s99, 0
	global_load_dwordx4 v[4:7], v62, s[56:57]
	v_readlane_b32 s6, v56, 32
	s_lshl_b32 s52, s6, 10
	s_add_u32 s56, s98, s52
	s_addc_u32 s57, s99, 0
	global_load_dwordx4 v[8:11], v62, s[56:57]
	s_waitcnt vmcnt(14)
	v_cvt_pk_f32_fp8_e32 v[156:157], v12
	v_cvt_pk_f32_fp8_sdwa v[158:159], v12 src0_sel:WORD_1
	v_cvt_pk_f32_fp8_e32 v[160:161], v13
	v_cvt_pk_f32_fp8_sdwa v[162:163], v13 src0_sel:WORD_1
	v_cvt_pk_f32_fp8_e32 v[164:165], v16
	v_cvt_pk_f32_fp8_sdwa v[166:167], v16 src0_sel:WORD_1
	v_cvt_pk_f32_fp8_e32 v[168:169], v17
	v_cvt_pk_f32_fp8_sdwa v[170:171], v17 src0_sel:WORD_1
	v_pk_fma_f32 v[182:183], v[156:157], v[216:217], 0 op_sel_hi:[1,1,0]
	v_pk_fma_f32 v[184:185], v[164:165], v[216:217], 0 op_sel_hi:[1,1,0]
	v_pk_fma_f32 v[182:183], v[158:159], v[218:219], v[182:183]
	v_pk_fma_f32 v[184:185], v[166:167], v[218:219], v[184:185]
	v_pk_fma_f32 v[182:183], v[160:161], v[220:221], v[182:183]
	v_pk_fma_f32 v[184:185], v[168:169], v[220:221], v[184:185]
	v_pk_fma_f32 v[182:183], v[162:163], v[222:223], v[182:183]
	v_pk_fma_f32 v[184:185], v[170:171], v[222:223], v[184:185]
	v_cvt_pk_f32_fp8_e32 v[156:157], v14
	v_cvt_pk_f32_fp8_sdwa v[158:159], v14 src0_sel:WORD_1
	v_cvt_pk_f32_fp8_e32 v[160:161], v15
	v_cvt_pk_f32_fp8_sdwa v[162:163], v15 src0_sel:WORD_1
	v_cvt_pk_f32_fp8_e32 v[164:165], v18
	v_cvt_pk_f32_fp8_sdwa v[166:167], v18 src0_sel:WORD_1
	v_cvt_pk_f32_fp8_e32 v[168:169], v19
	v_cvt_pk_f32_fp8_sdwa v[170:171], v19 src0_sel:WORD_1
	v_pk_fma_f32 v[182:183], v[156:157], v[224:225], v[182:183]
	v_pk_fma_f32 v[184:185], v[164:165], v[224:225], v[184:185]
	v_pk_fma_f32 v[182:183], v[158:159], v[226:227], v[182:183]
	v_pk_fma_f32 v[184:185], v[166:167], v[226:227], v[184:185]
	v_pk_fma_f32 v[182:183], v[160:161], v[228:229], v[182:183]
	v_pk_fma_f32 v[184:185], v[168:169], v[228:229], v[184:185]
	v_pk_fma_f32 v[182:183], v[162:163], v[230:231], v[182:183]
	v_pk_fma_f32 v[184:185], v[170:171], v[230:231], v[184:185]
	v_add_f32_e32 v242, v182, v183
	v_add_f32_e32 v243, v184, v185
	v_readlane_b32 s7, v56, 16
	s_lshl_b32 s52, s7, 10
	s_add_u32 s56, s98, s52
	s_addc_u32 s57, s99, 0
	global_load_dwordx4 v[12:15], v62, s[56:57]
	v_readlane_b32 s8, v56, 48
	s_lshl_b32 s52, s8, 10
	s_add_u32 s56, s98, s52
	s_addc_u32 s57, s99, 0
	global_load_dwordx4 v[16:19], v62, s[56:57]
	s_waitcnt vmcnt(14)
	v_cvt_pk_f32_fp8_e32 v[156:157], v20
	v_cvt_pk_f32_fp8_sdwa v[158:159], v20 src0_sel:WORD_1
	v_cvt_pk_f32_fp8_e32 v[160:161], v21
	v_cvt_pk_f32_fp8_sdwa v[162:163], v21 src0_sel:WORD_1
	v_cvt_pk_f32_fp8_e32 v[164:165], v24
	v_cvt_pk_f32_fp8_sdwa v[166:167], v24 src0_sel:WORD_1
	v_cvt_pk_f32_fp8_e32 v[168:169], v25
	v_cvt_pk_f32_fp8_sdwa v[170:171], v25 src0_sel:WORD_1
	v_pk_fma_f32 v[182:183], v[156:157], v[216:217], 0 op_sel_hi:[1,1,0]
	v_pk_fma_f32 v[184:185], v[164:165], v[216:217], 0 op_sel_hi:[1,1,0]
	v_pk_fma_f32 v[182:183], v[158:159], v[218:219], v[182:183]
	v_pk_fma_f32 v[184:185], v[166:167], v[218:219], v[184:185]
	v_pk_fma_f32 v[182:183], v[160:161], v[220:221], v[182:183]
	v_pk_fma_f32 v[184:185], v[168:169], v[220:221], v[184:185]
	v_pk_fma_f32 v[182:183], v[162:163], v[222:223], v[182:183]
	v_pk_fma_f32 v[184:185], v[170:171], v[222:223], v[184:185]
	v_cvt_pk_f32_fp8_e32 v[156:157], v22
	v_cvt_pk_f32_fp8_sdwa v[158:159], v22 src0_sel:WORD_1
	v_cvt_pk_f32_fp8_e32 v[160:161], v23
	v_cvt_pk_f32_fp8_sdwa v[162:163], v23 src0_sel:WORD_1
	v_cvt_pk_f32_fp8_e32 v[164:165], v26
	v_cvt_pk_f32_fp8_sdwa v[166:167], v26 src0_sel:WORD_1
	v_cvt_pk_f32_fp8_e32 v[168:169], v27
	v_cvt_pk_f32_fp8_sdwa v[170:171], v27 src0_sel:WORD_1
	v_pk_fma_f32 v[182:183], v[156:157], v[224:225], v[182:183]
	v_pk_fma_f32 v[184:185], v[164:165], v[224:225], v[184:185]
	v_pk_fma_f32 v[182:183], v[158:159], v[226:227], v[182:183]
	v_pk_fma_f32 v[184:185], v[166:167], v[226:227], v[184:185]
	v_pk_fma_f32 v[182:183], v[160:161], v[228:229], v[182:183]
	v_pk_fma_f32 v[184:185], v[168:169], v[228:229], v[184:185]
	v_pk_fma_f32 v[182:183], v[162:163], v[230:231], v[182:183]
	v_pk_fma_f32 v[184:185], v[170:171], v[230:231], v[184:185]
	v_add_f32_e32 v244, v182, v183
	v_add_f32_e32 v245, v184, v185
	v_readlane_b32 s9, v56, 8
	s_lshl_b32 s52, s9, 10
	s_add_u32 s56, s98, s52
	s_addc_u32 s57, s99, 0
	global_load_dwordx4 v[20:23], v62, s[56:57]
	v_readlane_b32 s11, v56, 40
	s_lshl_b32 s52, s11, 10
	s_add_u32 s56, s98, s52
	s_addc_u32 s57, s99, 0
	global_load_dwordx4 v[24:27], v62, s[56:57]
	s_waitcnt vmcnt(14)
	v_cvt_pk_f32_fp8_e32 v[156:157], v28
	v_cvt_pk_f32_fp8_sdwa v[158:159], v28 src0_sel:WORD_1
	v_cvt_pk_f32_fp8_e32 v[160:161], v29
	v_cvt_pk_f32_fp8_sdwa v[162:163], v29 src0_sel:WORD_1
	v_cvt_pk_f32_fp8_e32 v[164:165], v32
	v_cvt_pk_f32_fp8_sdwa v[166:167], v32 src0_sel:WORD_1
	v_cvt_pk_f32_fp8_e32 v[168:169], v33
	v_cvt_pk_f32_fp8_sdwa v[170:171], v33 src0_sel:WORD_1
	v_pk_fma_f32 v[182:183], v[156:157], v[216:217], 0 op_sel_hi:[1,1,0]
	v_pk_fma_f32 v[184:185], v[164:165], v[216:217], 0 op_sel_hi:[1,1,0]
	v_pk_fma_f32 v[182:183], v[158:159], v[218:219], v[182:183]
	v_pk_fma_f32 v[184:185], v[166:167], v[218:219], v[184:185]
	v_pk_fma_f32 v[182:183], v[160:161], v[220:221], v[182:183]
	v_pk_fma_f32 v[184:185], v[168:169], v[220:221], v[184:185]
	v_pk_fma_f32 v[182:183], v[162:163], v[222:223], v[182:183]
	v_pk_fma_f32 v[184:185], v[170:171], v[222:223], v[184:185]
	v_cvt_pk_f32_fp8_e32 v[156:157], v30
	v_cvt_pk_f32_fp8_sdwa v[158:159], v30 src0_sel:WORD_1
	v_cvt_pk_f32_fp8_e32 v[160:161], v31
	v_cvt_pk_f32_fp8_sdwa v[162:163], v31 src0_sel:WORD_1
	v_cvt_pk_f32_fp8_e32 v[164:165], v34
	v_cvt_pk_f32_fp8_sdwa v[166:167], v34 src0_sel:WORD_1
	v_cvt_pk_f32_fp8_e32 v[168:169], v35
	v_cvt_pk_f32_fp8_sdwa v[170:171], v35 src0_sel:WORD_1
	v_pk_fma_f32 v[182:183], v[156:157], v[224:225], v[182:183]
	v_pk_fma_f32 v[184:185], v[164:165], v[224:225], v[184:185]
	v_pk_fma_f32 v[182:183], v[158:159], v[226:227], v[182:183]
	v_pk_fma_f32 v[184:185], v[166:167], v[226:227], v[184:185]
	v_pk_fma_f32 v[182:183], v[160:161], v[228:229], v[182:183]
	v_pk_fma_f32 v[184:185], v[168:169], v[228:229], v[184:185]
	v_pk_fma_f32 v[182:183], v[162:163], v[230:231], v[182:183]
	v_pk_fma_f32 v[184:185], v[170:171], v[230:231], v[184:185]
	v_add_f32_e32 v246, v182, v183
	v_add_f32_e32 v247, v184, v185
	v_readlane_b32 s13, v56, 24
	s_lshl_b32 s52, s13, 10
	s_add_u32 s56, s98, s52
	s_addc_u32 s57, s99, 0
	global_load_dwordx4 v[28:31], v62, s[56:57]
	v_readlane_b32 s16, v56, 56
	s_lshl_b32 s52, s16, 10
	s_add_u32 s56, s98, s52
	s_addc_u32 s57, s99, 0
	global_load_dwordx4 v[32:35], v62, s[56:57]
	s_branch .Lex_d4
.Lex_d3:
	s_waitcnt vmcnt(14)
	v_cvt_pk_f32_fp8_e32 v[156:157], v4
	v_cvt_pk_f32_fp8_sdwa v[158:159], v4 src0_sel:WORD_1
	v_cvt_pk_f32_fp8_e32 v[160:161], v5
	v_cvt_pk_f32_fp8_sdwa v[162:163], v5 src0_sel:WORD_1
	v_cvt_pk_f32_fp8_e32 v[164:165], v8
	v_cvt_pk_f32_fp8_sdwa v[166:167], v8 src0_sel:WORD_1
	v_cvt_pk_f32_fp8_e32 v[168:169], v9
	v_cvt_pk_f32_fp8_sdwa v[170:171], v9 src0_sel:WORD_1
	v_pk_fma_f32 v[182:183], v[156:157], v[232:233], 0 op_sel_hi:[1,1,0]
	v_pk_fma_f32 v[184:185], v[164:165], v[232:233], 0 op_sel_hi:[1,1,0]
	v_pk_fma_f32 v[182:183], v[158:159], v[234:235], v[182:183]
	v_pk_fma_f32 v[184:185], v[166:167], v[234:235], v[184:185]
	v_pk_fma_f32 v[182:183], v[160:161], v[236:237], v[182:183]
	v_pk_fma_f32 v[184:185], v[168:169], v[236:237], v[184:185]
	v_pk_fma_f32 v[182:183], v[162:163], v[238:239], v[182:183]
	v_pk_fma_f32 v[184:185], v[170:171], v[238:239], v[184:185]
	v_cvt_pk_f32_fp8_e32 v[156:157], v6
	v_cvt_pk_f32_fp8_sdwa v[158:159], v6 src0_sel:WORD_1
	v_cvt_pk_f32_fp8_e32 v[160:161], v7
	v_cvt_pk_f32_fp8_sdwa v[162:163], v7 src0_sel:WORD_1
	v_cvt_pk_f32_fp8_e32 v[164:165], v10
	v_cvt_pk_f32_fp8_sdwa v[166:167], v10 src0_sel:WORD_1
	v_cvt_pk_f32_fp8_e32 v[168:169], v11
	v_cvt_pk_f32_fp8_sdwa v[170:171], v11 src0_sel:WORD_1
	v_pk_fma_f32 v[182:183], v[156:157], v[70:71], v[182:183]
	v_pk_fma_f32 v[184:185], v[164:165], v[70:71], v[184:185]
	v_pk_fma_f32 v[182:183], v[158:159], v[72:73], v[182:183]
	v_pk_fma_f32 v[184:185], v[166:167], v[72:73], v[184:185]
	v_pk_fma_f32 v[182:183], v[160:161], v[74:75], v[182:183]
	v_pk_fma_f32 v[184:185], v[168:169], v[74:75], v[184:185]
	v_pk_fma_f32 v[182:183], v[162:163], v[2:3], v[182:183]
	v_pk_fma_f32 v[184:185], v[170:171], v[2:3], v[184:185]
	v_add_f32_e32 v240, v182, v183
	v_add_f32_e32 v241, v184, v185
	v_readlane_b32 s5, v56, 0
	s_lshl_b32 s52, s5, 10
	s_add_u32 s56, s98, s52
	s_addc_u32 s57, s99, 0
	global_load_dwordx4 v[4:7], v62, s[56:57]
	v_readlane_b32 s6, v56, 32
	s_lshl_b32 s52, s6, 10
	s_add_u32 s56, s98, s52
	s_addc_u32 s57, s99, 0
	global_load_dwordx4 v[8:11], v62, s[56:57]
	s_waitcnt vmcnt(14)
	v_cvt_pk_f32_fp8_e32 v[156:157], v12
	v_cvt_pk_f32_fp8_sdwa v[158:159], v12 src0_sel:WORD_1
	v_cvt_pk_f32_fp8_e32 v[160:161], v13
	v_cvt_pk_f32_fp8_sdwa v[162:163], v13 src0_sel:WORD_1
	v_cvt_pk_f32_fp8_e32 v[164:165], v16
	v_cvt_pk_f32_fp8_sdwa v[166:167], v16 src0_sel:WORD_1
	v_cvt_pk_f32_fp8_e32 v[168:169], v17
	v_cvt_pk_f32_fp8_sdwa v[170:171], v17 src0_sel:WORD_1
	v_pk_fma_f32 v[182:183], v[156:157], v[232:233], 0 op_sel_hi:[1,1,0]
	v_pk_fma_f32 v[184:185], v[164:165], v[232:233], 0 op_sel_hi:[1,1,0]
	v_pk_fma_f32 v[182:183], v[158:159], v[234:235], v[182:183]
	v_pk_fma_f32 v[184:185], v[166:167], v[234:235], v[184:185]
	v_pk_fma_f32 v[182:183], v[160:161], v[236:237], v[182:183]
	v_pk_fma_f32 v[184:185], v[168:169], v[236:237], v[184:185]
	v_pk_fma_f32 v[182:183], v[162:163], v[238:239], v[182:183]
	v_pk_fma_f32 v[184:185], v[170:171], v[238:239], v[184:185]
	v_cvt_pk_f32_fp8_e32 v[156:157], v14
	v_cvt_pk_f32_fp8_sdwa v[158:159], v14 src0_sel:WORD_1
	v_cvt_pk_f32_fp8_e32 v[160:161], v15
	v_cvt_pk_f32_fp8_sdwa v[162:163], v15 src0_sel:WORD_1
	v_cvt_pk_f32_fp8_e32 v[164:165], v18
	v_cvt_pk_f32_fp8_sdwa v[166:167], v18 src0_sel:WORD_1
	v_cvt_pk_f32_fp8_e32 v[168:169], v19
	v_cvt_pk_f32_fp8_sdwa v[170:171], v19 src0_sel:WORD_1
	v_pk_fma_f32 v[182:183], v[156:157], v[70:71], v[182:183]
	v_pk_fma_f32 v[184:185], v[164:165], v[70:71], v[184:185]
	v_pk_fma_f32 v[182:183], v[158:159], v[72:73], v[182:183]
	v_pk_fma_f32 v[184:185], v[166:167], v[72:73], v[184:185]
	v_pk_fma_f32 v[182:183], v[160:161], v[74:75], v[182:183]
	v_pk_fma_f32 v[184:185], v[168:169], v[74:75], v[184:185]
	v_pk_fma_f32 v[182:183], v[162:163], v[2:3], v[182:183]
	v_pk_fma_f32 v[184:185], v[170:171], v[2:3], v[184:185]
	v_add_f32_e32 v242, v182, v183
	v_add_f32_e32 v243, v184, v185
	v_readlane_b32 s7, v56, 16
	s_lshl_b32 s52, s7, 10
	s_add_u32 s56, s98, s52
	s_addc_u32 s57, s99, 0
	global_load_dwordx4 v[12:15], v62, s[56:57]
	v_readlane_b32 s8, v56, 48
	s_lshl_b32 s52, s8, 10
	s_add_u32 s56, s98, s52
	s_addc_u32 s57, s99, 0
	global_load_dwordx4 v[16:19], v62, s[56:57]
	s_waitcnt vmcnt(14)
	v_cvt_pk_f32_fp8_e32 v[156:157], v20
	v_cvt_pk_f32_fp8_sdwa v[158:159], v20 src0_sel:WORD_1
	v_cvt_pk_f32_fp8_e32 v[160:161], v21
	v_cvt_pk_f32_fp8_sdwa v[162:163], v21 src0_sel:WORD_1
	v_cvt_pk_f32_fp8_e32 v[164:165], v24
	v_cvt_pk_f32_fp8_sdwa v[166:167], v24 src0_sel:WORD_1
	v_cvt_pk_f32_fp8_e32 v[168:169], v25
	v_cvt_pk_f32_fp8_sdwa v[170:171], v25 src0_sel:WORD_1
	v_pk_fma_f32 v[182:183], v[156:157], v[232:233], 0 op_sel_hi:[1,1,0]
	v_pk_fma_f32 v[184:185], v[164:165], v[232:233], 0 op_sel_hi:[1,1,0]
	v_pk_fma_f32 v[182:183], v[158:159], v[234:235], v[182:183]
	v_pk_fma_f32 v[184:185], v[166:167], v[234:235], v[184:185]
	v_pk_fma_f32 v[182:183], v[160:161], v[236:237], v[182:183]
	v_pk_fma_f32 v[184:185], v[168:169], v[236:237], v[184:185]
	v_pk_fma_f32 v[182:183], v[162:163], v[238:239], v[182:183]
	v_pk_fma_f32 v[184:185], v[170:171], v[238:239], v[184:185]
	v_cvt_pk_f32_fp8_e32 v[156:157], v22
	v_cvt_pk_f32_fp8_sdwa v[158:159], v22 src0_sel:WORD_1
	v_cvt_pk_f32_fp8_e32 v[160:161], v23
	v_cvt_pk_f32_fp8_sdwa v[162:163], v23 src0_sel:WORD_1
	v_cvt_pk_f32_fp8_e32 v[164:165], v26
	v_cvt_pk_f32_fp8_sdwa v[166:167], v26 src0_sel:WORD_1
	v_cvt_pk_f32_fp8_e32 v[168:169], v27
	v_cvt_pk_f32_fp8_sdwa v[170:171], v27 src0_sel:WORD_1
	v_pk_fma_f32 v[182:183], v[156:157], v[70:71], v[182:183]
	v_pk_fma_f32 v[184:185], v[164:165], v[70:71], v[184:185]
	v_pk_fma_f32 v[182:183], v[158:159], v[72:73], v[182:183]
	v_pk_fma_f32 v[184:185], v[166:167], v[72:73], v[184:185]
	v_pk_fma_f32 v[182:183], v[160:161], v[74:75], v[182:183]
	v_pk_fma_f32 v[184:185], v[168:169], v[74:75], v[184:185]
	v_pk_fma_f32 v[182:183], v[162:163], v[2:3], v[182:183]
	v_pk_fma_f32 v[184:185], v[170:171], v[2:3], v[184:185]
	v_add_f32_e32 v244, v182, v183
	v_add_f32_e32 v245, v184, v185
	v_readlane_b32 s9, v56, 8
	s_lshl_b32 s52, s9, 10
	s_add_u32 s56, s98, s52
	s_addc_u32 s57, s99, 0
	global_load_dwordx4 v[20:23], v62, s[56:57]
	v_readlane_b32 s11, v56, 40
	s_lshl_b32 s52, s11, 10
	s_add_u32 s56, s98, s52
	s_addc_u32 s57, s99, 0
	global_load_dwordx4 v[24:27], v62, s[56:57]
	s_waitcnt vmcnt(14)
	v_cvt_pk_f32_fp8_e32 v[156:157], v28
	v_cvt_pk_f32_fp8_sdwa v[158:159], v28 src0_sel:WORD_1
	v_cvt_pk_f32_fp8_e32 v[160:161], v29
	v_cvt_pk_f32_fp8_sdwa v[162:163], v29 src0_sel:WORD_1
	v_cvt_pk_f32_fp8_e32 v[164:165], v32
	v_cvt_pk_f32_fp8_sdwa v[166:167], v32 src0_sel:WORD_1
	v_cvt_pk_f32_fp8_e32 v[168:169], v33
	v_cvt_pk_f32_fp8_sdwa v[170:171], v33 src0_sel:WORD_1
	v_pk_fma_f32 v[182:183], v[156:157], v[232:233], 0 op_sel_hi:[1,1,0]
	v_pk_fma_f32 v[184:185], v[164:165], v[232:233], 0 op_sel_hi:[1,1,0]
	v_pk_fma_f32 v[182:183], v[158:159], v[234:235], v[182:183]
	v_pk_fma_f32 v[184:185], v[166:167], v[234:235], v[184:185]
	v_pk_fma_f32 v[182:183], v[160:161], v[236:237], v[182:183]
	v_pk_fma_f32 v[184:185], v[168:169], v[236:237], v[184:185]
	v_pk_fma_f32 v[182:183], v[162:163], v[238:239], v[182:183]
	v_pk_fma_f32 v[184:185], v[170:171], v[238:239], v[184:185]
	v_cvt_pk_f32_fp8_e32 v[156:157], v30
	v_cvt_pk_f32_fp8_sdwa v[158:159], v30 src0_sel:WORD_1
	v_cvt_pk_f32_fp8_e32 v[160:161], v31
	v_cvt_pk_f32_fp8_sdwa v[162:163], v31 src0_sel:WORD_1
	v_cvt_pk_f32_fp8_e32 v[164:165], v34
	v_cvt_pk_f32_fp8_sdwa v[166:167], v34 src0_sel:WORD_1
	v_cvt_pk_f32_fp8_e32 v[168:169], v35
	v_cvt_pk_f32_fp8_sdwa v[170:171], v35 src0_sel:WORD_1
	v_pk_fma_f32 v[182:183], v[156:157], v[70:71], v[182:183]
	v_pk_fma_f32 v[184:185], v[164:165], v[70:71], v[184:185]
	v_pk_fma_f32 v[182:183], v[158:159], v[72:73], v[182:183]
	v_pk_fma_f32 v[184:185], v[166:167], v[72:73], v[184:185]
	v_pk_fma_f32 v[182:183], v[160:161], v[74:75], v[182:183]
	v_pk_fma_f32 v[184:185], v[168:169], v[74:75], v[184:185]
	v_pk_fma_f32 v[182:183], v[162:163], v[2:3], v[182:183]
	v_pk_fma_f32 v[184:185], v[170:171], v[2:3], v[184:185]
	v_add_f32_e32 v246, v182, v183
	v_add_f32_e32 v247, v184, v185
	v_readlane_b32 s13, v56, 24
	s_lshl_b32 s52, s13, 10
	s_add_u32 s56, s98, s52
	s_addc_u32 s57, s99, 0
	global_load_dwordx4 v[28:31], v62, s[56:57]
	v_readlane_b32 s16, v56, 56
	s_lshl_b32 s52, s16, 10
	s_add_u32 s56, s98, s52
	s_addc_u32 s57, s99, 0
	global_load_dwordx4 v[32:35], v62, s[56:57]
.Lex_d4:
	s_nop 1
	v_permlane32_swap_b32_e32 v240, v241
	v_permlane32_swap_b32_e32 v242, v243
	v_permlane32_swap_b32_e32 v244, v245
	v_permlane32_swap_b32_e32 v246, v247
	v_add_f32_e32 v240, v240, v241
	v_add_f32_e32 v242, v242, v243
	v_add_f32_e32 v244, v244, v245
	v_add_f32_e32 v246, v246, v247
	s_nop 1
	v_permlane16_swap_b32_e32 v240, v242
	v_permlane16_swap_b32_e32 v244, v246
	v_add_f32_e32 v240, v240, v242
	v_add_f32_e32 v244, v244, v246
	s_nop 0
	s_nop 0
	v_add_f32_dpp v240, v240, v240 row_ror:8 row_mask:0xf bank_mask:0xf
	v_add_f32_dpp v244, v244, v244 row_ror:8 row_mask:0xf bank_mask:0xf
	s_nop 0
	v_add_f32_dpp v240, v240, v240 row_ror:4 row_mask:0xf bank_mask:0xf
	v_add_f32_dpp v244, v244, v244 row_ror:4 row_mask:0xf bank_mask:0xf
	s_nop 0
	v_add_f32_dpp v240, v240, v240 row_ror:2 row_mask:0xf bank_mask:0xf
	v_add_f32_dpp v244, v244, v244 row_ror:2 row_mask:0xf bank_mask:0xf
	s_nop 0
	v_add_f32_dpp v240, v240, v240 row_ror:1 row_mask:0xf bank_mask:0xf
	v_add_f32_dpp v244, v244, v244 row_ror:1 row_mask:0xf bank_mask:0xf
	s_nop 1
	v_cndmask_b32_e64 v248, v240, v244, s[0:1]
	v_mul_f32_e32 v248, v54, v248
	v_mul_f32_e32 v249, 0x3f3504f3, v248
	v_cmp_nlt_f32_e64 s[34:35], |v249|, 1.0
	s_and_saveexec_b64 s[52:53], s[34:35]
	s_xor_b64 s[34:35], exec, s[52:53]
	s_cbranch_execz .Lex_ga5
	v_fma_f32 v250, |v249|, s27, v178
	v_fma_f32 v250, |v249|, v250, s30
	v_fma_f32 v250, |v249|, v250, s31
	v_fma_f32 v250, |v249|, v250, s33
	v_fma_f32 v250, |v249|, v250, s37
	v_fma_f32 v250, |v249|, v250, s39
	v_fma_f32 v250, |v249|, v250, |v249|
	v_mul_f32_e32 v251, 0xbfb8aa3b, v250
	v_fma_f32 v252, v250, s41, -v251
	v_rndne_f32_e32 v253, v251
	v_fmac_f32_e32 v252, 0xb2a5705f, v250
	v_sub_f32_e32 v251, v251, v253
	v_add_f32_e32 v251, v251, v252
	v_cvt_i32_f32_e32 v252, v253
	v_exp_f32_e32 v251, v251
	v_cmp_nlt_f32_e32 vcc, s43, v250
	v_ldexp_f32 v251, v251, v252
	s_nop 0
	v_cndmask_b32_e32 v251, 0, v251, vcc
	v_cmp_ngt_f32_e32 vcc, s45, v250
	s_nop 1
	v_cndmask_b32_e32 v250, v179, v251, vcc
	v_sub_f32_e32 v250, 1.0, v250
.Lex_ga5:
	s_andn2_saveexec_b64 s[34:35], s[34:35]
	v_mul_f32_e32 v250, v249, v249
	v_fmamk_f32 v251, v250, 0xba1345e1, v176
	v_fmaak_f32 v251, v250, v251, 0xbcdac9b8
	v_fmaak_f32 v251, v250, v251, 0x3de703be
	v_fmaak_f32 v251, v250, v251, 0xbec09330
	v_fmaak_f32 v250, v250, v251, 0x3e0375d0
	v_fma_f32 v250, |v249|, v250, |v249|
	s_or_b64 exec, exec, s[34:35]
	v_bfi_b32 v249, s47, v250, v249
	v_mul_f32_e32 v248, 0.5, v248
	v_add_f32_e32 v249, 1.0, v249
	v_mul_f32_e32 v248, v248, v249
	v_mul_f32_e32 v254, v53, v248
	s_nop 0
	v_readlane_b32 s50, v254, 0
	v_readlane_b32 s48, v254, 32
	v_readlane_b32 s46, v254, 16
	v_readlane_b32 s44, v254, 48
	v_readlane_b32 s42, v254, 8
	v_readlane_b32 s40, v254, 40
	v_readlane_b32 s38, v254, 24
	v_readlane_b32 s36, v254, 56
	s_cmp_lg_u32 s15, 0
	s_cbranch_scc1 .Lex_d6
	s_waitcnt vmcnt(15)
	v_cvt_scalef32_pk_f32_fp4 v[156:157], v36, 1.0
	v_cvt_scalef32_pk_f32_fp4 v[158:159], v36, 1.0 op_sel:[1,0,0]
	v_cvt_scalef32_pk_f32_fp4 v[160:161], v36, 1.0 op_sel:[0,1,0]
	v_cvt_scalef32_pk_f32_fp4 v[162:163], v36, 1.0 op_sel:[1,1,0]
	v_cvt_scalef32_pk_f32_fp4 v[164:165], v37, 1.0
	v_cvt_scalef32_pk_f32_fp4 v[166:167], v37, 1.0 op_sel:[1,0,0]
	v_cvt_scalef32_pk_f32_fp4 v[168:169], v37, 1.0 op_sel:[0,1,0]
	v_cvt_scalef32_pk_f32_fp4 v[170:171], v37, 1.0 op_sel:[1,1,0]
	v_pk_fma_f32 v[108:109], v[156:157], s[50:51], v[108:109] op_sel_hi:[1,0,1]
	v_pk_fma_f32 v[110:111], v[158:159], s[50:51], v[110:111] op_sel_hi:[1,0,1]
	v_pk_fma_f32 v[112:113], v[160:161], s[50:51], v[112:113] op_sel_hi:[1,0,1]
	v_pk_fma_f32 v[114:115], v[162:163], s[50:51], v[114:115] op_sel_hi:[1,0,1]
	v_pk_fma_f32 v[116:117], v[164:165], s[50:51], v[116:117] op_sel_hi:[1,0,1]
	v_pk_fma_f32 v[118:119], v[166:167], s[50:51], v[118:119] op_sel_hi:[1,0,1]
	v_pk_fma_f32 v[120:121], v[168:169], s[50:51], v[120:121] op_sel_hi:[1,0,1]
	v_pk_fma_f32 v[122:123], v[170:171], s[50:51], v[122:123] op_sel_hi:[1,0,1]
	s_lshl_b32 s52, s5, 9
	s_add_u32 s58, s100, s52
	s_addc_u32 s59, s101, 0
	global_load_dwordx2 v[36:37], v63, s[58:59]
	s_waitcnt vmcnt(15)
	v_cvt_scalef32_pk_f32_fp4 v[156:157], v38, 1.0
	v_cvt_scalef32_pk_f32_fp4 v[158:159], v38, 1.0 op_sel:[1,0,0]
	v_cvt_scalef32_pk_f32_fp4 v[160:161], v38, 1.0 op_sel:[0,1,0]
	v_cvt_scalef32_pk_f32_fp4 v[162:163], v38, 1.0 op_sel:[1,1,0]
	v_cvt_scalef32_pk_f32_fp4 v[164:165], v39, 1.0
	v_cvt_scalef32_pk_f32_fp4 v[166:167], v39, 1.0 op_sel:[1,0,0]
	v_cvt_scalef32_pk_f32_fp4 v[168:169], v39, 1.0 op_sel:[0,1,0]
	v_cvt_scalef32_pk_f32_fp4 v[170:171], v39, 1.0 op_sel:[1,1,0]
	v_pk_fma_f32 v[108:109], v[156:157], s[48:49], v[108:109] op_sel_hi:[1,0,1]
	v_pk_fma_f32 v[110:111], v[158:159], s[48:49], v[110:111] op_sel_hi:[1,0,1]
	v_pk_fma_f32 v[112:113], v[160:161], s[48:49], v[112:113] op_sel_hi:[1,0,1]
	v_pk_fma_f32 v[114:115], v[162:163], s[48:49], v[114:115] op_sel_hi:[1,0,1]
	v_pk_fma_f32 v[116:117], v[164:165], s[48:49], v[116:117] op_sel_hi:[1,0,1]
	v_pk_fma_f32 v[118:119], v[166:167], s[48:49], v[118:119] op_sel_hi:[1,0,1]
	v_pk_fma_f32 v[120:121], v[168:169], s[48:49], v[120:121] op_sel_hi:[1,0,1]
	v_pk_fma_f32 v[122:123], v[170:171], s[48:49], v[122:123] op_sel_hi:[1,0,1]
	s_lshl_b32 s52, s6, 9
	s_add_u32 s58, s100, s52
	s_addc_u32 s59, s101, 0
	global_load_dwordx2 v[38:39], v63, s[58:59]
	s_waitcnt vmcnt(15)
	v_cvt_scalef32_pk_f32_fp4 v[156:157], v40, 1.0
	v_cvt_scalef32_pk_f32_fp4 v[158:159], v40, 1.0 op_sel:[1,0,0]
	v_cvt_scalef32_pk_f32_fp4 v[160:161], v40, 1.0 op_sel:[0,1,0]
	v_cvt_scalef32_pk_f32_fp4 v[162:163], v40, 1.0 op_sel:[1,1,0]
	v_cvt_scalef32_pk_f32_fp4 v[164:165], v41, 1.0
	v_cvt_scalef32_pk_f32_fp4 v[166:167], v41, 1.0 op_sel:[1,0,0]
	v_cvt_scalef32_pk_f32_fp4 v[168:169], v41, 1.0 op_sel:[0,1,0]
	v_cvt_scalef32_pk_f32_fp4 v[170:171], v41, 1.0 op_sel:[1,1,0]
	v_pk_fma_f32 v[108:109], v[156:157], s[46:47], v[108:109] op_sel_hi:[1,0,1]
	v_pk_fma_f32 v[110:111], v[158:159], s[46:47], v[110:111] op_sel_hi:[1,0,1]
	v_pk_fma_f32 v[112:113], v[160:161], s[46:47], v[112:113] op_sel_hi:[1,0,1]
	v_pk_fma_f32 v[114:115], v[162:163], s[46:47], v[114:115] op_sel_hi:[1,0,1]
	v_pk_fma_f32 v[116:117], v[164:165], s[46:47], v[116:117] op_sel_hi:[1,0,1]
	v_pk_fma_f32 v[118:119], v[166:167], s[46:47], v[118:119] op_sel_hi:[1,0,1]
	v_pk_fma_f32 v[120:121], v[168:169], s[46:47], v[120:121] op_sel_hi:[1,0,1]
	v_pk_fma_f32 v[122:123], v[170:171], s[46:47], v[122:123] op_sel_hi:[1,0,1]
	s_lshl_b32 s52, s7, 9
	s_add_u32 s58, s100, s52
	s_addc_u32 s59, s101, 0
	global_load_dwordx2 v[40:41], v63, s[58:59]
	s_waitcnt vmcnt(15)
	v_cvt_scalef32_pk_f32_fp4 v[156:157], v42, 1.0
	v_cvt_scalef32_pk_f32_fp4 v[158:159], v42, 1.0 op_sel:[1,0,0]
	v_cvt_scalef32_pk_f32_fp4 v[160:161], v42, 1.0 op_sel:[0,1,0]
	v_cvt_scalef32_pk_f32_fp4 v[162:163], v42, 1.0 op_sel:[1,1,0]
	v_cvt_scalef32_pk_f32_fp4 v[164:165], v43, 1.0
	v_cvt_scalef32_pk_f32_fp4 v[166:167], v43, 1.0 op_sel:[1,0,0]
	v_cvt_scalef32_pk_f32_fp4 v[168:169], v43, 1.0 op_sel:[0,1,0]
	v_cvt_scalef32_pk_f32_fp4 v[170:171], v43, 1.0 op_sel:[1,1,0]
	v_pk_fma_f32 v[108:109], v[156:157], s[44:45], v[108:109] op_sel_hi:[1,0,1]
	v_pk_fma_f32 v[110:111], v[158:159], s[44:45], v[110:111] op_sel_hi:[1,0,1]
	v_pk_fma_f32 v[112:113], v[160:161], s[44:45], v[112:113] op_sel_hi:[1,0,1]
	v_pk_fma_f32 v[114:115], v[162:163], s[44:45], v[114:115] op_sel_hi:[1,0,1]
	v_pk_fma_f32 v[116:117], v[164:165], s[44:45], v[116:117] op_sel_hi:[1,0,1]
	v_pk_fma_f32 v[118:119], v[166:167], s[44:45], v[118:119] op_sel_hi:[1,0,1]
	v_pk_fma_f32 v[120:121], v[168:169], s[44:45], v[120:121] op_sel_hi:[1,0,1]
	v_pk_fma_f32 v[122:123], v[170:171], s[44:45], v[122:123] op_sel_hi:[1,0,1]
	s_lshl_b32 s52, s8, 9
	s_add_u32 s58, s100, s52
	s_addc_u32 s59, s101, 0
	global_load_dwordx2 v[42:43], v63, s[58:59]
	s_waitcnt vmcnt(15)
	v_cvt_scalef32_pk_f32_fp4 v[156:157], v44, 1.0
	v_cvt_scalef32_pk_f32_fp4 v[158:159], v44, 1.0 op_sel:[1,0,0]
	v_cvt_scalef32_pk_f32_fp4 v[160:161], v44, 1.0 op_sel:[0,1,0]
	v_cvt_scalef32_pk_f32_fp4 v[162:163], v44, 1.0 op_sel:[1,1,0]
	v_cvt_scalef32_pk_f32_fp4 v[164:165], v45, 1.0
	v_cvt_scalef32_pk_f32_fp4 v[166:167], v45, 1.0 op_sel:[1,0,0]
	v_cvt_scalef32_pk_f32_fp4 v[168:169], v45, 1.0 op_sel:[0,1,0]
	v_cvt_scalef32_pk_f32_fp4 v[170:171], v45, 1.0 op_sel:[1,1,0]
	v_pk_fma_f32 v[108:109], v[156:157], s[42:43], v[108:109] op_sel_hi:[1,0,1]
	v_pk_fma_f32 v[110:111], v[158:159], s[42:43], v[110:111] op_sel_hi:[1,0,1]
	v_pk_fma_f32 v[112:113], v[160:161], s[42:43], v[112:113] op_sel_hi:[1,0,1]
	v_pk_fma_f32 v[114:115], v[162:163], s[42:43], v[114:115] op_sel_hi:[1,0,1]
	v_pk_fma_f32 v[116:117], v[164:165], s[42:43], v[116:117] op_sel_hi:[1,0,1]
	v_pk_fma_f32 v[118:119], v[166:167], s[42:43], v[118:119] op_sel_hi:[1,0,1]
	v_pk_fma_f32 v[120:121], v[168:169], s[42:43], v[120:121] op_sel_hi:[1,0,1]
	v_pk_fma_f32 v[122:123], v[170:171], s[42:43], v[122:123] op_sel_hi:[1,0,1]
	s_lshl_b32 s52, s9, 9
	s_add_u32 s58, s100, s52
	s_addc_u32 s59, s101, 0
	global_load_dwordx2 v[44:45], v63, s[58:59]
	s_waitcnt vmcnt(15)
	v_cvt_scalef32_pk_f32_fp4 v[156:157], v46, 1.0
	v_cvt_scalef32_pk_f32_fp4 v[158:159], v46, 1.0 op_sel:[1,0,0]
	v_cvt_scalef32_pk_f32_fp4 v[160:161], v46, 1.0 op_sel:[0,1,0]
	v_cvt_scalef32_pk_f32_fp4 v[162:163], v46, 1.0 op_sel:[1,1,0]
	v_cvt_scalef32_pk_f32_fp4 v[164:165], v47, 1.0
	v_cvt_scalef32_pk_f32_fp4 v[166:167], v47, 1.0 op_sel:[1,0,0]
	v_cvt_scalef32_pk_f32_fp4 v[168:169], v47, 1.0 op_sel:[0,1,0]
	v_cvt_scalef32_pk_f32_fp4 v[170:171], v47, 1.0 op_sel:[1,1,0]
	v_pk_fma_f32 v[108:109], v[156:157], s[40:41], v[108:109] op_sel_hi:[1,0,1]
	v_pk_fma_f32 v[110:111], v[158:159], s[40:41], v[110:111] op_sel_hi:[1,0,1]
	v_pk_fma_f32 v[112:113], v[160:161], s[40:41], v[112:113] op_sel_hi:[1,0,1]
	v_pk_fma_f32 v[114:115], v[162:163], s[40:41], v[114:115] op_sel_hi:[1,0,1]
	v_pk_fma_f32 v[116:117], v[164:165], s[40:41], v[116:117] op_sel_hi:[1,0,1]
	v_pk_fma_f32 v[118:119], v[166:167], s[40:41], v[118:119] op_sel_hi:[1,0,1]
	v_pk_fma_f32 v[120:121], v[168:169], s[40:41], v[120:121] op_sel_hi:[1,0,1]
	v_pk_fma_f32 v[122:123], v[170:171], s[40:41], v[122:123] op_sel_hi:[1,0,1]
	s_lshl_b32 s52, s11, 9
	s_add_u32 s58, s100, s52
	s_addc_u32 s59, s101, 0
	global_load_dwordx2 v[46:47], v63, s[58:59]
	s_waitcnt vmcnt(15)
	v_cvt_scalef32_pk_f32_fp4 v[156:157], v48, 1.0
	v_cvt_scalef32_pk_f32_fp4 v[158:159], v48, 1.0 op_sel:[1,0,0]
	v_cvt_scalef32_pk_f32_fp4 v[160:161], v48, 1.0 op_sel:[0,1,0]
	v_cvt_scalef32_pk_f32_fp4 v[162:163], v48, 1.0 op_sel:[1,1,0]
	v_cvt_scalef32_pk_f32_fp4 v[164:165], v49, 1.0
	v_cvt_scalef32_pk_f32_fp4 v[166:167], v49, 1.0 op_sel:[1,0,0]
	v_cvt_scalef32_pk_f32_fp4 v[168:169], v49, 1.0 op_sel:[0,1,0]
	v_cvt_scalef32_pk_f32_fp4 v[170:171], v49, 1.0 op_sel:[1,1,0]
	v_pk_fma_f32 v[108:109], v[156:157], s[38:39], v[108:109] op_sel_hi:[1,0,1]
	v_pk_fma_f32 v[110:111], v[158:159], s[38:39], v[110:111] op_sel_hi:[1,0,1]
	v_pk_fma_f32 v[112:113], v[160:161], s[38:39], v[112:113] op_sel_hi:[1,0,1]
	v_pk_fma_f32 v[114:115], v[162:163], s[38:39], v[114:115] op_sel_hi:[1,0,1]
	v_pk_fma_f32 v[116:117], v[164:165], s[38:39], v[116:117] op_sel_hi:[1,0,1]
	v_pk_fma_f32 v[118:119], v[166:167], s[38:39], v[118:119] op_sel_hi:[1,0,1]
	v_pk_fma_f32 v[120:121], v[168:169], s[38:39], v[120:121] op_sel_hi:[1,0,1]
	v_pk_fma_f32 v[122:123], v[170:171], s[38:39], v[122:123] op_sel_hi:[1,0,1]
	s_lshl_b32 s52, s13, 9
	s_add_u32 s58, s100, s52
	s_addc_u32 s59, s101, 0
	global_load_dwordx2 v[48:49], v63, s[58:59]
	s_waitcnt vmcnt(15)
	v_cvt_scalef32_pk_f32_fp4 v[156:157], v50, 1.0
	v_cvt_scalef32_pk_f32_fp4 v[158:159], v50, 1.0 op_sel:[1,0,0]
	v_cvt_scalef32_pk_f32_fp4 v[160:161], v50, 1.0 op_sel:[0,1,0]
	v_cvt_scalef32_pk_f32_fp4 v[162:163], v50, 1.0 op_sel:[1,1,0]
	v_cvt_scalef32_pk_f32_fp4 v[164:165], v51, 1.0
	v_cvt_scalef32_pk_f32_fp4 v[166:167], v51, 1.0 op_sel:[1,0,0]
	v_cvt_scalef32_pk_f32_fp4 v[168:169], v51, 1.0 op_sel:[0,1,0]
	v_cvt_scalef32_pk_f32_fp4 v[170:171], v51, 1.0 op_sel:[1,1,0]
	v_pk_fma_f32 v[108:109], v[156:157], s[36:37], v[108:109] op_sel_hi:[1,0,1]
	v_pk_fma_f32 v[110:111], v[158:159], s[36:37], v[110:111] op_sel_hi:[1,0,1]
	v_pk_fma_f32 v[112:113], v[160:161], s[36:37], v[112:113] op_sel_hi:[1,0,1]
	v_pk_fma_f32 v[114:115], v[162:163], s[36:37], v[114:115] op_sel_hi:[1,0,1]
	v_pk_fma_f32 v[116:117], v[164:165], s[36:37], v[116:117] op_sel_hi:[1,0,1]
	v_pk_fma_f32 v[118:119], v[166:167], s[36:37], v[118:119] op_sel_hi:[1,0,1]
	v_pk_fma_f32 v[120:121], v[168:169], s[36:37], v[120:121] op_sel_hi:[1,0,1]
	v_pk_fma_f32 v[122:123], v[170:171], s[36:37], v[122:123] op_sel_hi:[1,0,1]
	s_lshl_b32 s52, s16, 9
	s_add_u32 s58, s100, s52
	s_addc_u32 s59, s101, 0
	global_load_dwordx2 v[50:51], v63, s[58:59]
	s_branch .Lex_d9
.Lex_d6:
	s_cmp_lg_u32 s15, 1
	s_cbranch_scc1 .Lex_d7
	s_waitcnt vmcnt(15)
	v_cvt_scalef32_pk_f32_fp4 v[156:157], v36, 1.0
	v_cvt_scalef32_pk_f32_fp4 v[158:159], v36, 1.0 op_sel:[1,0,0]
	v_cvt_scalef32_pk_f32_fp4 v[160:161], v36, 1.0 op_sel:[0,1,0]
	v_cvt_scalef32_pk_f32_fp4 v[162:163], v36, 1.0 op_sel:[1,1,0]
	v_cvt_scalef32_pk_f32_fp4 v[164:165], v37, 1.0
	v_cvt_scalef32_pk_f32_fp4 v[166:167], v37, 1.0 op_sel:[1,0,0]
	v_cvt_scalef32_pk_f32_fp4 v[168:169], v37, 1.0 op_sel:[0,1,0]
	v_cvt_scalef32_pk_f32_fp4 v[170:171], v37, 1.0 op_sel:[1,1,0]
	v_pk_fma_f32 v[124:125], v[156:157], s[50:51], v[124:125] op_sel_hi:[1,0,1]
	v_pk_fma_f32 v[126:127], v[158:159], s[50:51], v[126:127] op_sel_hi:[1,0,1]
	v_pk_fma_f32 v[128:129], v[160:161], s[50:51], v[128:129] op_sel_hi:[1,0,1]
	v_pk_fma_f32 v[130:131], v[162:163], s[50:51], v[130:131] op_sel_hi:[1,0,1]
	v_pk_fma_f32 v[132:133], v[164:165], s[50:51], v[132:133] op_sel_hi:[1,0,1]
	v_pk_fma_f32 v[136:137], v[166:167], s[50:51], v[136:137] op_sel_hi:[1,0,1]
	v_pk_fma_f32 v[138:139], v[168:169], s[50:51], v[138:139] op_sel_hi:[1,0,1]
	v_pk_fma_f32 v[140:141], v[170:171], s[50:51], v[140:141] op_sel_hi:[1,0,1]
	s_lshl_b32 s52, s5, 9
	s_add_u32 s58, s100, s52
	s_addc_u32 s59, s101, 0
	global_load_dwordx2 v[36:37], v63, s[58:59]
	s_waitcnt vmcnt(15)
	v_cvt_scalef32_pk_f32_fp4 v[156:157], v38, 1.0
	v_cvt_scalef32_pk_f32_fp4 v[158:159], v38, 1.0 op_sel:[1,0,0]
	v_cvt_scalef32_pk_f32_fp4 v[160:161], v38, 1.0 op_sel:[0,1,0]
	v_cvt_scalef32_pk_f32_fp4 v[162:163], v38, 1.0 op_sel:[1,1,0]
	v_cvt_scalef32_pk_f32_fp4 v[164:165], v39, 1.0
	v_cvt_scalef32_pk_f32_fp4 v[166:167], v39, 1.0 op_sel:[1,0,0]
	v_cvt_scalef32_pk_f32_fp4 v[168:169], v39, 1.0 op_sel:[0,1,0]
	v_cvt_scalef32_pk_f32_fp4 v[170:171], v39, 1.0 op_sel:[1,1,0]
	v_pk_fma_f32 v[124:125], v[156:157], s[48:49], v[124:125] op_sel_hi:[1,0,1]
	v_pk_fma_f32 v[126:127], v[158:159], s[48:49], v[126:127] op_sel_hi:[1,0,1]
	v_pk_fma_f32 v[128:129], v[160:161], s[48:49], v[128:129] op_sel_hi:[1,0,1]
	v_pk_fma_f32 v[130:131], v[162:163], s[48:49], v[130:131] op_sel_hi:[1,0,1]
	v_pk_fma_f32 v[132:133], v[164:165], s[48:49], v[132:133] op_sel_hi:[1,0,1]
	v_pk_fma_f32 v[136:137], v[166:167], s[48:49], v[136:137] op_sel_hi:[1,0,1]
	v_pk_fma_f32 v[138:139], v[168:169], s[48:49], v[138:139] op_sel_hi:[1,0,1]
	v_pk_fma_f32 v[140:141], v[170:171], s[48:49], v[140:141] op_sel_hi:[1,0,1]
	s_lshl_b32 s52, s6, 9
	s_add_u32 s58, s100, s52
	s_addc_u32 s59, s101, 0
	global_load_dwordx2 v[38:39], v63, s[58:59]
	s_waitcnt vmcnt(15)
	v_cvt_scalef32_pk_f32_fp4 v[156:157], v40, 1.0
	v_cvt_scalef32_pk_f32_fp4 v[158:159], v40, 1.0 op_sel:[1,0,0]
	v_cvt_scalef32_pk_f32_fp4 v[160:161], v40, 1.0 op_sel:[0,1,0]
	v_cvt_scalef32_pk_f32_fp4 v[162:163], v40, 1.0 op_sel:[1,1,0]
	v_cvt_scalef32_pk_f32_fp4 v[164:165], v41, 1.0
	v_cvt_scalef32_pk_f32_fp4 v[166:167], v41, 1.0 op_sel:[1,0,0]
	v_cvt_scalef32_pk_f32_fp4 v[168:169], v41, 1.0 op_sel:[0,1,0]
	v_cvt_scalef32_pk_f32_fp4 v[170:171], v41, 1.0 op_sel:[1,1,0]
	v_pk_fma_f32 v[124:125], v[156:157], s[46:47], v[124:125] op_sel_hi:[1,0,1]
	v_pk_fma_f32 v[126:127], v[158:159], s[46:47], v[126:127] op_sel_hi:[1,0,1]
	v_pk_fma_f32 v[128:129], v[160:161], s[46:47], v[128:129] op_sel_hi:[1,0,1]
	v_pk_fma_f32 v[130:131], v[162:163], s[46:47], v[130:131] op_sel_hi:[1,0,1]
	v_pk_fma_f32 v[132:133], v[164:165], s[46:47], v[132:133] op_sel_hi:[1,0,1]
	v_pk_fma_f32 v[136:137], v[166:167], s[46:47], v[136:137] op_sel_hi:[1,0,1]
	v_pk_fma_f32 v[138:139], v[168:169], s[46:47], v[138:139] op_sel_hi:[1,0,1]
	v_pk_fma_f32 v[140:141], v[170:171], s[46:47], v[140:141] op_sel_hi:[1,0,1]
	s_lshl_b32 s52, s7, 9
	s_add_u32 s58, s100, s52
	s_addc_u32 s59, s101, 0
	global_load_dwordx2 v[40:41], v63, s[58:59]
	s_waitcnt vmcnt(15)
	v_cvt_scalef32_pk_f32_fp4 v[156:157], v42, 1.0
	v_cvt_scalef32_pk_f32_fp4 v[158:159], v42, 1.0 op_sel:[1,0,0]
	v_cvt_scalef32_pk_f32_fp4 v[160:161], v42, 1.0 op_sel:[0,1,0]
	v_cvt_scalef32_pk_f32_fp4 v[162:163], v42, 1.0 op_sel:[1,1,0]
	v_cvt_scalef32_pk_f32_fp4 v[164:165], v43, 1.0
	v_cvt_scalef32_pk_f32_fp4 v[166:167], v43, 1.0 op_sel:[1,0,0]
	v_cvt_scalef32_pk_f32_fp4 v[168:169], v43, 1.0 op_sel:[0,1,0]
	v_cvt_scalef32_pk_f32_fp4 v[170:171], v43, 1.0 op_sel:[1,1,0]
	v_pk_fma_f32 v[124:125], v[156:157], s[44:45], v[124:125] op_sel_hi:[1,0,1]
	v_pk_fma_f32 v[126:127], v[158:159], s[44:45], v[126:127] op_sel_hi:[1,0,1]
	v_pk_fma_f32 v[128:129], v[160:161], s[44:45], v[128:129] op_sel_hi:[1,0,1]
	v_pk_fma_f32 v[130:131], v[162:163], s[44:45], v[130:131] op_sel_hi:[1,0,1]
	v_pk_fma_f32 v[132:133], v[164:165], s[44:45], v[132:133] op_sel_hi:[1,0,1]
	v_pk_fma_f32 v[136:137], v[166:167], s[44:45], v[136:137] op_sel_hi:[1,0,1]
	v_pk_fma_f32 v[138:139], v[168:169], s[44:45], v[138:139] op_sel_hi:[1,0,1]
	v_pk_fma_f32 v[140:141], v[170:171], s[44:45], v[140:141] op_sel_hi:[1,0,1]
	s_lshl_b32 s52, s8, 9
	s_add_u32 s58, s100, s52
	s_addc_u32 s59, s101, 0
	global_load_dwordx2 v[42:43], v63, s[58:59]
	s_waitcnt vmcnt(15)
	v_cvt_scalef32_pk_f32_fp4 v[156:157], v44, 1.0
	v_cvt_scalef32_pk_f32_fp4 v[158:159], v44, 1.0 op_sel:[1,0,0]
	v_cvt_scalef32_pk_f32_fp4 v[160:161], v44, 1.0 op_sel:[0,1,0]
	v_cvt_scalef32_pk_f32_fp4 v[162:163], v44, 1.0 op_sel:[1,1,0]
	v_cvt_scalef32_pk_f32_fp4 v[164:165], v45, 1.0
	v_cvt_scalef32_pk_f32_fp4 v[166:167], v45, 1.0 op_sel:[1,0,0]
	v_cvt_scalef32_pk_f32_fp4 v[168:169], v45, 1.0 op_sel:[0,1,0]
	v_cvt_scalef32_pk_f32_fp4 v[170:171], v45, 1.0 op_sel:[1,1,0]
	v_pk_fma_f32 v[124:125], v[156:157], s[42:43], v[124:125] op_sel_hi:[1,0,1]
	v_pk_fma_f32 v[126:127], v[158:159], s[42:43], v[126:127] op_sel_hi:[1,0,1]
	v_pk_fma_f32 v[128:129], v[160:161], s[42:43], v[128:129] op_sel_hi:[1,0,1]
	v_pk_fma_f32 v[130:131], v[162:163], s[42:43], v[130:131] op_sel_hi:[1,0,1]
	v_pk_fma_f32 v[132:133], v[164:165], s[42:43], v[132:133] op_sel_hi:[1,0,1]
	v_pk_fma_f32 v[136:137], v[166:167], s[42:43], v[136:137] op_sel_hi:[1,0,1]
	v_pk_fma_f32 v[138:139], v[168:169], s[42:43], v[138:139] op_sel_hi:[1,0,1]
	v_pk_fma_f32 v[140:141], v[170:171], s[42:43], v[140:141] op_sel_hi:[1,0,1]
	s_lshl_b32 s52, s9, 9
	s_add_u32 s58, s100, s52
	s_addc_u32 s59, s101, 0
	global_load_dwordx2 v[44:45], v63, s[58:59]
	s_waitcnt vmcnt(15)
	v_cvt_scalef32_pk_f32_fp4 v[156:157], v46, 1.0
	v_cvt_scalef32_pk_f32_fp4 v[158:159], v46, 1.0 op_sel:[1,0,0]
	v_cvt_scalef32_pk_f32_fp4 v[160:161], v46, 1.0 op_sel:[0,1,0]
	v_cvt_scalef32_pk_f32_fp4 v[162:163], v46, 1.0 op_sel:[1,1,0]
	v_cvt_scalef32_pk_f32_fp4 v[164:165], v47, 1.0
	v_cvt_scalef32_pk_f32_fp4 v[166:167], v47, 1.0 op_sel:[1,0,0]
	v_cvt_scalef32_pk_f32_fp4 v[168:169], v47, 1.0 op_sel:[0,1,0]
	v_cvt_scalef32_pk_f32_fp4 v[170:171], v47, 1.0 op_sel:[1,1,0]
	v_pk_fma_f32 v[124:125], v[156:157], s[40:41], v[124:125] op_sel_hi:[1,0,1]
	v_pk_fma_f32 v[126:127], v[158:159], s[40:41], v[126:127] op_sel_hi:[1,0,1]
	v_pk_fma_f32 v[128:129], v[160:161], s[40:41], v[128:129] op_sel_hi:[1,0,1]
	v_pk_fma_f32 v[130:131], v[162:163], s[40:41], v[130:131] op_sel_hi:[1,0,1]
	v_pk_fma_f32 v[132:133], v[164:165], s[40:41], v[132:133] op_sel_hi:[1,0,1]
	v_pk_fma_f32 v[136:137], v[166:167], s[40:41], v[136:137] op_sel_hi:[1,0,1]
	v_pk_fma_f32 v[138:139], v[168:169], s[40:41], v[138:139] op_sel_hi:[1,0,1]
	v_pk_fma_f32 v[140:141], v[170:171], s[40:41], v[140:141] op_sel_hi:[1,0,1]
	s_lshl_b32 s52, s11, 9
	s_add_u32 s58, s100, s52
	s_addc_u32 s59, s101, 0
	global_load_dwordx2 v[46:47], v63, s[58:59]
	s_waitcnt vmcnt(15)
	v_cvt_scalef32_pk_f32_fp4 v[156:157], v48, 1.0
	v_cvt_scalef32_pk_f32_fp4 v[158:159], v48, 1.0 op_sel:[1,0,0]
	v_cvt_scalef32_pk_f32_fp4 v[160:161], v48, 1.0 op_sel:[0,1,0]
	v_cvt_scalef32_pk_f32_fp4 v[162:163], v48, 1.0 op_sel:[1,1,0]
	v_cvt_scalef32_pk_f32_fp4 v[164:165], v49, 1.0
	v_cvt_scalef32_pk_f32_fp4 v[166:167], v49, 1.0 op_sel:[1,0,0]
	v_cvt_scalef32_pk_f32_fp4 v[168:169], v49, 1.0 op_sel:[0,1,0]
	v_cvt_scalef32_pk_f32_fp4 v[170:171], v49, 1.0 op_sel:[1,1,0]
	v_pk_fma_f32 v[124:125], v[156:157], s[38:39], v[124:125] op_sel_hi:[1,0,1]
	v_pk_fma_f32 v[126:127], v[158:159], s[38:39], v[126:127] op_sel_hi:[1,0,1]
	v_pk_fma_f32 v[128:129], v[160:161], s[38:39], v[128:129] op_sel_hi:[1,0,1]
	v_pk_fma_f32 v[130:131], v[162:163], s[38:39], v[130:131] op_sel_hi:[1,0,1]
	v_pk_fma_f32 v[132:133], v[164:165], s[38:39], v[132:133] op_sel_hi:[1,0,1]
	v_pk_fma_f32 v[136:137], v[166:167], s[38:39], v[136:137] op_sel_hi:[1,0,1]
	v_pk_fma_f32 v[138:139], v[168:169], s[38:39], v[138:139] op_sel_hi:[1,0,1]
	v_pk_fma_f32 v[140:141], v[170:171], s[38:39], v[140:141] op_sel_hi:[1,0,1]
	s_lshl_b32 s52, s13, 9
	s_add_u32 s58, s100, s52
	s_addc_u32 s59, s101, 0
	global_load_dwordx2 v[48:49], v63, s[58:59]
	s_waitcnt vmcnt(15)
	v_cvt_scalef32_pk_f32_fp4 v[156:157], v50, 1.0
	v_cvt_scalef32_pk_f32_fp4 v[158:159], v50, 1.0 op_sel:[1,0,0]
	v_cvt_scalef32_pk_f32_fp4 v[160:161], v50, 1.0 op_sel:[0,1,0]
	v_cvt_scalef32_pk_f32_fp4 v[162:163], v50, 1.0 op_sel:[1,1,0]
	v_cvt_scalef32_pk_f32_fp4 v[164:165], v51, 1.0
	v_cvt_scalef32_pk_f32_fp4 v[166:167], v51, 1.0 op_sel:[1,0,0]
	v_cvt_scalef32_pk_f32_fp4 v[168:169], v51, 1.0 op_sel:[0,1,0]
	v_cvt_scalef32_pk_f32_fp4 v[170:171], v51, 1.0 op_sel:[1,1,0]
	v_pk_fma_f32 v[124:125], v[156:157], s[36:37], v[124:125] op_sel_hi:[1,0,1]
	v_pk_fma_f32 v[126:127], v[158:159], s[36:37], v[126:127] op_sel_hi:[1,0,1]
	v_pk_fma_f32 v[128:129], v[160:161], s[36:37], v[128:129] op_sel_hi:[1,0,1]
	v_pk_fma_f32 v[130:131], v[162:163], s[36:37], v[130:131] op_sel_hi:[1,0,1]
	v_pk_fma_f32 v[132:133], v[164:165], s[36:37], v[132:133] op_sel_hi:[1,0,1]
	v_pk_fma_f32 v[136:137], v[166:167], s[36:37], v[136:137] op_sel_hi:[1,0,1]
	v_pk_fma_f32 v[138:139], v[168:169], s[36:37], v[138:139] op_sel_hi:[1,0,1]
	v_pk_fma_f32 v[140:141], v[170:171], s[36:37], v[140:141] op_sel_hi:[1,0,1]
	s_lshl_b32 s52, s16, 9
	s_add_u32 s58, s100, s52
	s_addc_u32 s59, s101, 0
	global_load_dwordx2 v[50:51], v63, s[58:59]
	s_branch .Lex_d9
.Lex_d7:
	s_cmp_lg_u32 s15, 2
	s_cbranch_scc1 .Lex_d8
	s_waitcnt vmcnt(15)
	v_cvt_scalef32_pk_f32_fp4 v[156:157], v36, 1.0
	v_cvt_scalef32_pk_f32_fp4 v[158:159], v36, 1.0 op_sel:[1,0,0]
	v_cvt_scalef32_pk_f32_fp4 v[160:161], v36, 1.0 op_sel:[0,1,0]
	v_cvt_scalef32_pk_f32_fp4 v[162:163], v36, 1.0 op_sel:[1,1,0]
	v_cvt_scalef32_pk_f32_fp4 v[164:165], v37, 1.0
	v_cvt_scalef32_pk_f32_fp4 v[166:167], v37, 1.0 op_sel:[1,0,0]
	v_cvt_scalef32_pk_f32_fp4 v[168:169], v37, 1.0 op_sel:[0,1,0]
	v_cvt_scalef32_pk_f32_fp4 v[170:171], v37, 1.0 op_sel:[1,1,0]
	v_pk_fma_f32 v[188:189], v[156:157], s[50:51], v[188:189] op_sel_hi:[1,0,1]
	v_pk_fma_f32 v[190:191], v[158:159], s[50:51], v[190:191] op_sel_hi:[1,0,1]
	v_pk_fma_f32 v[192:193], v[160:161], s[50:51], v[192:193] op_sel_hi:[1,0,1]
	v_pk_fma_f32 v[194:195], v[162:163], s[50:51], v[194:195] op_sel_hi:[1,0,1]
	v_pk_fma_f32 v[196:197], v[164:165], s[50:51], v[196:197] op_sel_hi:[1,0,1]
	v_pk_fma_f32 v[198:199], v[166:167], s[50:51], v[198:199] op_sel_hi:[1,0,1]
	v_pk_fma_f32 v[200:201], v[168:169], s[50:51], v[200:201] op_sel_hi:[1,0,1]
	v_pk_fma_f32 v[202:203], v[170:171], s[50:51], v[202:203] op_sel_hi:[1,0,1]
	s_lshl_b32 s52, s5, 9
	s_add_u32 s58, s100, s52
	s_addc_u32 s59, s101, 0
	global_load_dwordx2 v[36:37], v63, s[58:59]
	s_waitcnt vmcnt(15)
	v_cvt_scalef32_pk_f32_fp4 v[156:157], v38, 1.0
	v_cvt_scalef32_pk_f32_fp4 v[158:159], v38, 1.0 op_sel:[1,0,0]
	v_cvt_scalef32_pk_f32_fp4 v[160:161], v38, 1.0 op_sel:[0,1,0]
	v_cvt_scalef32_pk_f32_fp4 v[162:163], v38, 1.0 op_sel:[1,1,0]
	v_cvt_scalef32_pk_f32_fp4 v[164:165], v39, 1.0
	v_cvt_scalef32_pk_f32_fp4 v[166:167], v39, 1.0 op_sel:[1,0,0]
	v_cvt_scalef32_pk_f32_fp4 v[168:169], v39, 1.0 op_sel:[0,1,0]
	v_cvt_scalef32_pk_f32_fp4 v[170:171], v39, 1.0 op_sel:[1,1,0]
	v_pk_fma_f32 v[188:189], v[156:157], s[48:49], v[188:189] op_sel_hi:[1,0,1]
	v_pk_fma_f32 v[190:191], v[158:159], s[48:49], v[190:191] op_sel_hi:[1,0,1]
	v_pk_fma_f32 v[192:193], v[160:161], s[48:49], v[192:193] op_sel_hi:[1,0,1]
	v_pk_fma_f32 v[194:195], v[162:163], s[48:49], v[194:195] op_sel_hi:[1,0,1]
	v_pk_fma_f32 v[196:197], v[164:165], s[48:49], v[196:197] op_sel_hi:[1,0,1]
	v_pk_fma_f32 v[198:199], v[166:167], s[48:49], v[198:199] op_sel_hi:[1,0,1]
	v_pk_fma_f32 v[200:201], v[168:169], s[48:49], v[200:201] op_sel_hi:[1,0,1]
	v_pk_fma_f32 v[202:203], v[170:171], s[48:49], v[202:203] op_sel_hi:[1,0,1]
	s_lshl_b32 s52, s6, 9
	s_add_u32 s58, s100, s52
	s_addc_u32 s59, s101, 0
	global_load_dwordx2 v[38:39], v63, s[58:59]
	s_waitcnt vmcnt(15)
	v_cvt_scalef32_pk_f32_fp4 v[156:157], v40, 1.0
	v_cvt_scalef32_pk_f32_fp4 v[158:159], v40, 1.0 op_sel:[1,0,0]
	v_cvt_scalef32_pk_f32_fp4 v[160:161], v40, 1.0 op_sel:[0,1,0]
	v_cvt_scalef32_pk_f32_fp4 v[162:163], v40, 1.0 op_sel:[1,1,0]
	v_cvt_scalef32_pk_f32_fp4 v[164:165], v41, 1.0
	v_cvt_scalef32_pk_f32_fp4 v[166:167], v41, 1.0 op_sel:[1,0,0]
	v_cvt_scalef32_pk_f32_fp4 v[168:169], v41, 1.0 op_sel:[0,1,0]
	v_cvt_scalef32_pk_f32_fp4 v[170:171], v41, 1.0 op_sel:[1,1,0]
	v_pk_fma_f32 v[188:189], v[156:157], s[46:47], v[188:189] op_sel_hi:[1,0,1]
	v_pk_fma_f32 v[190:191], v[158:159], s[46:47], v[190:191] op_sel_hi:[1,0,1]
	v_pk_fma_f32 v[192:193], v[160:161], s[46:47], v[192:193] op_sel_hi:[1,0,1]
	v_pk_fma_f32 v[194:195], v[162:163], s[46:47], v[194:195] op_sel_hi:[1,0,1]
	v_pk_fma_f32 v[196:197], v[164:165], s[46:47], v[196:197] op_sel_hi:[1,0,1]
	v_pk_fma_f32 v[198:199], v[166:167], s[46:47], v[198:199] op_sel_hi:[1,0,1]
	v_pk_fma_f32 v[200:201], v[168:169], s[46:47], v[200:201] op_sel_hi:[1,0,1]
	v_pk_fma_f32 v[202:203], v[170:171], s[46:47], v[202:203] op_sel_hi:[1,0,1]
	s_lshl_b32 s52, s7, 9
	s_add_u32 s58, s100, s52
	s_addc_u32 s59, s101, 0
	global_load_dwordx2 v[40:41], v63, s[58:59]
	s_waitcnt vmcnt(15)
	v_cvt_scalef32_pk_f32_fp4 v[156:157], v42, 1.0
	v_cvt_scalef32_pk_f32_fp4 v[158:159], v42, 1.0 op_sel:[1,0,0]
	v_cvt_scalef32_pk_f32_fp4 v[160:161], v42, 1.0 op_sel:[0,1,0]
	v_cvt_scalef32_pk_f32_fp4 v[162:163], v42, 1.0 op_sel:[1,1,0]
	v_cvt_scalef32_pk_f32_fp4 v[164:165], v43, 1.0
	v_cvt_scalef32_pk_f32_fp4 v[166:167], v43, 1.0 op_sel:[1,0,0]
	v_cvt_scalef32_pk_f32_fp4 v[168:169], v43, 1.0 op_sel:[0,1,0]
	v_cvt_scalef32_pk_f32_fp4 v[170:171], v43, 1.0 op_sel:[1,1,0]
	v_pk_fma_f32 v[188:189], v[156:157], s[44:45], v[188:189] op_sel_hi:[1,0,1]
	v_pk_fma_f32 v[190:191], v[158:159], s[44:45], v[190:191] op_sel_hi:[1,0,1]
	v_pk_fma_f32 v[192:193], v[160:161], s[44:45], v[192:193] op_sel_hi:[1,0,1]
	v_pk_fma_f32 v[194:195], v[162:163], s[44:45], v[194:195] op_sel_hi:[1,0,1]
	v_pk_fma_f32 v[196:197], v[164:165], s[44:45], v[196:197] op_sel_hi:[1,0,1]
	v_pk_fma_f32 v[198:199], v[166:167], s[44:45], v[198:199] op_sel_hi:[1,0,1]
	v_pk_fma_f32 v[200:201], v[168:169], s[44:45], v[200:201] op_sel_hi:[1,0,1]
	v_pk_fma_f32 v[202:203], v[170:171], s[44:45], v[202:203] op_sel_hi:[1,0,1]
	s_lshl_b32 s52, s8, 9
	s_add_u32 s58, s100, s52
	s_addc_u32 s59, s101, 0
	global_load_dwordx2 v[42:43], v63, s[58:59]
	s_waitcnt vmcnt(15)
	v_cvt_scalef32_pk_f32_fp4 v[156:157], v44, 1.0
	v_cvt_scalef32_pk_f32_fp4 v[158:159], v44, 1.0 op_sel:[1,0,0]
	v_cvt_scalef32_pk_f32_fp4 v[160:161], v44, 1.0 op_sel:[0,1,0]
	v_cvt_scalef32_pk_f32_fp4 v[162:163], v44, 1.0 op_sel:[1,1,0]
	v_cvt_scalef32_pk_f32_fp4 v[164:165], v45, 1.0
	v_cvt_scalef32_pk_f32_fp4 v[166:167], v45, 1.0 op_sel:[1,0,0]
	v_cvt_scalef32_pk_f32_fp4 v[168:169], v45, 1.0 op_sel:[0,1,0]
	v_cvt_scalef32_pk_f32_fp4 v[170:171], v45, 1.0 op_sel:[1,1,0]
	v_pk_fma_f32 v[188:189], v[156:157], s[42:43], v[188:189] op_sel_hi:[1,0,1]
	v_pk_fma_f32 v[190:191], v[158:159], s[42:43], v[190:191] op_sel_hi:[1,0,1]
	v_pk_fma_f32 v[192:193], v[160:161], s[42:43], v[192:193] op_sel_hi:[1,0,1]
	v_pk_fma_f32 v[194:195], v[162:163], s[42:43], v[194:195] op_sel_hi:[1,0,1]
	v_pk_fma_f32 v[196:197], v[164:165], s[42:43], v[196:197] op_sel_hi:[1,0,1]
	v_pk_fma_f32 v[198:199], v[166:167], s[42:43], v[198:199] op_sel_hi:[1,0,1]
	v_pk_fma_f32 v[200:201], v[168:169], s[42:43], v[200:201] op_sel_hi:[1,0,1]
	v_pk_fma_f32 v[202:203], v[170:171], s[42:43], v[202:203] op_sel_hi:[1,0,1]
	s_lshl_b32 s52, s9, 9
	s_add_u32 s58, s100, s52
	s_addc_u32 s59, s101, 0
	global_load_dwordx2 v[44:45], v63, s[58:59]
	s_waitcnt vmcnt(15)
	v_cvt_scalef32_pk_f32_fp4 v[156:157], v46, 1.0
	v_cvt_scalef32_pk_f32_fp4 v[158:159], v46, 1.0 op_sel:[1,0,0]
	v_cvt_scalef32_pk_f32_fp4 v[160:161], v46, 1.0 op_sel:[0,1,0]
	v_cvt_scalef32_pk_f32_fp4 v[162:163], v46, 1.0 op_sel:[1,1,0]
	v_cvt_scalef32_pk_f32_fp4 v[164:165], v47, 1.0
	v_cvt_scalef32_pk_f32_fp4 v[166:167], v47, 1.0 op_sel:[1,0,0]
	v_cvt_scalef32_pk_f32_fp4 v[168:169], v47, 1.0 op_sel:[0,1,0]
	v_cvt_scalef32_pk_f32_fp4 v[170:171], v47, 1.0 op_sel:[1,1,0]
	v_pk_fma_f32 v[188:189], v[156:157], s[40:41], v[188:189] op_sel_hi:[1,0,1]
	v_pk_fma_f32 v[190:191], v[158:159], s[40:41], v[190:191] op_sel_hi:[1,0,1]
	v_pk_fma_f32 v[192:193], v[160:161], s[40:41], v[192:193] op_sel_hi:[1,0,1]
	v_pk_fma_f32 v[194:195], v[162:163], s[40:41], v[194:195] op_sel_hi:[1,0,1]
	v_pk_fma_f32 v[196:197], v[164:165], s[40:41], v[196:197] op_sel_hi:[1,0,1]
	v_pk_fma_f32 v[198:199], v[166:167], s[40:41], v[198:199] op_sel_hi:[1,0,1]
	v_pk_fma_f32 v[200:201], v[168:169], s[40:41], v[200:201] op_sel_hi:[1,0,1]
	v_pk_fma_f32 v[202:203], v[170:171], s[40:41], v[202:203] op_sel_hi:[1,0,1]
	s_lshl_b32 s52, s11, 9
	s_add_u32 s58, s100, s52
	s_addc_u32 s59, s101, 0
	global_load_dwordx2 v[46:47], v63, s[58:59]
	s_waitcnt vmcnt(15)
	v_cvt_scalef32_pk_f32_fp4 v[156:157], v48, 1.0
	v_cvt_scalef32_pk_f32_fp4 v[158:159], v48, 1.0 op_sel:[1,0,0]
	v_cvt_scalef32_pk_f32_fp4 v[160:161], v48, 1.0 op_sel:[0,1,0]
	v_cvt_scalef32_pk_f32_fp4 v[162:163], v48, 1.0 op_sel:[1,1,0]
	v_cvt_scalef32_pk_f32_fp4 v[164:165], v49, 1.0
	v_cvt_scalef32_pk_f32_fp4 v[166:167], v49, 1.0 op_sel:[1,0,0]
	v_cvt_scalef32_pk_f32_fp4 v[168:169], v49, 1.0 op_sel:[0,1,0]
	v_cvt_scalef32_pk_f32_fp4 v[170:171], v49, 1.0 op_sel:[1,1,0]
	v_pk_fma_f32 v[188:189], v[156:157], s[38:39], v[188:189] op_sel_hi:[1,0,1]
	v_pk_fma_f32 v[190:191], v[158:159], s[38:39], v[190:191] op_sel_hi:[1,0,1]
	v_pk_fma_f32 v[192:193], v[160:161], s[38:39], v[192:193] op_sel_hi:[1,0,1]
	v_pk_fma_f32 v[194:195], v[162:163], s[38:39], v[194:195] op_sel_hi:[1,0,1]
	v_pk_fma_f32 v[196:197], v[164:165], s[38:39], v[196:197] op_sel_hi:[1,0,1]
	v_pk_fma_f32 v[198:199], v[166:167], s[38:39], v[198:199] op_sel_hi:[1,0,1]
	v_pk_fma_f32 v[200:201], v[168:169], s[38:39], v[200:201] op_sel_hi:[1,0,1]
	v_pk_fma_f32 v[202:203], v[170:171], s[38:39], v[202:203] op_sel_hi:[1,0,1]
	s_lshl_b32 s52, s13, 9
	s_add_u32 s58, s100, s52
	s_addc_u32 s59, s101, 0
	global_load_dwordx2 v[48:49], v63, s[58:59]
	s_waitcnt vmcnt(15)
	v_cvt_scalef32_pk_f32_fp4 v[156:157], v50, 1.0
	v_cvt_scalef32_pk_f32_fp4 v[158:159], v50, 1.0 op_sel:[1,0,0]
	v_cvt_scalef32_pk_f32_fp4 v[160:161], v50, 1.0 op_sel:[0,1,0]
	v_cvt_scalef32_pk_f32_fp4 v[162:163], v50, 1.0 op_sel:[1,1,0]
	v_cvt_scalef32_pk_f32_fp4 v[164:165], v51, 1.0
	v_cvt_scalef32_pk_f32_fp4 v[166:167], v51, 1.0 op_sel:[1,0,0]
	v_cvt_scalef32_pk_f32_fp4 v[168:169], v51, 1.0 op_sel:[0,1,0]
	v_cvt_scalef32_pk_f32_fp4 v[170:171], v51, 1.0 op_sel:[1,1,0]
	v_pk_fma_f32 v[188:189], v[156:157], s[36:37], v[188:189] op_sel_hi:[1,0,1]
	v_pk_fma_f32 v[190:191], v[158:159], s[36:37], v[190:191] op_sel_hi:[1,0,1]
	v_pk_fma_f32 v[192:193], v[160:161], s[36:37], v[192:193] op_sel_hi:[1,0,1]
	v_pk_fma_f32 v[194:195], v[162:163], s[36:37], v[194:195] op_sel_hi:[1,0,1]
	v_pk_fma_f32 v[196:197], v[164:165], s[36:37], v[196:197] op_sel_hi:[1,0,1]
	v_pk_fma_f32 v[198:199], v[166:167], s[36:37], v[198:199] op_sel_hi:[1,0,1]
	v_pk_fma_f32 v[200:201], v[168:169], s[36:37], v[200:201] op_sel_hi:[1,0,1]
	v_pk_fma_f32 v[202:203], v[170:171], s[36:37], v[202:203] op_sel_hi:[1,0,1]
	s_lshl_b32 s52, s16, 9
	s_add_u32 s58, s100, s52
	s_addc_u32 s59, s101, 0
	global_load_dwordx2 v[50:51], v63, s[58:59]
	s_branch .Lex_d9
.Lex_d8:
	s_waitcnt vmcnt(15)
	v_cvt_scalef32_pk_f32_fp4 v[156:157], v36, 1.0
	v_cvt_scalef32_pk_f32_fp4 v[158:159], v36, 1.0 op_sel:[1,0,0]
	v_cvt_scalef32_pk_f32_fp4 v[160:161], v36, 1.0 op_sel:[0,1,0]
	v_cvt_scalef32_pk_f32_fp4 v[162:163], v36, 1.0 op_sel:[1,1,0]
	v_cvt_scalef32_pk_f32_fp4 v[164:165], v37, 1.0
	v_cvt_scalef32_pk_f32_fp4 v[166:167], v37, 1.0 op_sel:[1,0,0]
	v_cvt_scalef32_pk_f32_fp4 v[168:169], v37, 1.0 op_sel:[0,1,0]
	v_cvt_scalef32_pk_f32_fp4 v[170:171], v37, 1.0 op_sel:[1,1,0]
	v_pk_fma_f32 v[204:205], v[156:157], s[50:51], v[204:205] op_sel_hi:[1,0,1]
	v_pk_fma_f32 v[206:207], v[158:159], s[50:51], v[206:207] op_sel_hi:[1,0,1]
	v_pk_fma_f32 v[208:209], v[160:161], s[50:51], v[208:209] op_sel_hi:[1,0,1]
	v_pk_fma_f32 v[210:211], v[162:163], s[50:51], v[210:211] op_sel_hi:[1,0,1]
	v_pk_fma_f32 v[212:213], v[164:165], s[50:51], v[212:213] op_sel_hi:[1,0,1]
	v_pk_fma_f32 v[186:187], v[166:167], s[50:51], v[186:187] op_sel_hi:[1,0,1]
	v_pk_fma_f32 v[66:67], v[168:169], s[50:51], v[66:67] op_sel_hi:[1,0,1]
	v_pk_fma_f32 v[68:69], v[170:171], s[50:51], v[68:69] op_sel_hi:[1,0,1]
	s_lshl_b32 s52, s5, 9
	s_add_u32 s58, s100, s52
	s_addc_u32 s59, s101, 0
	global_load_dwordx2 v[36:37], v63, s[58:59]
	s_waitcnt vmcnt(15)
	v_cvt_scalef32_pk_f32_fp4 v[156:157], v38, 1.0
	v_cvt_scalef32_pk_f32_fp4 v[158:159], v38, 1.0 op_sel:[1,0,0]
	v_cvt_scalef32_pk_f32_fp4 v[160:161], v38, 1.0 op_sel:[0,1,0]
	v_cvt_scalef32_pk_f32_fp4 v[162:163], v38, 1.0 op_sel:[1,1,0]
	v_cvt_scalef32_pk_f32_fp4 v[164:165], v39, 1.0
	v_cvt_scalef32_pk_f32_fp4 v[166:167], v39, 1.0 op_sel:[1,0,0]
	v_cvt_scalef32_pk_f32_fp4 v[168:169], v39, 1.0 op_sel:[0,1,0]
	v_cvt_scalef32_pk_f32_fp4 v[170:171], v39, 1.0 op_sel:[1,1,0]
	v_pk_fma_f32 v[204:205], v[156:157], s[48:49], v[204:205] op_sel_hi:[1,0,1]
	v_pk_fma_f32 v[206:207], v[158:159], s[48:49], v[206:207] op_sel_hi:[1,0,1]
	v_pk_fma_f32 v[208:209], v[160:161], s[48:49], v[208:209] op_sel_hi:[1,0,1]
	v_pk_fma_f32 v[210:211], v[162:163], s[48:49], v[210:211] op_sel_hi:[1,0,1]
	v_pk_fma_f32 v[212:213], v[164:165], s[48:49], v[212:213] op_sel_hi:[1,0,1]
	v_pk_fma_f32 v[186:187], v[166:167], s[48:49], v[186:187] op_sel_hi:[1,0,1]
	v_pk_fma_f32 v[66:67], v[168:169], s[48:49], v[66:67] op_sel_hi:[1,0,1]
	v_pk_fma_f32 v[68:69], v[170:171], s[48:49], v[68:69] op_sel_hi:[1,0,1]
	s_lshl_b32 s52, s6, 9
	s_add_u32 s58, s100, s52
	s_addc_u32 s59, s101, 0
	global_load_dwordx2 v[38:39], v63, s[58:59]
	s_waitcnt vmcnt(15)
	v_cvt_scalef32_pk_f32_fp4 v[156:157], v40, 1.0
	v_cvt_scalef32_pk_f32_fp4 v[158:159], v40, 1.0 op_sel:[1,0,0]
	v_cvt_scalef32_pk_f32_fp4 v[160:161], v40, 1.0 op_sel:[0,1,0]
	v_cvt_scalef32_pk_f32_fp4 v[162:163], v40, 1.0 op_sel:[1,1,0]
	v_cvt_scalef32_pk_f32_fp4 v[164:165], v41, 1.0
	v_cvt_scalef32_pk_f32_fp4 v[166:167], v41, 1.0 op_sel:[1,0,0]
	v_cvt_scalef32_pk_f32_fp4 v[168:169], v41, 1.0 op_sel:[0,1,0]
	v_cvt_scalef32_pk_f32_fp4 v[170:171], v41, 1.0 op_sel:[1,1,0]
	v_pk_fma_f32 v[204:205], v[156:157], s[46:47], v[204:205] op_sel_hi:[1,0,1]
	v_pk_fma_f32 v[206:207], v[158:159], s[46:47], v[206:207] op_sel_hi:[1,0,1]
	v_pk_fma_f32 v[208:209], v[160:161], s[46:47], v[208:209] op_sel_hi:[1,0,1]
	v_pk_fma_f32 v[210:211], v[162:163], s[46:47], v[210:211] op_sel_hi:[1,0,1]
	v_pk_fma_f32 v[212:213], v[164:165], s[46:47], v[212:213] op_sel_hi:[1,0,1]
	v_pk_fma_f32 v[186:187], v[166:167], s[46:47], v[186:187] op_sel_hi:[1,0,1]
	v_pk_fma_f32 v[66:67], v[168:169], s[46:47], v[66:67] op_sel_hi:[1,0,1]
	v_pk_fma_f32 v[68:69], v[170:171], s[46:47], v[68:69] op_sel_hi:[1,0,1]
	s_lshl_b32 s52, s7, 9
	s_add_u32 s58, s100, s52
	s_addc_u32 s59, s101, 0
	global_load_dwordx2 v[40:41], v63, s[58:59]
	s_waitcnt vmcnt(15)
	v_cvt_scalef32_pk_f32_fp4 v[156:157], v42, 1.0
	v_cvt_scalef32_pk_f32_fp4 v[158:159], v42, 1.0 op_sel:[1,0,0]
	v_cvt_scalef32_pk_f32_fp4 v[160:161], v42, 1.0 op_sel:[0,1,0]
	v_cvt_scalef32_pk_f32_fp4 v[162:163], v42, 1.0 op_sel:[1,1,0]
	v_cvt_scalef32_pk_f32_fp4 v[164:165], v43, 1.0
	v_cvt_scalef32_pk_f32_fp4 v[166:167], v43, 1.0 op_sel:[1,0,0]
	v_cvt_scalef32_pk_f32_fp4 v[168:169], v43, 1.0 op_sel:[0,1,0]
	v_cvt_scalef32_pk_f32_fp4 v[170:171], v43, 1.0 op_sel:[1,1,0]
	v_pk_fma_f32 v[204:205], v[156:157], s[44:45], v[204:205] op_sel_hi:[1,0,1]
	v_pk_fma_f32 v[206:207], v[158:159], s[44:45], v[206:207] op_sel_hi:[1,0,1]
	v_pk_fma_f32 v[208:209], v[160:161], s[44:45], v[208:209] op_sel_hi:[1,0,1]
	v_pk_fma_f32 v[210:211], v[162:163], s[44:45], v[210:211] op_sel_hi:[1,0,1]
	v_pk_fma_f32 v[212:213], v[164:165], s[44:45], v[212:213] op_sel_hi:[1,0,1]
	v_pk_fma_f32 v[186:187], v[166:167], s[44:45], v[186:187] op_sel_hi:[1,0,1]
	v_pk_fma_f32 v[66:67], v[168:169], s[44:45], v[66:67] op_sel_hi:[1,0,1]
	v_pk_fma_f32 v[68:69], v[170:171], s[44:45], v[68:69] op_sel_hi:[1,0,1]
	s_lshl_b32 s52, s8, 9
	s_add_u32 s58, s100, s52
	s_addc_u32 s59, s101, 0
	global_load_dwordx2 v[42:43], v63, s[58:59]
	s_waitcnt vmcnt(15)
	v_cvt_scalef32_pk_f32_fp4 v[156:157], v44, 1.0
	v_cvt_scalef32_pk_f32_fp4 v[158:159], v44, 1.0 op_sel:[1,0,0]
	v_cvt_scalef32_pk_f32_fp4 v[160:161], v44, 1.0 op_sel:[0,1,0]
	v_cvt_scalef32_pk_f32_fp4 v[162:163], v44, 1.0 op_sel:[1,1,0]
	v_cvt_scalef32_pk_f32_fp4 v[164:165], v45, 1.0
	v_cvt_scalef32_pk_f32_fp4 v[166:167], v45, 1.0 op_sel:[1,0,0]
	v_cvt_scalef32_pk_f32_fp4 v[168:169], v45, 1.0 op_sel:[0,1,0]
	v_cvt_scalef32_pk_f32_fp4 v[170:171], v45, 1.0 op_sel:[1,1,0]
	v_pk_fma_f32 v[204:205], v[156:157], s[42:43], v[204:205] op_sel_hi:[1,0,1]
	v_pk_fma_f32 v[206:207], v[158:159], s[42:43], v[206:207] op_sel_hi:[1,0,1]
	v_pk_fma_f32 v[208:209], v[160:161], s[42:43], v[208:209] op_sel_hi:[1,0,1]
	v_pk_fma_f32 v[210:211], v[162:163], s[42:43], v[210:211] op_sel_hi:[1,0,1]
	v_pk_fma_f32 v[212:213], v[164:165], s[42:43], v[212:213] op_sel_hi:[1,0,1]
	v_pk_fma_f32 v[186:187], v[166:167], s[42:43], v[186:187] op_sel_hi:[1,0,1]
	v_pk_fma_f32 v[66:67], v[168:169], s[42:43], v[66:67] op_sel_hi:[1,0,1]
	v_pk_fma_f32 v[68:69], v[170:171], s[42:43], v[68:69] op_sel_hi:[1,0,1]
	s_lshl_b32 s52, s9, 9
	s_add_u32 s58, s100, s52
	s_addc_u32 s59, s101, 0
	global_load_dwordx2 v[44:45], v63, s[58:59]
	s_waitcnt vmcnt(15)
	v_cvt_scalef32_pk_f32_fp4 v[156:157], v46, 1.0
	v_cvt_scalef32_pk_f32_fp4 v[158:159], v46, 1.0 op_sel:[1,0,0]
	v_cvt_scalef32_pk_f32_fp4 v[160:161], v46, 1.0 op_sel:[0,1,0]
	v_cvt_scalef32_pk_f32_fp4 v[162:163], v46, 1.0 op_sel:[1,1,0]
	v_cvt_scalef32_pk_f32_fp4 v[164:165], v47, 1.0
	v_cvt_scalef32_pk_f32_fp4 v[166:167], v47, 1.0 op_sel:[1,0,0]
	v_cvt_scalef32_pk_f32_fp4 v[168:169], v47, 1.0 op_sel:[0,1,0]
	v_cvt_scalef32_pk_f32_fp4 v[170:171], v47, 1.0 op_sel:[1,1,0]
	v_pk_fma_f32 v[204:205], v[156:157], s[40:41], v[204:205] op_sel_hi:[1,0,1]
	v_pk_fma_f32 v[206:207], v[158:159], s[40:41], v[206:207] op_sel_hi:[1,0,1]
	v_pk_fma_f32 v[208:209], v[160:161], s[40:41], v[208:209] op_sel_hi:[1,0,1]
	v_pk_fma_f32 v[210:211], v[162:163], s[40:41], v[210:211] op_sel_hi:[1,0,1]
	v_pk_fma_f32 v[212:213], v[164:165], s[40:41], v[212:213] op_sel_hi:[1,0,1]
	v_pk_fma_f32 v[186:187], v[166:167], s[40:41], v[186:187] op_sel_hi:[1,0,1]
	v_pk_fma_f32 v[66:67], v[168:169], s[40:41], v[66:67] op_sel_hi:[1,0,1]
	v_pk_fma_f32 v[68:69], v[170:171], s[40:41], v[68:69] op_sel_hi:[1,0,1]
	s_lshl_b32 s52, s11, 9
	s_add_u32 s58, s100, s52
	s_addc_u32 s59, s101, 0
	global_load_dwordx2 v[46:47], v63, s[58:59]
	s_waitcnt vmcnt(15)
	v_cvt_scalef32_pk_f32_fp4 v[156:157], v48, 1.0
	v_cvt_scalef32_pk_f32_fp4 v[158:159], v48, 1.0 op_sel:[1,0,0]
	v_cvt_scalef32_pk_f32_fp4 v[160:161], v48, 1.0 op_sel:[0,1,0]
	v_cvt_scalef32_pk_f32_fp4 v[162:163], v48, 1.0 op_sel:[1,1,0]
	v_cvt_scalef32_pk_f32_fp4 v[164:165], v49, 1.0
	v_cvt_scalef32_pk_f32_fp4 v[166:167], v49, 1.0 op_sel:[1,0,0]
	v_cvt_scalef32_pk_f32_fp4 v[168:169], v49, 1.0 op_sel:[0,1,0]
	v_cvt_scalef32_pk_f32_fp4 v[170:171], v49, 1.0 op_sel:[1,1,0]
	v_pk_fma_f32 v[204:205], v[156:157], s[38:39], v[204:205] op_sel_hi:[1,0,1]
	v_pk_fma_f32 v[206:207], v[158:159], s[38:39], v[206:207] op_sel_hi:[1,0,1]
	v_pk_fma_f32 v[208:209], v[160:161], s[38:39], v[208:209] op_sel_hi:[1,0,1]
	v_pk_fma_f32 v[210:211], v[162:163], s[38:39], v[210:211] op_sel_hi:[1,0,1]
	v_pk_fma_f32 v[212:213], v[164:165], s[38:39], v[212:213] op_sel_hi:[1,0,1]
	v_pk_fma_f32 v[186:187], v[166:167], s[38:39], v[186:187] op_sel_hi:[1,0,1]
	v_pk_fma_f32 v[66:67], v[168:169], s[38:39], v[66:67] op_sel_hi:[1,0,1]
	v_pk_fma_f32 v[68:69], v[170:171], s[38:39], v[68:69] op_sel_hi:[1,0,1]
	s_lshl_b32 s52, s13, 9
	s_add_u32 s58, s100, s52
	s_addc_u32 s59, s101, 0
	global_load_dwordx2 v[48:49], v63, s[58:59]
	s_waitcnt vmcnt(15)
	v_cvt_scalef32_pk_f32_fp4 v[156:157], v50, 1.0
	v_cvt_scalef32_pk_f32_fp4 v[158:159], v50, 1.0 op_sel:[1,0,0]
	v_cvt_scalef32_pk_f32_fp4 v[160:161], v50, 1.0 op_sel:[0,1,0]
	v_cvt_scalef32_pk_f32_fp4 v[162:163], v50, 1.0 op_sel:[1,1,0]
	v_cvt_scalef32_pk_f32_fp4 v[164:165], v51, 1.0
	v_cvt_scalef32_pk_f32_fp4 v[166:167], v51, 1.0 op_sel:[1,0,0]
	v_cvt_scalef32_pk_f32_fp4 v[168:169], v51, 1.0 op_sel:[0,1,0]
	v_cvt_scalef32_pk_f32_fp4 v[170:171], v51, 1.0 op_sel:[1,1,0]
	v_pk_fma_f32 v[204:205], v[156:157], s[36:37], v[204:205] op_sel_hi:[1,0,1]
	v_pk_fma_f32 v[206:207], v[158:159], s[36:37], v[206:207] op_sel_hi:[1,0,1]
	v_pk_fma_f32 v[208:209], v[160:161], s[36:37], v[208:209] op_sel_hi:[1,0,1]
	v_pk_fma_f32 v[210:211], v[162:163], s[36:37], v[210:211] op_sel_hi:[1,0,1]
	v_pk_fma_f32 v[212:213], v[164:165], s[36:37], v[212:213] op_sel_hi:[1,0,1]
	v_pk_fma_f32 v[186:187], v[166:167], s[36:37], v[186:187] op_sel_hi:[1,0,1]
	v_pk_fma_f32 v[66:67], v[168:169], s[36:37], v[66:67] op_sel_hi:[1,0,1]
	v_pk_fma_f32 v[68:69], v[170:171], s[36:37], v[68:69] op_sel_hi:[1,0,1]
	s_lshl_b32 s52, s16, 9
	s_add_u32 s58, s100, s52
	s_addc_u32 s59, s101, 0
	global_load_dwordx2 v[50:51], v63, s[58:59]
.Lex_d9:
	v_mov_b32_e32 v52, v56
	v_mov_b32_e32 v53, v57
	v_mov_b32_e32 v54, v58
	v_mov_b32_e32 v55, v59
	s_lshr_b32 s15, s14, 4
	s_add_i32 s4, s4, 1
	s_cmp_lt_u32 s4, 64
	s_cbranch_scc1 .Lex_grp
	s_waitcnt vmcnt(0)
	s_lshl_b32 s10, s12, 2
	v_add_u32_e32 v64, s10, v79
	v_ashrrev_i32_e32 v65, 31, v64
	v_lshl_add_u64 v[64:65], s[28:29], 0, v[64:65]
	v_lshlrev_b64 v[0:1], 11, v[64:65]
	v_lshl_add_u64 v[0:1], v[80:81], 0, v[0:1]
	global_load_dwordx4 v[160:163], v[0:1], off offset:16
	global_load_dwordx4 v[156:159], v[0:1], off
	v_mov_b32_e32 v134, v108
	v_mov_b32_e32 v135, v109
	v_mov_b32_e32 v150, v110
	v_mov_b32_e32 v151, v111
	v_mov_b32_e32 v148, v112
	v_mov_b32_e32 v149, v113
	v_mov_b32_e32 v146, v114
	v_mov_b32_e32 v147, v115
	v_mov_b32_e32 v144, v116
	v_mov_b32_e32 v145, v117
	v_mov_b32_e32 v142, v118
	v_mov_b32_e32 v143, v119
	v_mov_b32_e32 v152, v120
	v_mov_b32_e32 v153, v121
	v_mov_b32_e32 v154, v122
	v_mov_b32_e32 v155, v123
	s_waitcnt vmcnt(0)
	v_lshlrev_b32_e32 v96, 16, v156
	v_and_b32_e32 v97, 0xffff0000, v156
	v_lshlrev_b32_e32 v92, 16, v160
	v_and_b32_e32 v93, 0xffff0000, v160
	v_lshlrev_b32_e32 v98, 16, v157
	v_and_b32_e32 v99, 0xffff0000, v157
	v_lshlrev_b32_e32 v94, 16, v161
	v_and_b32_e32 v95, 0xffff0000, v161
	v_lshlrev_b32_e32 v100, 16, v158
	v_and_b32_e32 v101, 0xffff0000, v158
	v_lshlrev_b32_e32 v104, 16, v162
	v_and_b32_e32 v105, 0xffff0000, v162
	v_lshlrev_b32_e32 v102, 16, v159
	v_and_b32_e32 v103, 0xffff0000, v159
	v_lshlrev_b32_e32 v106, 16, v163
	v_and_b32_e32 v107, 0xffff0000, v163
	v_lshlrev_b64 v[0:1], 10, v[64:65]
	global_load_dwordx4 v[4:7], v[88:89], off
	global_load_dwordx4 v[8:11], v[90:91], off
	v_pk_fma_f32 v[16:17], v[96:97], s[26:27], v[134:135] op_sel_hi:[1,0,1]
	v_pk_fma_f32 v[18:19], v[98:99], s[26:27], v[150:151] op_sel_hi:[1,0,1]
	v_add_f32_e32 v2, 0, v16
	v_add_f32_e32 v2, v17, v2
	v_add_f32_e32 v2, v18, v2
	v_add_f32_e32 v2, v19, v2
	v_pk_fma_f32 v[20:21], v[100:101], s[26:27], v[148:149] op_sel_hi:[1,0,1]
	v_pk_fma_f32 v[22:23], v[102:103], s[26:27], v[146:147] op_sel_hi:[1,0,1]
	v_add_f32_e32 v2, v20, v2
	v_add_f32_e32 v2, v21, v2
	v_add_f32_e32 v2, v22, v2
	v_add_f32_e32 v2, v23, v2
	v_pk_fma_f32 v[24:25], v[92:93], s[26:27], v[144:145] op_sel_hi:[1,0,1]
	v_pk_fma_f32 v[26:27], v[94:95], s[26:27], v[142:143] op_sel_hi:[1,0,1]
	v_add_f32_e32 v2, v24, v2
	v_add_f32_e32 v2, v25, v2
	v_add_f32_e32 v2, v26, v2
	v_pk_fma_f32 v[12:13], v[104:105], s[26:27], v[152:153] op_sel_hi:[1,0,1]
	v_add_f32_e32 v2, v27, v2
	v_add_f32_e32 v2, v12, v2
	v_pk_fma_f32 v[14:15], v[106:107], s[26:27], v[154:155] op_sel_hi:[1,0,1]
	v_add_f32_e32 v2, v13, v2
	v_add_f32_e32 v2, v14, v2
	v_add_f32_e32 v2, v15, v2
	v_mov_b32_e32 v28, 0
	v_lshl_add_u64 v[0:1], v[0:1], 2, v[86:87]
	v_add_f32_dpp v2, v2, v2 quad_perm:[1,0,3,2] row_mask:0xf bank_mask:0xf bound_ctrl:1
	s_nop 0
	s_nop 0
	v_add_f32_dpp v2, v2, v2 quad_perm:[2,3,0,1] row_mask:0xf bank_mask:0xf bound_ctrl:1
	s_nop 0
	s_nop 0
	v_add_f32_dpp v2, v2, v2 row_half_mirror row_mask:0xf bank_mask:0xf bound_ctrl:1
	s_nop 1
	v_add_f32_dpp v2, v2, v2 row_mirror row_mask:0xf bank_mask:0xf bound_ctrl:1
	s_nop 1
	v_mov_b32_dpp v28, v2 row_bcast:15 row_mask:0xa bank_mask:0xf
	v_add_f32_e32 v2, v2, v28
	v_mov_b32_e32 v28, 0
	s_nop 1
	v_mov_b32_dpp v28, v2 row_bcast:31 row_mask:0xc bank_mask:0xf
	v_add_f32_e32 v2, v2, v28
	s_nop 0
	v_readlane_b32 s34, v2, 63
	s_nop 1
	v_mul_f32_e32 v2, s34, v180
	v_pk_add_f32 v[16:17], v[16:17], v[2:3] op_sel_hi:[1,0] neg_lo:[0,1] neg_hi:[0,1]
	v_pk_add_f32 v[18:19], v[18:19], v[2:3] op_sel_hi:[1,0] neg_lo:[0,1] neg_hi:[0,1]
	v_pk_mul_f32 v[28:29], v[16:17], v[16:17]
	v_pk_mul_f32 v[30:31], v[18:19], v[18:19]
	v_pk_add_f32 v[20:21], v[20:21], v[2:3] op_sel_hi:[1,0] neg_lo:[0,1] neg_hi:[0,1]
	v_pk_add_f32 v[22:23], v[22:23], v[2:3] op_sel_hi:[1,0] neg_lo:[0,1] neg_hi:[0,1]
	v_pk_add_f32 v[24:25], v[24:25], v[2:3] op_sel_hi:[1,0] neg_lo:[0,1] neg_hi:[0,1]
	v_pk_add_f32 v[26:27], v[26:27], v[2:3] op_sel_hi:[1,0] neg_lo:[0,1] neg_hi:[0,1]
	v_pk_add_f32 v[12:13], v[12:13], v[2:3] op_sel_hi:[1,0] neg_lo:[0,1] neg_hi:[0,1]
	v_pk_add_f32 v[14:15], v[14:15], v[2:3] op_sel_hi:[1,0] neg_lo:[0,1] neg_hi:[0,1]
	v_add_f32_e32 v2, v28, v29
	v_add_f32_e32 v2, v30, v2
	v_pk_mul_f32 v[32:33], v[20:21], v[20:21]
	v_add_f32_e32 v2, v31, v2
	v_add_f32_e32 v2, v32, v2
	v_pk_mul_f32 v[34:35], v[22:23], v[22:23]
	v_add_f32_e32 v2, v33, v2
	v_add_f32_e32 v2, v34, v2
	v_pk_mul_f32 v[36:37], v[24:25], v[24:25]
	v_add_f32_e32 v2, v35, v2
	v_add_f32_e32 v2, v36, v2
	v_pk_mul_f32 v[38:39], v[26:27], v[26:27]
	v_add_f32_e32 v2, v37, v2
	v_add_f32_e32 v2, v38, v2
	v_pk_mul_f32 v[40:41], v[12:13], v[12:13]
	v_add_f32_e32 v2, v39, v2
	v_add_f32_e32 v2, v40, v2
	v_pk_mul_f32 v[42:43], v[14:15], v[14:15]
	v_add_f32_e32 v2, v41, v2
	v_add_f32_e32 v2, v42, v2
	v_add_f32_e32 v2, v43, v2
	v_mov_b32_e32 v28, 0
	s_nop 0
	v_add_f32_dpp v2, v2, v2 quad_perm:[1,0,3,2] row_mask:0xf bank_mask:0xf bound_ctrl:1
	s_nop 1
	v_add_f32_dpp v2, v2, v2 quad_perm:[2,3,0,1] row_mask:0xf bank_mask:0xf bound_ctrl:1
	s_nop 1
	v_add_f32_dpp v2, v2, v2 row_half_mirror row_mask:0xf bank_mask:0xf bound_ctrl:1
	s_nop 1
	v_add_f32_dpp v2, v2, v2 row_mirror row_mask:0xf bank_mask:0xf bound_ctrl:1
	s_nop 1
	v_mov_b32_dpp v28, v2 row_bcast:15 row_mask:0xa bank_mask:0xf
	v_add_f32_e32 v2, v2, v28
	v_mov_b32_e32 v28, 0
	s_nop 1
	v_mov_b32_dpp v28, v2 row_bcast:31 row_mask:0xc bank_mask:0xf
	v_add_f32_e32 v2, v2, v28
	s_nop 0
	v_readlane_b32 s34, v2, 63
	s_nop 1
	v_fma_f32 v2, s34, v180, v177
	v_mul_f32_e32 v28, 0x4b800000, v2
	v_cmp_gt_f32_e32 vcc, s49, v2
	s_nop 1
	v_cndmask_b32_e32 v2, v2, v28, vcc
	v_rsq_f32_e32 v2, v2
	s_nop 0
	v_mul_f32_e32 v28, 0x45800000, v2
	v_cndmask_b32_e32 v2, v2, v28, vcc
	v_pk_mul_f32 v[16:17], v[16:17], v[2:3] op_sel_hi:[1,0]
	v_pk_mul_f32 v[18:19], v[18:19], v[2:3] op_sel_hi:[1,0]
	s_waitcnt vmcnt(0)
	v_pk_fma_f32 v[4:5], v[4:5], v[16:17], v[8:9]
	v_pk_fma_f32 v[6:7], v[6:7], v[18:19], v[10:11]
	global_store_dwordx4 v[0:1], v[4:7], off
	global_load_dwordx4 v[4:7], v[88:89], off offset:16
	s_nop 0
	global_load_dwordx4 v[8:11], v[90:91], off offset:16
	v_pk_mul_f32 v[16:17], v[22:23], v[2:3] op_sel_hi:[1,0]
	v_pk_mul_f32 v[18:19], v[20:21], v[2:3] op_sel_hi:[1,0]
	v_pk_mul_f32 v[14:15], v[14:15], v[2:3] op_sel_hi:[1,0]
	v_pk_mul_f32 v[12:13], v[12:13], v[2:3] op_sel_hi:[1,0]
	s_waitcnt vmcnt(0)
	v_pk_fma_f32 v[4:5], v[4:5], v[18:19], v[8:9]
	v_pk_fma_f32 v[6:7], v[6:7], v[16:17], v[10:11]
	global_store_dwordx4 v[0:1], v[4:7], off offset:16
	global_load_dwordx4 v[4:7], v[88:89], off offset:32
	s_nop 0
	global_load_dwordx4 v[8:11], v[90:91], off offset:32
	v_pk_mul_f32 v[16:17], v[26:27], v[2:3] op_sel_hi:[1,0]
	v_pk_mul_f32 v[18:19], v[24:25], v[2:3] op_sel_hi:[1,0]
	s_waitcnt vmcnt(0)
	v_pk_fma_f32 v[6:7], v[6:7], v[16:17], v[10:11]
	v_pk_fma_f32 v[4:5], v[4:5], v[18:19], v[8:9]
	global_store_dwordx4 v[0:1], v[4:7], off offset:32
	global_load_dwordx4 v[4:7], v[88:89], off offset:48
	s_nop 0
	global_load_dwordx4 v[8:11], v[90:91], off offset:48
	s_waitcnt vmcnt(0)
	v_pk_fma_f32 v[4:5], v[12:13], v[4:5], v[8:9]
	v_pk_fma_f32 v[6:7], v[14:15], v[6:7], v[10:11]
	global_store_dwordx4 v[0:1], v[4:7], off offset:48
	s_lshl_b32 s10, s12, 2
	s_add_i32 s10, s10, 1
	v_add_u32_e32 v64, s10, v79
	v_ashrrev_i32_e32 v65, 31, v64
	v_lshl_add_u64 v[64:65], s[28:29], 0, v[64:65]
	v_lshlrev_b64 v[0:1], 11, v[64:65]
	v_lshl_add_u64 v[0:1], v[80:81], 0, v[0:1]
	global_load_dwordx4 v[160:163], v[0:1], off offset:16
	global_load_dwordx4 v[156:159], v[0:1], off
	v_mov_b32_e32 v134, v124
	v_mov_b32_e32 v135, v125
	v_mov_b32_e32 v150, v126
	v_mov_b32_e32 v151, v127
	v_mov_b32_e32 v148, v128
	v_mov_b32_e32 v149, v129
	v_mov_b32_e32 v146, v130
	v_mov_b32_e32 v147, v131
	v_mov_b32_e32 v144, v132
	v_mov_b32_e32 v145, v133
	v_mov_b32_e32 v142, v136
	v_mov_b32_e32 v143, v137
	v_mov_b32_e32 v152, v138
	v_mov_b32_e32 v153, v139
	v_mov_b32_e32 v154, v140
	v_mov_b32_e32 v155, v141
	s_waitcnt vmcnt(0)
	v_lshlrev_b32_e32 v96, 16, v156
	v_and_b32_e32 v97, 0xffff0000, v156
	v_lshlrev_b32_e32 v92, 16, v160
	v_and_b32_e32 v93, 0xffff0000, v160
	v_lshlrev_b32_e32 v98, 16, v157
	v_and_b32_e32 v99, 0xffff0000, v157
	v_lshlrev_b32_e32 v94, 16, v161
	v_and_b32_e32 v95, 0xffff0000, v161
	v_lshlrev_b32_e32 v100, 16, v158
	v_and_b32_e32 v101, 0xffff0000, v158
	v_lshlrev_b32_e32 v104, 16, v162
	v_and_b32_e32 v105, 0xffff0000, v162
	v_lshlrev_b32_e32 v102, 16, v159
	v_and_b32_e32 v103, 0xffff0000, v159
	v_lshlrev_b32_e32 v106, 16, v163
	v_and_b32_e32 v107, 0xffff0000, v163
	v_lshlrev_b64 v[0:1], 10, v[64:65]
	global_load_dwordx4 v[4:7], v[88:89], off
	global_load_dwordx4 v[8:11], v[90:91], off
	v_pk_fma_f32 v[16:17], v[96:97], s[26:27], v[134:135] op_sel_hi:[1,0,1]
	v_pk_fma_f32 v[18:19], v[98:99], s[26:27], v[150:151] op_sel_hi:[1,0,1]
	v_add_f32_e32 v2, 0, v16
	v_add_f32_e32 v2, v17, v2
	v_add_f32_e32 v2, v18, v2
	v_add_f32_e32 v2, v19, v2
	v_pk_fma_f32 v[20:21], v[100:101], s[26:27], v[148:149] op_sel_hi:[1,0,1]
	v_pk_fma_f32 v[22:23], v[102:103], s[26:27], v[146:147] op_sel_hi:[1,0,1]
	v_add_f32_e32 v2, v20, v2
	v_add_f32_e32 v2, v21, v2
	v_add_f32_e32 v2, v22, v2
	v_add_f32_e32 v2, v23, v2
	v_pk_fma_f32 v[24:25], v[92:93], s[26:27], v[144:145] op_sel_hi:[1,0,1]
	v_pk_fma_f32 v[26:27], v[94:95], s[26:27], v[142:143] op_sel_hi:[1,0,1]
	v_add_f32_e32 v2, v24, v2
	v_add_f32_e32 v2, v25, v2
	v_add_f32_e32 v2, v26, v2
	v_pk_fma_f32 v[12:13], v[104:105], s[26:27], v[152:153] op_sel_hi:[1,0,1]
	v_add_f32_e32 v2, v27, v2
	v_add_f32_e32 v2, v12, v2
	v_pk_fma_f32 v[14:15], v[106:107], s[26:27], v[154:155] op_sel_hi:[1,0,1]
	v_add_f32_e32 v2, v13, v2
	v_add_f32_e32 v2, v14, v2
	v_add_f32_e32 v2, v15, v2
	v_mov_b32_e32 v28, 0
	v_lshl_add_u64 v[0:1], v[0:1], 2, v[86:87]
	v_add_f32_dpp v2, v2, v2 quad_perm:[1,0,3,2] row_mask:0xf bank_mask:0xf bound_ctrl:1
	s_nop 0
	s_nop 0
	v_add_f32_dpp v2, v2, v2 quad_perm:[2,3,0,1] row_mask:0xf bank_mask:0xf bound_ctrl:1
	s_nop 0
	s_nop 0
	v_add_f32_dpp v2, v2, v2 row_half_mirror row_mask:0xf bank_mask:0xf bound_ctrl:1
	s_nop 1
	v_add_f32_dpp v2, v2, v2 row_mirror row_mask:0xf bank_mask:0xf bound_ctrl:1
	s_nop 1
	v_mov_b32_dpp v28, v2 row_bcast:15 row_mask:0xa bank_mask:0xf
	v_add_f32_e32 v2, v2, v28
	v_mov_b32_e32 v28, 0
	s_nop 1
	v_mov_b32_dpp v28, v2 row_bcast:31 row_mask:0xc bank_mask:0xf
	v_add_f32_e32 v2, v2, v28
	s_nop 0
	v_readlane_b32 s34, v2, 63
	s_nop 1
	v_mul_f32_e32 v2, s34, v180
	v_pk_add_f32 v[16:17], v[16:17], v[2:3] op_sel_hi:[1,0] neg_lo:[0,1] neg_hi:[0,1]
	v_pk_add_f32 v[18:19], v[18:19], v[2:3] op_sel_hi:[1,0] neg_lo:[0,1] neg_hi:[0,1]
	v_pk_mul_f32 v[28:29], v[16:17], v[16:17]
	v_pk_mul_f32 v[30:31], v[18:19], v[18:19]
	v_pk_add_f32 v[20:21], v[20:21], v[2:3] op_sel_hi:[1,0] neg_lo:[0,1] neg_hi:[0,1]
	v_pk_add_f32 v[22:23], v[22:23], v[2:3] op_sel_hi:[1,0] neg_lo:[0,1] neg_hi:[0,1]
	v_pk_add_f32 v[24:25], v[24:25], v[2:3] op_sel_hi:[1,0] neg_lo:[0,1] neg_hi:[0,1]
	v_pk_add_f32 v[26:27], v[26:27], v[2:3] op_sel_hi:[1,0] neg_lo:[0,1] neg_hi:[0,1]
	v_pk_add_f32 v[12:13], v[12:13], v[2:3] op_sel_hi:[1,0] neg_lo:[0,1] neg_hi:[0,1]
	v_pk_add_f32 v[14:15], v[14:15], v[2:3] op_sel_hi:[1,0] neg_lo:[0,1] neg_hi:[0,1]
	v_add_f32_e32 v2, v28, v29
	v_add_f32_e32 v2, v30, v2
	v_pk_mul_f32 v[32:33], v[20:21], v[20:21]
	v_add_f32_e32 v2, v31, v2
	v_add_f32_e32 v2, v32, v2
	v_pk_mul_f32 v[34:35], v[22:23], v[22:23]
	v_add_f32_e32 v2, v33, v2
	v_add_f32_e32 v2, v34, v2
	v_pk_mul_f32 v[36:37], v[24:25], v[24:25]
	v_add_f32_e32 v2, v35, v2
	v_add_f32_e32 v2, v36, v2
	v_pk_mul_f32 v[38:39], v[26:27], v[26:27]
	v_add_f32_e32 v2, v37, v2
	v_add_f32_e32 v2, v38, v2
	v_pk_mul_f32 v[40:41], v[12:13], v[12:13]
	v_add_f32_e32 v2, v39, v2
	v_add_f32_e32 v2, v40, v2
	v_pk_mul_f32 v[42:43], v[14:15], v[14:15]
	v_add_f32_e32 v2, v41, v2
	v_add_f32_e32 v2, v42, v2
	v_add_f32_e32 v2, v43, v2
	v_mov_b32_e32 v28, 0
	s_nop 0
	v_add_f32_dpp v2, v2, v2 quad_perm:[1,0,3,2] row_mask:0xf bank_mask:0xf bound_ctrl:1
	s_nop 1
	v_add_f32_dpp v2, v2, v2 quad_perm:[2,3,0,1] row_mask:0xf bank_mask:0xf bound_ctrl:1
	s_nop 1
	v_add_f32_dpp v2, v2, v2 row_half_mirror row_mask:0xf bank_mask:0xf bound_ctrl:1
	s_nop 1
	v_add_f32_dpp v2, v2, v2 row_mirror row_mask:0xf bank_mask:0xf bound_ctrl:1
	s_nop 1
	v_mov_b32_dpp v28, v2 row_bcast:15 row_mask:0xa bank_mask:0xf
	v_add_f32_e32 v2, v2, v28
	v_mov_b32_e32 v28, 0
	s_nop 1
	v_mov_b32_dpp v28, v2 row_bcast:31 row_mask:0xc bank_mask:0xf
	v_add_f32_e32 v2, v2, v28
	s_nop 0
	v_readlane_b32 s34, v2, 63
	s_nop 1
	v_fma_f32 v2, s34, v180, v177
	v_mul_f32_e32 v28, 0x4b800000, v2
	v_cmp_gt_f32_e32 vcc, s49, v2
	s_nop 1
	v_cndmask_b32_e32 v2, v2, v28, vcc
	v_rsq_f32_e32 v2, v2
	s_nop 0
	v_mul_f32_e32 v28, 0x45800000, v2
	v_cndmask_b32_e32 v2, v2, v28, vcc
	v_pk_mul_f32 v[16:17], v[16:17], v[2:3] op_sel_hi:[1,0]
	v_pk_mul_f32 v[18:19], v[18:19], v[2:3] op_sel_hi:[1,0]
	s_waitcnt vmcnt(0)
	v_pk_fma_f32 v[4:5], v[4:5], v[16:17], v[8:9]
	v_pk_fma_f32 v[6:7], v[6:7], v[18:19], v[10:11]
	global_store_dwordx4 v[0:1], v[4:7], off
	global_load_dwordx4 v[4:7], v[88:89], off offset:16
	s_nop 0
	global_load_dwordx4 v[8:11], v[90:91], off offset:16
	v_pk_mul_f32 v[16:17], v[22:23], v[2:3] op_sel_hi:[1,0]
	v_pk_mul_f32 v[18:19], v[20:21], v[2:3] op_sel_hi:[1,0]
	v_pk_mul_f32 v[14:15], v[14:15], v[2:3] op_sel_hi:[1,0]
	v_pk_mul_f32 v[12:13], v[12:13], v[2:3] op_sel_hi:[1,0]
	s_waitcnt vmcnt(0)
	v_pk_fma_f32 v[4:5], v[4:5], v[18:19], v[8:9]
	v_pk_fma_f32 v[6:7], v[6:7], v[16:17], v[10:11]
	global_store_dwordx4 v[0:1], v[4:7], off offset:16
	global_load_dwordx4 v[4:7], v[88:89], off offset:32
	s_nop 0
	global_load_dwordx4 v[8:11], v[90:91], off offset:32
	v_pk_mul_f32 v[16:17], v[26:27], v[2:3] op_sel_hi:[1,0]
	v_pk_mul_f32 v[18:19], v[24:25], v[2:3] op_sel_hi:[1,0]
	s_waitcnt vmcnt(0)
	v_pk_fma_f32 v[6:7], v[6:7], v[16:17], v[10:11]
	v_pk_fma_f32 v[4:5], v[4:5], v[18:19], v[8:9]
	global_store_dwordx4 v[0:1], v[4:7], off offset:32
	global_load_dwordx4 v[4:7], v[88:89], off offset:48
	s_nop 0
	global_load_dwordx4 v[8:11], v[90:91], off offset:48
	s_waitcnt vmcnt(0)
	v_pk_fma_f32 v[4:5], v[12:13], v[4:5], v[8:9]
	v_pk_fma_f32 v[6:7], v[14:15], v[6:7], v[10:11]
	global_store_dwordx4 v[0:1], v[4:7], off offset:48
	s_lshl_b32 s10, s12, 2
	s_add_i32 s10, s10, 2
	v_add_u32_e32 v64, s10, v79
	v_ashrrev_i32_e32 v65, 31, v64
	v_lshl_add_u64 v[64:65], s[28:29], 0, v[64:65]
	v_lshlrev_b64 v[0:1], 11, v[64:65]
	v_lshl_add_u64 v[0:1], v[80:81], 0, v[0:1]
	global_load_dwordx4 v[160:163], v[0:1], off offset:16
	global_load_dwordx4 v[156:159], v[0:1], off
	v_mov_b32_e32 v134, v188
	v_mov_b32_e32 v135, v189
	v_mov_b32_e32 v150, v190
	v_mov_b32_e32 v151, v191
	v_mov_b32_e32 v148, v192
	v_mov_b32_e32 v149, v193
	v_mov_b32_e32 v146, v194
	v_mov_b32_e32 v147, v195
	v_mov_b32_e32 v144, v196
	v_mov_b32_e32 v145, v197
	v_mov_b32_e32 v142, v198
	v_mov_b32_e32 v143, v199
	v_mov_b32_e32 v152, v200
	v_mov_b32_e32 v153, v201
	v_mov_b32_e32 v154, v202
	v_mov_b32_e32 v155, v203
	s_waitcnt vmcnt(0)
	v_lshlrev_b32_e32 v96, 16, v156
	v_and_b32_e32 v97, 0xffff0000, v156
	v_lshlrev_b32_e32 v92, 16, v160
	v_and_b32_e32 v93, 0xffff0000, v160
	v_lshlrev_b32_e32 v98, 16, v157
	v_and_b32_e32 v99, 0xffff0000, v157
	v_lshlrev_b32_e32 v94, 16, v161
	v_and_b32_e32 v95, 0xffff0000, v161
	v_lshlrev_b32_e32 v100, 16, v158
	v_and_b32_e32 v101, 0xffff0000, v158
	v_lshlrev_b32_e32 v104, 16, v162
	v_and_b32_e32 v105, 0xffff0000, v162
	v_lshlrev_b32_e32 v102, 16, v159
	v_and_b32_e32 v103, 0xffff0000, v159
	v_lshlrev_b32_e32 v106, 16, v163
	v_and_b32_e32 v107, 0xffff0000, v163
	v_lshlrev_b64 v[0:1], 10, v[64:65]
	global_load_dwordx4 v[4:7], v[88:89], off
	global_load_dwordx4 v[8:11], v[90:91], off
	v_pk_fma_f32 v[16:17], v[96:97], s[26:27], v[134:135] op_sel_hi:[1,0,1]
	v_pk_fma_f32 v[18:19], v[98:99], s[26:27], v[150:151] op_sel_hi:[1,0,1]
	v_add_f32_e32 v2, 0, v16
	v_add_f32_e32 v2, v17, v2
	v_add_f32_e32 v2, v18, v2
	v_add_f32_e32 v2, v19, v2
	v_pk_fma_f32 v[20:21], v[100:101], s[26:27], v[148:149] op_sel_hi:[1,0,1]
	v_pk_fma_f32 v[22:23], v[102:103], s[26:27], v[146:147] op_sel_hi:[1,0,1]
	v_add_f32_e32 v2, v20, v2
	v_add_f32_e32 v2, v21, v2
	v_add_f32_e32 v2, v22, v2
	v_add_f32_e32 v2, v23, v2
	v_pk_fma_f32 v[24:25], v[92:93], s[26:27], v[144:145] op_sel_hi:[1,0,1]
	v_pk_fma_f32 v[26:27], v[94:95], s[26:27], v[142:143] op_sel_hi:[1,0,1]
	v_add_f32_e32 v2, v24, v2
	v_add_f32_e32 v2, v25, v2
	v_add_f32_e32 v2, v26, v2
	v_pk_fma_f32 v[12:13], v[104:105], s[26:27], v[152:153] op_sel_hi:[1,0,1]
	v_add_f32_e32 v2, v27, v2
	v_add_f32_e32 v2, v12, v2
	v_pk_fma_f32 v[14:15], v[106:107], s[26:27], v[154:155] op_sel_hi:[1,0,1]
	v_add_f32_e32 v2, v13, v2
	v_add_f32_e32 v2, v14, v2
	v_add_f32_e32 v2, v15, v2
	v_mov_b32_e32 v28, 0
	v_lshl_add_u64 v[0:1], v[0:1], 2, v[86:87]
	v_add_f32_dpp v2, v2, v2 quad_perm:[1,0,3,2] row_mask:0xf bank_mask:0xf bound_ctrl:1
	s_nop 0
	s_nop 0
	v_add_f32_dpp v2, v2, v2 quad_perm:[2,3,0,1] row_mask:0xf bank_mask:0xf bound_ctrl:1
	s_nop 0
	s_nop 0
	v_add_f32_dpp v2, v2, v2 row_half_mirror row_mask:0xf bank_mask:0xf bound_ctrl:1
	s_nop 1
	v_add_f32_dpp v2, v2, v2 row_mirror row_mask:0xf bank_mask:0xf bound_ctrl:1
	s_nop 1
	v_mov_b32_dpp v28, v2 row_bcast:15 row_mask:0xa bank_mask:0xf
	v_add_f32_e32 v2, v2, v28
	v_mov_b32_e32 v28, 0
	s_nop 1
	v_mov_b32_dpp v28, v2 row_bcast:31 row_mask:0xc bank_mask:0xf
	v_add_f32_e32 v2, v2, v28
	s_nop 0
	v_readlane_b32 s34, v2, 63
	s_nop 1
	v_mul_f32_e32 v2, s34, v180
	v_pk_add_f32 v[16:17], v[16:17], v[2:3] op_sel_hi:[1,0] neg_lo:[0,1] neg_hi:[0,1]
	v_pk_add_f32 v[18:19], v[18:19], v[2:3] op_sel_hi:[1,0] neg_lo:[0,1] neg_hi:[0,1]
	v_pk_mul_f32 v[28:29], v[16:17], v[16:17]
	v_pk_mul_f32 v[30:31], v[18:19], v[18:19]
	v_pk_add_f32 v[20:21], v[20:21], v[2:3] op_sel_hi:[1,0] neg_lo:[0,1] neg_hi:[0,1]
	v_pk_add_f32 v[22:23], v[22:23], v[2:3] op_sel_hi:[1,0] neg_lo:[0,1] neg_hi:[0,1]
	v_pk_add_f32 v[24:25], v[24:25], v[2:3] op_sel_hi:[1,0] neg_lo:[0,1] neg_hi:[0,1]
	v_pk_add_f32 v[26:27], v[26:27], v[2:3] op_sel_hi:[1,0] neg_lo:[0,1] neg_hi:[0,1]
	v_pk_add_f32 v[12:13], v[12:13], v[2:3] op_sel_hi:[1,0] neg_lo:[0,1] neg_hi:[0,1]
	v_pk_add_f32 v[14:15], v[14:15], v[2:3] op_sel_hi:[1,0] neg_lo:[0,1] neg_hi:[0,1]
	v_add_f32_e32 v2, v28, v29
	v_add_f32_e32 v2, v30, v2
	v_pk_mul_f32 v[32:33], v[20:21], v[20:21]
	v_add_f32_e32 v2, v31, v2
	v_add_f32_e32 v2, v32, v2
	v_pk_mul_f32 v[34:35], v[22:23], v[22:23]
	v_add_f32_e32 v2, v33, v2
	v_add_f32_e32 v2, v34, v2
	v_pk_mul_f32 v[36:37], v[24:25], v[24:25]
	v_add_f32_e32 v2, v35, v2
	v_add_f32_e32 v2, v36, v2
	v_pk_mul_f32 v[38:39], v[26:27], v[26:27]
	v_add_f32_e32 v2, v37, v2
	v_add_f32_e32 v2, v38, v2
	v_pk_mul_f32 v[40:41], v[12:13], v[12:13]
	v_add_f32_e32 v2, v39, v2
	v_add_f32_e32 v2, v40, v2
	v_pk_mul_f32 v[42:43], v[14:15], v[14:15]
	v_add_f32_e32 v2, v41, v2
	v_add_f32_e32 v2, v42, v2
	v_add_f32_e32 v2, v43, v2
	v_mov_b32_e32 v28, 0
	s_nop 0
	v_add_f32_dpp v2, v2, v2 quad_perm:[1,0,3,2] row_mask:0xf bank_mask:0xf bound_ctrl:1
	s_nop 1
	v_add_f32_dpp v2, v2, v2 quad_perm:[2,3,0,1] row_mask:0xf bank_mask:0xf bound_ctrl:1
	s_nop 1
	v_add_f32_dpp v2, v2, v2 row_half_mirror row_mask:0xf bank_mask:0xf bound_ctrl:1
	s_nop 1
	v_add_f32_dpp v2, v2, v2 row_mirror row_mask:0xf bank_mask:0xf bound_ctrl:1
	s_nop 1
	v_mov_b32_dpp v28, v2 row_bcast:15 row_mask:0xa bank_mask:0xf
	v_add_f32_e32 v2, v2, v28
	v_mov_b32_e32 v28, 0
	s_nop 1
	v_mov_b32_dpp v28, v2 row_bcast:31 row_mask:0xc bank_mask:0xf
	v_add_f32_e32 v2, v2, v28
	s_nop 0
	v_readlane_b32 s34, v2, 63
	s_nop 1
	v_fma_f32 v2, s34, v180, v177
	v_mul_f32_e32 v28, 0x4b800000, v2
	v_cmp_gt_f32_e32 vcc, s49, v2
	s_nop 1
	v_cndmask_b32_e32 v2, v2, v28, vcc
	v_rsq_f32_e32 v2, v2
	s_nop 0
	v_mul_f32_e32 v28, 0x45800000, v2
	v_cndmask_b32_e32 v2, v2, v28, vcc
	v_pk_mul_f32 v[16:17], v[16:17], v[2:3] op_sel_hi:[1,0]
	v_pk_mul_f32 v[18:19], v[18:19], v[2:3] op_sel_hi:[1,0]
	s_waitcnt vmcnt(0)
	v_pk_fma_f32 v[4:5], v[4:5], v[16:17], v[8:9]
	v_pk_fma_f32 v[6:7], v[6:7], v[18:19], v[10:11]
	global_store_dwordx4 v[0:1], v[4:7], off
	global_load_dwordx4 v[4:7], v[88:89], off offset:16
	s_nop 0
	global_load_dwordx4 v[8:11], v[90:91], off offset:16
	v_pk_mul_f32 v[16:17], v[22:23], v[2:3] op_sel_hi:[1,0]
	v_pk_mul_f32 v[18:19], v[20:21], v[2:3] op_sel_hi:[1,0]
	v_pk_mul_f32 v[14:15], v[14:15], v[2:3] op_sel_hi:[1,0]
	v_pk_mul_f32 v[12:13], v[12:13], v[2:3] op_sel_hi:[1,0]
	s_waitcnt vmcnt(0)
	v_pk_fma_f32 v[4:5], v[4:5], v[18:19], v[8:9]
	v_pk_fma_f32 v[6:7], v[6:7], v[16:17], v[10:11]
	global_store_dwordx4 v[0:1], v[4:7], off offset:16
	global_load_dwordx4 v[4:7], v[88:89], off offset:32
	s_nop 0
	global_load_dwordx4 v[8:11], v[90:91], off offset:32
	v_pk_mul_f32 v[16:17], v[26:27], v[2:3] op_sel_hi:[1,0]
	v_pk_mul_f32 v[18:19], v[24:25], v[2:3] op_sel_hi:[1,0]
	s_waitcnt vmcnt(0)
	v_pk_fma_f32 v[6:7], v[6:7], v[16:17], v[10:11]
	v_pk_fma_f32 v[4:5], v[4:5], v[18:19], v[8:9]
	global_store_dwordx4 v[0:1], v[4:7], off offset:32
	global_load_dwordx4 v[4:7], v[88:89], off offset:48
	s_nop 0
	global_load_dwordx4 v[8:11], v[90:91], off offset:48
	s_waitcnt vmcnt(0)
	v_pk_fma_f32 v[4:5], v[12:13], v[4:5], v[8:9]
	v_pk_fma_f32 v[6:7], v[14:15], v[6:7], v[10:11]
	global_store_dwordx4 v[0:1], v[4:7], off offset:48
	s_lshl_b32 s10, s12, 2
	s_add_i32 s10, s10, 3
	v_add_u32_e32 v64, s10, v79
	v_ashrrev_i32_e32 v65, 31, v64
	v_lshl_add_u64 v[64:65], s[28:29], 0, v[64:65]
	v_lshlrev_b64 v[0:1], 11, v[64:65]
	v_lshl_add_u64 v[0:1], v[80:81], 0, v[0:1]
	global_load_dwordx4 v[160:163], v[0:1], off offset:16
	global_load_dwordx4 v[156:159], v[0:1], off
	v_mov_b32_e32 v134, v204
	v_mov_b32_e32 v135, v205
	v_mov_b32_e32 v150, v206
	v_mov_b32_e32 v151, v207
	v_mov_b32_e32 v148, v208
	v_mov_b32_e32 v149, v209
	v_mov_b32_e32 v146, v210
	v_mov_b32_e32 v147, v211
	v_mov_b32_e32 v144, v212
	v_mov_b32_e32 v145, v213
	v_mov_b32_e32 v142, v186
	v_mov_b32_e32 v143, v187
	v_mov_b32_e32 v152, v66
	v_mov_b32_e32 v153, v67
	v_mov_b32_e32 v154, v68
	v_mov_b32_e32 v155, v69
	s_waitcnt vmcnt(0)
	v_lshlrev_b32_e32 v96, 16, v156
	v_and_b32_e32 v97, 0xffff0000, v156
	v_lshlrev_b32_e32 v92, 16, v160
	v_and_b32_e32 v93, 0xffff0000, v160
	v_lshlrev_b32_e32 v98, 16, v157
	v_and_b32_e32 v99, 0xffff0000, v157
	v_lshlrev_b32_e32 v94, 16, v161
	v_and_b32_e32 v95, 0xffff0000, v161
	v_lshlrev_b32_e32 v100, 16, v158
	v_and_b32_e32 v101, 0xffff0000, v158
	v_lshlrev_b32_e32 v104, 16, v162
	v_and_b32_e32 v105, 0xffff0000, v162
	v_lshlrev_b32_e32 v102, 16, v159
	v_and_b32_e32 v103, 0xffff0000, v159
	v_lshlrev_b32_e32 v106, 16, v163
	v_and_b32_e32 v107, 0xffff0000, v163
	v_lshlrev_b64 v[0:1], 10, v[64:65]
	global_load_dwordx4 v[4:7], v[88:89], off
	global_load_dwordx4 v[8:11], v[90:91], off
	v_pk_fma_f32 v[16:17], v[96:97], s[26:27], v[134:135] op_sel_hi:[1,0,1]
	v_pk_fma_f32 v[18:19], v[98:99], s[26:27], v[150:151] op_sel_hi:[1,0,1]
	v_add_f32_e32 v2, 0, v16
	v_add_f32_e32 v2, v17, v2
	v_add_f32_e32 v2, v18, v2
	v_add_f32_e32 v2, v19, v2
	v_pk_fma_f32 v[20:21], v[100:101], s[26:27], v[148:149] op_sel_hi:[1,0,1]
	v_pk_fma_f32 v[22:23], v[102:103], s[26:27], v[146:147] op_sel_hi:[1,0,1]
	v_add_f32_e32 v2, v20, v2
	v_add_f32_e32 v2, v21, v2
	v_add_f32_e32 v2, v22, v2
	v_add_f32_e32 v2, v23, v2
	v_pk_fma_f32 v[24:25], v[92:93], s[26:27], v[144:145] op_sel_hi:[1,0,1]
	v_pk_fma_f32 v[26:27], v[94:95], s[26:27], v[142:143] op_sel_hi:[1,0,1]
	v_add_f32_e32 v2, v24, v2
	v_add_f32_e32 v2, v25, v2
	v_add_f32_e32 v2, v26, v2
	v_pk_fma_f32 v[12:13], v[104:105], s[26:27], v[152:153] op_sel_hi:[1,0,1]
	v_add_f32_e32 v2, v27, v2
	v_add_f32_e32 v2, v12, v2
	v_pk_fma_f32 v[14:15], v[106:107], s[26:27], v[154:155] op_sel_hi:[1,0,1]
	v_add_f32_e32 v2, v13, v2
	v_add_f32_e32 v2, v14, v2
	v_add_f32_e32 v2, v15, v2
	v_mov_b32_e32 v28, 0
	v_lshl_add_u64 v[0:1], v[0:1], 2, v[86:87]
	v_add_f32_dpp v2, v2, v2 quad_perm:[1,0,3,2] row_mask:0xf bank_mask:0xf bound_ctrl:1
	s_nop 0
	s_nop 0
	v_add_f32_dpp v2, v2, v2 quad_perm:[2,3,0,1] row_mask:0xf bank_mask:0xf bound_ctrl:1
	s_nop 0
	s_nop 0
	v_add_f32_dpp v2, v2, v2 row_half_mirror row_mask:0xf bank_mask:0xf bound_ctrl:1
	s_nop 1
	v_add_f32_dpp v2, v2, v2 row_mirror row_mask:0xf bank_mask:0xf bound_ctrl:1
	s_nop 1
	v_mov_b32_dpp v28, v2 row_bcast:15 row_mask:0xa bank_mask:0xf
	v_add_f32_e32 v2, v2, v28
	v_mov_b32_e32 v28, 0
	s_nop 1
	v_mov_b32_dpp v28, v2 row_bcast:31 row_mask:0xc bank_mask:0xf
	v_add_f32_e32 v2, v2, v28
	s_nop 0
	v_readlane_b32 s34, v2, 63
	s_nop 1
	v_mul_f32_e32 v2, s34, v180
	v_pk_add_f32 v[16:17], v[16:17], v[2:3] op_sel_hi:[1,0] neg_lo:[0,1] neg_hi:[0,1]
	v_pk_add_f32 v[18:19], v[18:19], v[2:3] op_sel_hi:[1,0] neg_lo:[0,1] neg_hi:[0,1]
	v_pk_mul_f32 v[28:29], v[16:17], v[16:17]
	v_pk_mul_f32 v[30:31], v[18:19], v[18:19]
	v_pk_add_f32 v[20:21], v[20:21], v[2:3] op_sel_hi:[1,0] neg_lo:[0,1] neg_hi:[0,1]
	v_pk_add_f32 v[22:23], v[22:23], v[2:3] op_sel_hi:[1,0] neg_lo:[0,1] neg_hi:[0,1]
	v_pk_add_f32 v[24:25], v[24:25], v[2:3] op_sel_hi:[1,0] neg_lo:[0,1] neg_hi:[0,1]
	v_pk_add_f32 v[26:27], v[26:27], v[2:3] op_sel_hi:[1,0] neg_lo:[0,1] neg_hi:[0,1]
	v_pk_add_f32 v[12:13], v[12:13], v[2:3] op_sel_hi:[1,0] neg_lo:[0,1] neg_hi:[0,1]
	v_pk_add_f32 v[14:15], v[14:15], v[2:3] op_sel_hi:[1,0] neg_lo:[0,1] neg_hi:[0,1]
	v_add_f32_e32 v2, v28, v29
	v_add_f32_e32 v2, v30, v2
	v_pk_mul_f32 v[32:33], v[20:21], v[20:21]
	v_add_f32_e32 v2, v31, v2
	v_add_f32_e32 v2, v32, v2
	v_pk_mul_f32 v[34:35], v[22:23], v[22:23]
	v_add_f32_e32 v2, v33, v2
	v_add_f32_e32 v2, v34, v2
	v_pk_mul_f32 v[36:37], v[24:25], v[24:25]
	v_add_f32_e32 v2, v35, v2
	v_add_f32_e32 v2, v36, v2
	v_pk_mul_f32 v[38:39], v[26:27], v[26:27]
	v_add_f32_e32 v2, v37, v2
	v_add_f32_e32 v2, v38, v2
	v_pk_mul_f32 v[40:41], v[12:13], v[12:13]
	v_add_f32_e32 v2, v39, v2
	v_add_f32_e32 v2, v40, v2
	v_pk_mul_f32 v[42:43], v[14:15], v[14:15]
	v_add_f32_e32 v2, v41, v2
	v_add_f32_e32 v2, v42, v2
	v_add_f32_e32 v2, v43, v2
	v_mov_b32_e32 v28, 0
	s_nop 0
	v_add_f32_dpp v2, v2, v2 quad_perm:[1,0,3,2] row_mask:0xf bank_mask:0xf bound_ctrl:1
	s_nop 1
	v_add_f32_dpp v2, v2, v2 quad_perm:[2,3,0,1] row_mask:0xf bank_mask:0xf bound_ctrl:1
	s_nop 1
	v_add_f32_dpp v2, v2, v2 row_half_mirror row_mask:0xf bank_mask:0xf bound_ctrl:1
	s_nop 1
	v_add_f32_dpp v2, v2, v2 row_mirror row_mask:0xf bank_mask:0xf bound_ctrl:1
	s_nop 1
	v_mov_b32_dpp v28, v2 row_bcast:15 row_mask:0xa bank_mask:0xf
	v_add_f32_e32 v2, v2, v28
	v_mov_b32_e32 v28, 0
	s_nop 1
	v_mov_b32_dpp v28, v2 row_bcast:31 row_mask:0xc bank_mask:0xf
	v_add_f32_e32 v2, v2, v28
	s_nop 0
	v_readlane_b32 s34, v2, 63
	s_nop 1
	v_fma_f32 v2, s34, v180, v177
	v_mul_f32_e32 v28, 0x4b800000, v2
	v_cmp_gt_f32_e32 vcc, s49, v2
	s_nop 1
	v_cndmask_b32_e32 v2, v2, v28, vcc
	v_rsq_f32_e32 v2, v2
	s_nop 0
	v_mul_f32_e32 v28, 0x45800000, v2
	v_cndmask_b32_e32 v2, v2, v28, vcc
	v_pk_mul_f32 v[16:17], v[16:17], v[2:3] op_sel_hi:[1,0]
	v_pk_mul_f32 v[18:19], v[18:19], v[2:3] op_sel_hi:[1,0]
	s_waitcnt vmcnt(0)
	v_pk_fma_f32 v[4:5], v[4:5], v[16:17], v[8:9]
	v_pk_fma_f32 v[6:7], v[6:7], v[18:19], v[10:11]
	global_store_dwordx4 v[0:1], v[4:7], off
	global_load_dwordx4 v[4:7], v[88:89], off offset:16
	s_nop 0
	global_load_dwordx4 v[8:11], v[90:91], off offset:16
	v_pk_mul_f32 v[16:17], v[22:23], v[2:3] op_sel_hi:[1,0]
	v_pk_mul_f32 v[18:19], v[20:21], v[2:3] op_sel_hi:[1,0]
	v_pk_mul_f32 v[14:15], v[14:15], v[2:3] op_sel_hi:[1,0]
	v_pk_mul_f32 v[12:13], v[12:13], v[2:3] op_sel_hi:[1,0]
	s_waitcnt vmcnt(0)
	v_pk_fma_f32 v[4:5], v[4:5], v[18:19], v[8:9]
	v_pk_fma_f32 v[6:7], v[6:7], v[16:17], v[10:11]
	global_store_dwordx4 v[0:1], v[4:7], off offset:16
	global_load_dwordx4 v[4:7], v[88:89], off offset:32
	s_nop 0
	global_load_dwordx4 v[8:11], v[90:91], off offset:32
	v_pk_mul_f32 v[16:17], v[26:27], v[2:3] op_sel_hi:[1,0]
	v_pk_mul_f32 v[18:19], v[24:25], v[2:3] op_sel_hi:[1,0]
	s_waitcnt vmcnt(0)
	v_pk_fma_f32 v[6:7], v[6:7], v[16:17], v[10:11]
	v_pk_fma_f32 v[4:5], v[4:5], v[18:19], v[8:9]
	global_store_dwordx4 v[0:1], v[4:7], off offset:32
	global_load_dwordx4 v[4:7], v[88:89], off offset:48
	s_nop 0
	global_load_dwordx4 v[8:11], v[90:91], off offset:48
	s_waitcnt vmcnt(0)
	v_pk_fma_f32 v[4:5], v[12:13], v[4:5], v[8:9]
	v_pk_fma_f32 v[6:7], v[14:15], v[6:7], v[10:11]
	global_store_dwordx4 v[0:1], v[4:7], off offset:48
	s_add_i32 s12, s12, 1
	s_cmp_lt_u32 s12, 2
	s_cbranch_scc1 .Lex_half
	v_mov_b32_e32 v3, 0
	s_branch .LBB0_685

	.amdhsa_kernel _Z10hybrid_fwd6Params
		.amdhsa_group_segment_fixed_size 73744
		.amdhsa_private_segment_fixed_size 0
		.amdhsa_kernarg_size 464
		.amdhsa_user_sgpr_count 2
		.amdhsa_user_sgpr_dispatch_ptr 0
		.amdhsa_user_sgpr_queue_ptr 0
		.amdhsa_user_sgpr_kernarg_segment_ptr 1
		.amdhsa_user_sgpr_dispatch_id 0
		.amdhsa_user_sgpr_kernarg_preload_length 0
		.amdhsa_user_sgpr_kernarg_preload_offset 0
		.amdhsa_user_sgpr_private_segment_size 0
		.amdhsa_uses_dynamic_stack 0
		.amdhsa_enable_private_segment 0
		.amdhsa_system_sgpr_workgroup_id_x 1
		.amdhsa_system_sgpr_workgroup_id_y 0
		.amdhsa_system_sgpr_workgroup_id_z 0
		.amdhsa_system_sgpr_workgroup_info 0
		.amdhsa_system_vgpr_workitem_id 2
		.amdhsa_next_free_vgpr 256
		.amdhsa_next_free_sgpr 102
		.amdhsa_accum_offset 256
		.amdhsa_reserve_vcc 1
		.amdhsa_float_round_mode_32 0
		.amdhsa_float_round_mode_16_64 0
		.amdhsa_float_denorm_mode_32 3
		.amdhsa_float_denorm_mode_16_64 3
		.amdhsa_dx10_clamp 1
		.amdhsa_ieee_mode 1
		.amdhsa_fp16_overflow 0
		.amdhsa_tg_split 0
		.amdhsa_exception_fp_ieee_invalid_op 0
		.amdhsa_exception_fp_denorm_src 0
		.amdhsa_exception_fp_ieee_div_zero 0
		.amdhsa_exception_fp_ieee_overflow 0
		.amdhsa_exception_fp_ieee_underflow 0
		.amdhsa_exception_fp_ieee_inexact 0
		.amdhsa_exception_int_div_zero 0
	.end_amdhsa_kernel

amdhsa.kernels:
  - .agpr_count:     0
    .args:
      - .offset:         0
        .size:           208
        .value_kind:     by_value
      - .offset:         208
        .size:           4
        .value_kind:     hidden_block_count_x
      - .offset:         212
        .size:           4
        .value_kind:     hidden_block_count_y
      - .offset:         216
        .size:           4
        .value_kind:     hidden_block_count_z
      - .offset:         220
        .size:           2
        .value_kind:     hidden_group_size_x
      - .offset:         222
        .size:           2
        .value_kind:     hidden_group_size_y
      - .offset:         224
        .size:           2
        .value_kind:     hidden_group_size_z
      - .offset:         226
        .size:           2
        .value_kind:     hidden_remainder_x
      - .offset:         228
        .size:           2
        .value_kind:     hidden_remainder_y
      - .offset:         230
        .size:           2
        .value_kind:     hidden_remainder_z
      - .offset:         248
        .size:           8
        .value_kind:     hidden_global_offset_x
      - .offset:         256
        .size:           8
        .value_kind:     hidden_global_offset_y
      - .offset:         264
        .size:           8
        .value_kind:     hidden_global_offset_z
      - .offset:         272
        .size:           2
        .value_kind:     hidden_grid_dims
      - .offset:         296
        .size:           8
        .value_kind:     hidden_multigrid_sync_arg
    .group_segment_fixed_size: 73744
    .kernarg_segment_align: 8
    .kernarg_segment_size: 464
    .language:       OpenCL C
    .language_version:
      - 2
      - 0
    .max_flat_workgroup_size: 256
    .name:           _Z10hybrid_fwd6Params
    .private_segment_fixed_size: 0
    .sgpr_count:     108
    .sgpr_spill_count: 186
    .symbol:         _Z10hybrid_fwd6Params.kd
    .uniform_work_group_size: 1
    .uses_dynamic_stack: false
    .vgpr_count:     256
    .vgpr_spill_count: 0
    .wavefront_size: 64
